# GEMM K-loops (all but in-proj): LDS-DMA loads use SGPR base + 32-bit VGPR offset, the 16 v_lshl_add_u64 per trip removed
# baseline (speedup 1.0000x reference)
; #define PG8_STAGE(bufoff, gbase, voff) do { _Pragma("unroll") for (int _i = 0; _i < 2; ++_i) \
;         __builtin_amdgcn_global_load_lds((const unsigned*)((const char*)(gbase) + (voff)[_i]), (PG8_LAS unsigned*)(lds + (bufoff) + ldsw + _i * 8192), 16, 0, 0); } while (0)
; #define PG8_LDA(dst, b, h) do { _Pragma("unroll") for (int m = 0; m < 4; ++m) _Pragma("unroll") for (int k = 0; k < 2; ++k) dst[m][k] = *(const PG8_LAS bf16x8*)(lds + PG8_SA(b, h) + aoff + m * 2048 + k * 1024); } while (0)
; #define PG8_LDB(dst, b, h) do { _Pragma("unroll") for (int n = 0; n < 2; ++n) _Pragma("unroll") for (int k = 0; k < 2; ++k) dst[n][k] = *(const PG8_LAS bf16x8*)(lds + PG8_SB(b, h) + boff + n * 2048 + k * 1024); } while (0)
; #define PG8_MMA(ai, bj, At, Bt) do { __builtin_amdgcn_s_setprio(1); _Pragma("unroll") for (int m = 0; m < 4; ++m) _Pragma("unroll") for (int n = 0; n < 2; ++n) _Pragma("unroll") for (int k = 0; k < 2; ++k) \
;         acc[ai][bj][m][n] = __builtin_amdgcn_mfma_f32_16x16x32_bf16(Bt[n][k], At[m][k], acc[ai][bj][m][n], 0, 0, 0); __builtin_amdgcn_s_setprio(0); } while (0)
; #define PG8_WAIT_V(n) asm volatile("s_waitcnt vmcnt(" #n ")" ::: "memory")
; #define PG8_BAR __builtin_amdgcn_s_barrier()
; template <class Epi, class Sched, bool ALIGN_EPI = false, bool SP2 = false>
; __device__ __forceinline__ void gemm_phase(PG8_LAS unsigned char* lds, const Gemm g, const Sched& S, const Epi& E) {
;     ...
;         for (int t = 0; t < nt; t += 2) {
;             const bool last = (t == nt - 2);
;             const char* a1 = cA + (size_t)(t + 1) * kstep;
;             const char* a2 = last ? nA : cA + (size_t)(t + 2) * kstep; const char* b2 = last ? nB : cB + (size_t)(t + 2) * kstep;
;             const char* a3 = a2 + kstep; const char* b3 = b2 + kstep;
;             if (last && has_next) S.a_ready(nxt);
;             if constexpr (SP2) {
;             PG8_LDB(B0, 0, 0); PG8_LDB(B1, 0, 1); PG8_SCHED; PG8_LDA(At, 0, 0); PG8_STAGE(PG8_SA(1, 1), a1 + hstep, voffA);
;             PG8_WAIT_V(8); PG8_WAIT_L(0); PG8_BAR; PG8_MMA(0, 0, At, B0); PG8_MMA(0, 1, At, B1); PG8_BAR; PG8_SCHED;
;     ...
;         for (int a = 0; a < 2; ++a)
; #pragma unroll
;             for (int b = 0; b < 2; ++b)
; #pragma unroll
;                 for (int m = 0; m < 4; ++m)
; #pragma unroll
;                     for (int n = 0; n < 2; ++n) acc[a][b][m][n] = (f32x4){0.f, 0.f, 0.f, 0.f};
.LBB0_458:
	v_mov_b32_e32 v123, 0
	s_andn2_b64 vcc, exec, s[42:43]
	v_mov_b32_e32 v122, v123
	v_mov_b32_e32 v121, v123
	v_mov_b32_e32 v120, v123
	v_mov_b32_e32 v127, v123
	v_mov_b32_e32 v126, v123
	v_mov_b32_e32 v125, v123
	v_mov_b32_e32 v124, v123
	v_mov_b32_e32 v111, v123
	v_mov_b32_e32 v110, v123
	v_mov_b32_e32 v109, v123
	v_mov_b32_e32 v108, v123
	v_mov_b32_e32 v107, v123
	v_mov_b32_e32 v106, v123
	v_mov_b32_e32 v105, v123
	v_mov_b32_e32 v104, v123
	v_mov_b32_e32 v95, v123
	v_mov_b32_e32 v94, v123
	v_mov_b32_e32 v93, v123
	v_mov_b32_e32 v92, v123
	v_mov_b32_e32 v91, v123
	v_mov_b32_e32 v90, v123
	v_mov_b32_e32 v89, v123
	v_mov_b32_e32 v88, v123
	v_mov_b32_e32 v79, v123
	v_mov_b32_e32 v78, v123
	v_mov_b32_e32 v77, v123
	v_mov_b32_e32 v76, v123
	v_mov_b32_e32 v75, v123
	v_mov_b32_e32 v74, v123
	v_mov_b32_e32 v73, v123
	v_mov_b32_e32 v72, v123
	v_mov_b32_e32 v119, v123
	v_mov_b32_e32 v118, v123
	v_mov_b32_e32 v117, v123
	v_mov_b32_e32 v116, v123
	v_mov_b32_e32 v115, v123
	v_mov_b32_e32 v114, v123
	v_mov_b32_e32 v113, v123
	v_mov_b32_e32 v112, v123
	v_mov_b32_e32 v103, v123
	v_mov_b32_e32 v102, v123
	v_mov_b32_e32 v101, v123
	v_mov_b32_e32 v100, v123
	v_mov_b32_e32 v99, v123
	v_mov_b32_e32 v98, v123
	v_mov_b32_e32 v97, v123
	v_mov_b32_e32 v96, v123
	v_mov_b32_e32 v87, v123
	v_mov_b32_e32 v86, v123
	v_mov_b32_e32 v85, v123
	v_mov_b32_e32 v84, v123
	v_mov_b32_e32 v83, v123
	v_mov_b32_e32 v82, v123
	v_mov_b32_e32 v81, v123
	v_mov_b32_e32 v80, v123
	v_mov_b32_e32 v71, v123
	v_mov_b32_e32 v70, v123
	v_mov_b32_e32 v69, v123
	v_mov_b32_e32 v68, v123
	v_mov_b32_e32 v67, v123
	v_mov_b32_e32 v66, v123
	v_mov_b32_e32 v65, v123
	v_mov_b32_e32 v64, v123
	v_mov_b32_e32 v63, v123
	v_mov_b32_e32 v62, v123
	v_mov_b32_e32 v61, v123
	v_mov_b32_e32 v60, v123
	v_mov_b32_e32 v59, v123
	v_mov_b32_e32 v58, v123
	v_mov_b32_e32 v57, v123
	v_mov_b32_e32 v56, v123
	v_mov_b32_e32 v47, v123
	v_mov_b32_e32 v46, v123
	v_mov_b32_e32 v45, v123
	v_mov_b32_e32 v44, v123
	v_mov_b32_e32 v43, v123
	v_mov_b32_e32 v42, v123
	v_mov_b32_e32 v41, v123
	v_mov_b32_e32 v40, v123
	v_mov_b32_e32 v31, v123
	v_mov_b32_e32 v30, v123
	v_mov_b32_e32 v29, v123
	v_mov_b32_e32 v28, v123
	v_mov_b32_e32 v27, v123
	v_mov_b32_e32 v26, v123
	v_mov_b32_e32 v25, v123
	v_mov_b32_e32 v24, v123
	v_mov_b32_e32 v15, v123
	v_mov_b32_e32 v14, v123
	v_mov_b32_e32 v13, v123
	v_mov_b32_e32 v12, v123
	v_mov_b32_e32 v11, v123
	v_mov_b32_e32 v10, v123
	v_mov_b32_e32 v9, v123
	v_mov_b32_e32 v8, v123
	v_mov_b32_e32 v55, v123
	v_mov_b32_e32 v54, v123
	v_mov_b32_e32 v53, v123
	v_mov_b32_e32 v52, v123
	v_mov_b32_e32 v51, v123
	v_mov_b32_e32 v50, v123
	v_mov_b32_e32 v49, v123
	v_mov_b32_e32 v48, v123
	v_mov_b32_e32 v39, v123
	v_mov_b32_e32 v38, v123
	v_mov_b32_e32 v37, v123
	v_mov_b32_e32 v36, v123
	v_mov_b32_e32 v35, v123
	v_mov_b32_e32 v34, v123
	v_mov_b32_e32 v33, v123
	v_mov_b32_e32 v32, v123
	v_mov_b32_e32 v23, v123
	v_mov_b32_e32 v22, v123
	v_mov_b32_e32 v21, v123
	v_mov_b32_e32 v20, v123
	v_mov_b32_e32 v19, v123
	v_mov_b32_e32 v18, v123
	v_mov_b32_e32 v17, v123
	v_mov_b32_e32 v16, v123
	v_mov_b32_e32 v7, v123
	v_mov_b32_e32 v6, v123
	v_mov_b32_e32 v5, v123
	v_mov_b32_e32 v4, v123
	v_mov_b32_e32 v3, v123
	v_mov_b32_e32 v2, v123
	v_mov_b32_e32 v1, v123
	v_mov_b32_e32 v0, v123
	s_cbranch_vccnz .LBB0_461
	s_add_u32 s0, s62, 0x80
	s_addc_u32 s1, s63, 0
	s_add_u32 s62, s60, 0x100
	s_addc_u32 s63, s61, 0
	s_mov_b32 s60, 0
	v_add_u32_e32 v150, s8, v132
	v_add_u32_e32 v151, s8, v128
	v_add_u32_e32 v198, s8, v134
	v_add_u32_e32 v199, s8, v130
	v_add_u32_e32 v222, 0x80, v132
	v_add_u32_e32 v223, 0x80, v128
	v_add_u32_e32 v224, 0x80, v150
	v_add_u32_e32 v225, 0x80, v151
	v_add_u32_e32 v226, 0x80, v134
	v_add_u32_e32 v227, 0x80, v130
.LBB0_460:
	ds_read_b128 v[146:149], v154
	ds_read_b128 v[158:161], v154 offset:1024
	ds_read_b128 v[162:165], v154 offset:2048
	ds_read_b128 v[166:169], v154 offset:3072
	ds_read_b128 v[170:173], v155
	ds_read_b128 v[174:177], v155 offset:1024
	ds_read_b128 v[178:181], v155 offset:2048
	ds_read_b128 v[182:185], v155 offset:3072
	s_add_i32 s97, s60, 2
	s_add_u32 s16, s0, 0x80
	s_addc_u32 s17, s1, 0
	s_cmp_eq_u32 s80, s60
	s_cselect_b32 s60, s56, s16
	s_cselect_b32 s61, s57, s17
	s_cselect_b32 vcc_hi, s59, s63
	s_cselect_b32 vcc_lo, s58, s62
	s_add_i32 m0, s72, 0xc000
	ds_read_b128 v[186:189], v156
	ds_read_b128 v[190:193], v156 offset:1024
	ds_read_b128 v[194:197], v156 offset:2048
	ds_read_b128 v[202:205], v156 offset:3072
	ds_read_b128 v[206:209], v156 offset:4096
	ds_read_b128 v[210:213], v156 offset:5120
	ds_read_b128 v[214:217], v156 offset:6144
	ds_read_b128 v[218:221], v156 offset:7168
	global_load_lds_dwordx4 v138, s[0:1]
	s_add_i32 m0, s72, 0xe000
	s_nop 0
	global_load_lds_dwordx4 v140, s[0:1]
	s_waitcnt vmcnt(8)
	s_waitcnt lgkmcnt(0)
	s_barrier
; #define PG8_STAGE(bufoff, gbase, voff) do { _Pragma("unroll") for (int _i = 0; _i < 2; ++_i) \
;         __builtin_amdgcn_global_load_lds((const unsigned*)((const char*)(gbase) + (voff)[_i]), (PG8_LAS unsigned*)(lds + (bufoff) + ldsw + _i * 8192), 16, 0, 0); } while (0)
; #define PG8_LDA(dst, b, h) do { _Pragma("unroll") for (int m = 0; m < 4; ++m) _Pragma("unroll") for (int k = 0; k < 2; ++k) dst[m][k] = *(const PG8_LAS bf16x8*)(lds + PG8_SA(b, h) + aoff + m * 2048 + k * 1024); } while (0)
; #define PG8_MMA(ai, bj, At, Bt) do { __builtin_amdgcn_s_setprio(1); _Pragma("unroll") for (int m = 0; m < 4; ++m) _Pragma("unroll") for (int n = 0; n < 2; ++n) _Pragma("unroll") for (int k = 0; k < 2; ++k) \
;         acc[ai][bj][m][n] = __builtin_amdgcn_mfma_f32_16x16x32_bf16(Bt[n][k], At[m][k], acc[ai][bj][m][n], 0, 0, 0); __builtin_amdgcn_s_setprio(0); } while (0)
; #define PG8_WAIT_V(n) asm volatile("s_waitcnt vmcnt(" #n ")" ::: "memory")
; #define PG8_WAIT_L(n) asm volatile("s_waitcnt lgkmcnt(" #n ")" ::: "memory")
; #define PG8_BAR __builtin_amdgcn_s_barrier()
; #define PG8_SCHED __builtin_amdgcn_sched_barrier(0)
; template <class Epi, class Sched, bool ALIGN_EPI = false, bool SP2 = false>
; __device__ __forceinline__ void gemm_phase(PG8_LAS unsigned char* lds, const Gemm g, const Sched& S, const Epi& E) {
;     ...
;             PG8_WAIT_V(8); PG8_WAIT_L(0); PG8_BAR; PG8_MMA(0, 0, At, B0); PG8_MMA(0, 1, At, B1); PG8_BAR; PG8_SCHED;
;             PG8_LDA(At, 0, 1); PG8_STAGE(PG8_SB(0, 0), b2, voffB); PG8_STAGE(PG8_SB(0, 1), b2 + hstep, voffB); PG8_STAGE(PG8_SA(0, 0), a2, voffA);
;             PG8_WAIT_V(8); PG8_WAIT_L(0); PG8_BAR; PG8_MMA(1, 0, At, B0); PG8_MMA(1, 1, At, B1); PG8_BAR; PG8_SCHED;
	s_setprio 1
	s_waitcnt lgkmcnt(0)
	v_mfma_f32_16x16x32_bf16 v[120:123], v[146:149], v[186:189], v[120:123]
	v_mfma_f32_16x16x32_bf16 v[124:127], v[162:165], v[186:189], v[124:127]
	v_mfma_f32_16x16x32_bf16 v[108:111], v[146:149], v[194:197], v[108:111]
	v_mfma_f32_16x16x32_bf16 v[104:107], v[162:165], v[194:197], v[104:107]
	v_mfma_f32_16x16x32_bf16 v[92:95], v[146:149], v[206:209], v[92:95]
	v_mfma_f32_16x16x32_bf16 v[88:91], v[162:165], v[206:209], v[88:91]
	v_mfma_f32_16x16x32_bf16 v[76:79], v[146:149], v[214:217], v[76:79]
	v_mfma_f32_16x16x32_bf16 v[72:75], v[162:165], v[214:217], v[72:75]
	v_mfma_f32_16x16x32_bf16 v[120:123], v[158:161], v[190:193], v[120:123]
	v_mfma_f32_16x16x32_bf16 v[124:127], v[166:169], v[190:193], v[124:127]
	v_mfma_f32_16x16x32_bf16 v[108:111], v[158:161], v[202:205], v[108:111]
	v_mfma_f32_16x16x32_bf16 v[104:107], v[166:169], v[202:205], v[104:107]
	v_mfma_f32_16x16x32_bf16 v[92:95], v[158:161], v[210:213], v[92:95]
	v_mfma_f32_16x16x32_bf16 v[88:91], v[166:169], v[210:213], v[88:91]
	v_mfma_f32_16x16x32_bf16 v[76:79], v[158:161], v[218:221], v[76:79]
	v_mfma_f32_16x16x32_bf16 v[72:75], v[166:169], v[218:221], v[72:75]
	s_setprio 0
	s_setprio 1
	v_mfma_f32_16x16x32_bf16 v[116:119], v[170:173], v[186:189], v[116:119]
	v_mfma_f32_16x16x32_bf16 v[112:115], v[178:181], v[186:189], v[112:115]
	v_mfma_f32_16x16x32_bf16 v[100:103], v[170:173], v[194:197], v[100:103]
	v_mfma_f32_16x16x32_bf16 v[96:99], v[178:181], v[194:197], v[96:99]
	v_mfma_f32_16x16x32_bf16 v[84:87], v[170:173], v[206:209], v[84:87]
	v_mfma_f32_16x16x32_bf16 v[80:83], v[178:181], v[206:209], v[80:83]
	v_mfma_f32_16x16x32_bf16 v[68:71], v[170:173], v[214:217], v[68:71]
	v_mfma_f32_16x16x32_bf16 v[64:67], v[178:181], v[214:217], v[64:67]
	v_mfma_f32_16x16x32_bf16 v[116:119], v[174:177], v[190:193], v[116:119]
	v_mfma_f32_16x16x32_bf16 v[112:115], v[182:185], v[190:193], v[112:115]
	v_mfma_f32_16x16x32_bf16 v[100:103], v[174:177], v[202:205], v[100:103]
	v_mfma_f32_16x16x32_bf16 v[96:99], v[182:185], v[202:205], v[96:99]
	v_mfma_f32_16x16x32_bf16 v[84:87], v[174:177], v[210:213], v[84:87]
	v_mfma_f32_16x16x32_bf16 v[80:83], v[182:185], v[210:213], v[80:83]
	v_mfma_f32_16x16x32_bf16 v[68:71], v[174:177], v[218:221], v[68:71]
	v_mfma_f32_16x16x32_bf16 v[64:67], v[182:185], v[218:221], v[64:67]
	s_setprio 0
	s_barrier
	s_add_i32 s16, s83, s49
	s_mov_b32 m0, s16
	ds_read_b128 v[186:189], v156 offset:16384
	ds_read_b128 v[190:193], v156 offset:17408
	ds_read_b128 v[194:197], v156 offset:18432
	ds_read_b128 v[202:205], v156 offset:19456
	ds_read_b128 v[206:209], v156 offset:20480
	ds_read_b128 v[210:213], v156 offset:21504
	ds_read_b128 v[214:217], v156 offset:22528
	ds_read_b128 v[218:221], v156 offset:23552
	global_load_lds_dwordx4 v132, vcc
	s_add_i32 m0, s16, 0x2000
	s_add_i32 s16, s84, s49
	global_load_lds_dwordx4 v128, vcc
	s_mov_b32 m0, s16
	s_nop 0
	global_load_lds_dwordx4 v150, vcc
	s_add_i32 m0, s16, 0x2000
	s_nop 0
	global_load_lds_dwordx4 v151, vcc
	s_mov_b32 m0, s72
	s_nop 0
	global_load_lds_dwordx4 v134, s[60:61]
	s_mov_b32 m0, s73
	s_nop 0
	global_load_lds_dwordx4 v130, s[60:61]
	s_waitcnt vmcnt(8)
	s_waitcnt lgkmcnt(0)
	s_barrier
	s_setprio 1
	s_waitcnt lgkmcnt(0)
	v_mfma_f32_16x16x32_bf16 v[60:63], v[146:149], v[186:189], v[60:63]
	v_mfma_f32_16x16x32_bf16 v[56:59], v[162:165], v[186:189], v[56:59]
	v_mfma_f32_16x16x32_bf16 v[44:47], v[146:149], v[194:197], v[44:47]
	v_mfma_f32_16x16x32_bf16 v[40:43], v[162:165], v[194:197], v[40:43]
	v_mfma_f32_16x16x32_bf16 v[28:31], v[146:149], v[206:209], v[28:31]
	v_mfma_f32_16x16x32_bf16 v[24:27], v[162:165], v[206:209], v[24:27]
	v_mfma_f32_16x16x32_bf16 v[12:15], v[146:149], v[214:217], v[12:15]
	v_mfma_f32_16x16x32_bf16 v[8:11], v[162:165], v[214:217], v[8:11]
	v_mfma_f32_16x16x32_bf16 v[60:63], v[158:161], v[190:193], v[60:63]
	v_mfma_f32_16x16x32_bf16 v[56:59], v[166:169], v[190:193], v[56:59]
	v_mfma_f32_16x16x32_bf16 v[44:47], v[158:161], v[202:205], v[44:47]
	v_mfma_f32_16x16x32_bf16 v[40:43], v[166:169], v[202:205], v[40:43]
	v_mfma_f32_16x16x32_bf16 v[28:31], v[158:161], v[210:213], v[28:31]
	v_mfma_f32_16x16x32_bf16 v[24:27], v[166:169], v[210:213], v[24:27]
	v_mfma_f32_16x16x32_bf16 v[12:15], v[158:161], v[218:221], v[12:15]
	v_mfma_f32_16x16x32_bf16 v[8:11], v[166:169], v[218:221], v[8:11]
	s_setprio 0
	s_setprio 1
	v_mfma_f32_16x16x32_bf16 v[52:55], v[170:173], v[186:189], v[52:55]
	v_mfma_f32_16x16x32_bf16 v[48:51], v[178:181], v[186:189], v[48:51]
	v_mfma_f32_16x16x32_bf16 v[36:39], v[170:173], v[194:197], v[36:39]
	v_mfma_f32_16x16x32_bf16 v[32:35], v[178:181], v[194:197], v[32:35]
	v_mfma_f32_16x16x32_bf16 v[20:23], v[170:173], v[206:209], v[20:23]
	v_mfma_f32_16x16x32_bf16 v[16:19], v[178:181], v[206:209], v[16:19]
	v_mfma_f32_16x16x32_bf16 v[4:7], v[170:173], v[214:217], v[4:7]
	v_mfma_f32_16x16x32_bf16 v[0:3], v[178:181], v[214:217], v[0:3]
	v_mfma_f32_16x16x32_bf16 v[52:55], v[174:177], v[190:193], v[52:55]
	v_mfma_f32_16x16x32_bf16 v[48:51], v[182:185], v[190:193], v[48:51]
	v_mfma_f32_16x16x32_bf16 v[36:39], v[174:177], v[202:205], v[36:39]
	v_mfma_f32_16x16x32_bf16 v[32:35], v[182:185], v[202:205], v[32:35]
	v_mfma_f32_16x16x32_bf16 v[20:23], v[174:177], v[210:213], v[20:23]
	v_mfma_f32_16x16x32_bf16 v[16:19], v[182:185], v[210:213], v[16:19]
	v_mfma_f32_16x16x32_bf16 v[4:7], v[174:177], v[218:221], v[4:7]
	v_mfma_f32_16x16x32_bf16 v[0:3], v[182:185], v[218:221], v[0:3]
	s_setprio 0
	s_barrier
; #define PG8_STAGE(bufoff, gbase, voff) do { _Pragma("unroll") for (int _i = 0; _i < 2; ++_i) \
;         __builtin_amdgcn_global_load_lds((const unsigned*)((const char*)(gbase) + (voff)[_i]), (PG8_LAS unsigned*)(lds + (bufoff) + ldsw + _i * 8192), 16, 0, 0); } while (0)
; #define PG8_LDA(dst, b, h) do { _Pragma("unroll") for (int m = 0; m < 4; ++m) _Pragma("unroll") for (int k = 0; k < 2; ++k) dst[m][k] = *(const PG8_LAS bf16x8*)(lds + PG8_SA(b, h) + aoff + m * 2048 + k * 1024); } while (0)
; #define PG8_LDB(dst, b, h) do { _Pragma("unroll") for (int n = 0; n < 2; ++n) _Pragma("unroll") for (int k = 0; k < 2; ++k) dst[n][k] = *(const PG8_LAS bf16x8*)(lds + PG8_SB(b, h) + boff + n * 2048 + k * 1024); } while (0)
; #define PG8_MMA(ai, bj, At, Bt) do { __builtin_amdgcn_s_setprio(1); _Pragma("unroll") for (int m = 0; m < 4; ++m) _Pragma("unroll") for (int n = 0; n < 2; ++n) _Pragma("unroll") for (int k = 0; k < 2; ++k) \
;         acc[ai][bj][m][n] = __builtin_amdgcn_mfma_f32_16x16x32_bf16(Bt[n][k], At[m][k], acc[ai][bj][m][n], 0, 0, 0); __builtin_amdgcn_s_setprio(0); } while (0)
; #define PG8_WAIT_V(n) asm volatile("s_waitcnt vmcnt(" #n ")" ::: "memory")
; #define PG8_WAIT_L(n) asm volatile("s_waitcnt lgkmcnt(" #n ")" ::: "memory")
; #define PG8_BAR __builtin_amdgcn_s_barrier()
; #define PG8_SCHED __builtin_amdgcn_sched_barrier(0)
; template <class Epi, class Sched, bool ALIGN_EPI = false, bool SP2 = false>
; __device__ __forceinline__ void gemm_phase(PG8_LAS unsigned char* lds, const Gemm g, const Sched& S, const Epi& E) {
;     ...
;             PG8_WAIT_V(8); PG8_WAIT_L(0); PG8_BAR; PG8_MMA(1, 0, At, B0); PG8_MMA(1, 1, At, B1); PG8_BAR; PG8_SCHED;
;             PG8_LDB(B0, 1, 0); PG8_LDB(B1, 1, 1); PG8_SCHED; PG8_LDA(At, 1, 0); PG8_STAGE(PG8_SA(0, 1), a2 + hstep, voffA);
;             PG8_WAIT_V(8); PG8_WAIT_L(0); PG8_BAR; PG8_MMA(0, 0, At, B0); PG8_MMA(0, 1, At, B1); PG8_BAR; PG8_SCHED;
;             PG8_LDA(At, 1, 1); PG8_STAGE(PG8_SB(1, 0), b3, voffB); PG8_STAGE(PG8_SB(1, 1), b3 + hstep, voffB); PG8_STAGE(PG8_SA(1, 0), a3, voffA);
;             PG8_WAIT_V(8); PG8_WAIT_L(0); PG8_BAR; PG8_MMA(1, 0, At, B0); PG8_MMA(1, 1, At, B1); PG8_BAR; PG8_SCHED;
	s_add_i32 s16, 0, 0x18000
	s_add_i32 s17, 0, 0x1c000
	v_add_u32_e32 v166, s16, v153
	v_add_u32_e32 v182, s17, v153
	ds_read_b128 v[146:149], v166
	ds_read_b128 v[158:161], v166 offset:1024
	ds_read_b128 v[162:165], v166 offset:2048
	ds_read_b128 v[166:169], v166 offset:3072
	ds_read_b128 v[170:173], v182
	ds_read_b128 v[174:177], v182 offset:1024
	ds_read_b128 v[178:181], v182 offset:2048
	ds_read_b128 v[182:185], v182 offset:3072
	s_mov_b32 m0, s74
	ds_read_b128 v[186:189], v156 offset:32768
	ds_read_b128 v[190:193], v156 offset:33792
	ds_read_b128 v[194:197], v156 offset:34816
	ds_read_b128 v[202:205], v156 offset:35840
	ds_read_b128 v[206:209], v156 offset:36864
	ds_read_b128 v[210:213], v156 offset:37888
	ds_read_b128 v[214:217], v156 offset:38912
	ds_read_b128 v[218:221], v156 offset:39936
	global_load_lds_dwordx4 v198, s[60:61]
	s_mov_b32 m0, s75
	s_nop 0
	global_load_lds_dwordx4 v199, s[60:61]
	s_waitcnt vmcnt(8)
	s_waitcnt lgkmcnt(0)
	s_barrier
	s_setprio 1
	s_waitcnt lgkmcnt(0)
	v_mfma_f32_16x16x32_bf16 v[120:123], v[146:149], v[186:189], v[120:123]
	v_mfma_f32_16x16x32_bf16 v[124:127], v[162:165], v[186:189], v[124:127]
	v_mfma_f32_16x16x32_bf16 v[108:111], v[146:149], v[194:197], v[108:111]
	v_mfma_f32_16x16x32_bf16 v[104:107], v[162:165], v[194:197], v[104:107]
	v_mfma_f32_16x16x32_bf16 v[92:95], v[146:149], v[206:209], v[92:95]
	v_mfma_f32_16x16x32_bf16 v[88:91], v[162:165], v[206:209], v[88:91]
	v_mfma_f32_16x16x32_bf16 v[76:79], v[146:149], v[214:217], v[76:79]
	v_mfma_f32_16x16x32_bf16 v[72:75], v[162:165], v[214:217], v[72:75]
	v_mfma_f32_16x16x32_bf16 v[120:123], v[158:161], v[190:193], v[120:123]
	v_mfma_f32_16x16x32_bf16 v[124:127], v[166:169], v[190:193], v[124:127]
	v_mfma_f32_16x16x32_bf16 v[108:111], v[158:161], v[202:205], v[108:111]
	v_mfma_f32_16x16x32_bf16 v[104:107], v[166:169], v[202:205], v[104:107]
	v_mfma_f32_16x16x32_bf16 v[92:95], v[158:161], v[210:213], v[92:95]
	v_mfma_f32_16x16x32_bf16 v[88:91], v[166:169], v[210:213], v[88:91]
	v_mfma_f32_16x16x32_bf16 v[76:79], v[158:161], v[218:221], v[76:79]
	v_mfma_f32_16x16x32_bf16 v[72:75], v[166:169], v[218:221], v[72:75]
	s_setprio 0
	s_setprio 1
	v_mfma_f32_16x16x32_bf16 v[116:119], v[170:173], v[186:189], v[116:119]
	v_mfma_f32_16x16x32_bf16 v[112:115], v[178:181], v[186:189], v[112:115]
	v_mfma_f32_16x16x32_bf16 v[100:103], v[170:173], v[194:197], v[100:103]
	v_mfma_f32_16x16x32_bf16 v[96:99], v[178:181], v[194:197], v[96:99]
	v_mfma_f32_16x16x32_bf16 v[84:87], v[170:173], v[206:209], v[84:87]
	v_mfma_f32_16x16x32_bf16 v[80:83], v[178:181], v[206:209], v[80:83]
	v_mfma_f32_16x16x32_bf16 v[68:71], v[170:173], v[214:217], v[68:71]
	v_mfma_f32_16x16x32_bf16 v[64:67], v[178:181], v[214:217], v[64:67]
	v_mfma_f32_16x16x32_bf16 v[116:119], v[174:177], v[190:193], v[116:119]
	v_mfma_f32_16x16x32_bf16 v[112:115], v[182:185], v[190:193], v[112:115]
	v_mfma_f32_16x16x32_bf16 v[100:103], v[174:177], v[202:205], v[100:103]
	v_mfma_f32_16x16x32_bf16 v[96:99], v[182:185], v[202:205], v[96:99]
	v_mfma_f32_16x16x32_bf16 v[84:87], v[174:177], v[210:213], v[84:87]
	v_mfma_f32_16x16x32_bf16 v[80:83], v[182:185], v[210:213], v[80:83]
	v_mfma_f32_16x16x32_bf16 v[68:71], v[174:177], v[218:221], v[68:71]
	v_mfma_f32_16x16x32_bf16 v[64:67], v[182:185], v[218:221], v[64:67]
	s_setprio 0
	s_barrier
	s_add_i32 s16, s16, s49
	s_mov_b32 m0, s16
	ds_read_b128 v[186:189], v156 offset:49152
	ds_read_b128 v[190:193], v156 offset:50176
	ds_read_b128 v[194:197], v156 offset:51200
	ds_read_b128 v[202:205], v156 offset:52224
	ds_read_b128 v[206:209], v156 offset:53248
	ds_read_b128 v[210:213], v156 offset:54272
	ds_read_b128 v[214:217], v156 offset:55296
	ds_read_b128 v[218:221], v156 offset:56320
	global_load_lds_dwordx4 v222, vcc
	s_add_i32 m0, s16, 0x2000
	s_add_i32 s16, s17, s49
	global_load_lds_dwordx4 v223, vcc
	s_mov_b32 m0, s16
	s_nop 0
	global_load_lds_dwordx4 v224, vcc
	s_add_i32 m0, s16, 0x2000
	s_nop 0
	global_load_lds_dwordx4 v225, vcc
	s_mov_b32 m0, s77
	s_nop 0
	global_load_lds_dwordx4 v226, s[60:61]
	s_mov_b32 m0, s78
	s_nop 0
	global_load_lds_dwordx4 v227, s[60:61]
	s_waitcnt vmcnt(8)
	s_waitcnt lgkmcnt(0)
	s_barrier
	s_setprio 1
	s_waitcnt lgkmcnt(0)
	v_mfma_f32_16x16x32_bf16 v[60:63], v[146:149], v[186:189], v[60:63]
	v_mfma_f32_16x16x32_bf16 v[56:59], v[162:165], v[186:189], v[56:59]
	v_mfma_f32_16x16x32_bf16 v[44:47], v[146:149], v[194:197], v[44:47]
	v_mfma_f32_16x16x32_bf16 v[40:43], v[162:165], v[194:197], v[40:43]
	v_mfma_f32_16x16x32_bf16 v[28:31], v[146:149], v[206:209], v[28:31]
	v_mfma_f32_16x16x32_bf16 v[24:27], v[162:165], v[206:209], v[24:27]
	v_mfma_f32_16x16x32_bf16 v[12:15], v[146:149], v[214:217], v[12:15]
	v_mfma_f32_16x16x32_bf16 v[8:11], v[162:165], v[214:217], v[8:11]
	v_mfma_f32_16x16x32_bf16 v[60:63], v[158:161], v[190:193], v[60:63]
	v_mfma_f32_16x16x32_bf16 v[56:59], v[166:169], v[190:193], v[56:59]
	v_mfma_f32_16x16x32_bf16 v[44:47], v[158:161], v[202:205], v[44:47]
	v_mfma_f32_16x16x32_bf16 v[40:43], v[166:169], v[202:205], v[40:43]
	v_mfma_f32_16x16x32_bf16 v[28:31], v[158:161], v[210:213], v[28:31]
	v_mfma_f32_16x16x32_bf16 v[24:27], v[166:169], v[210:213], v[24:27]
	v_mfma_f32_16x16x32_bf16 v[12:15], v[158:161], v[218:221], v[12:15]
	v_mfma_f32_16x16x32_bf16 v[8:11], v[166:169], v[218:221], v[8:11]
	s_setprio 0
	s_setprio 1
	v_mfma_f32_16x16x32_bf16 v[52:55], v[170:173], v[186:189], v[52:55]
	v_mfma_f32_16x16x32_bf16 v[48:51], v[178:181], v[186:189], v[48:51]
	v_mfma_f32_16x16x32_bf16 v[36:39], v[170:173], v[194:197], v[36:39]
	v_mfma_f32_16x16x32_bf16 v[32:35], v[178:181], v[194:197], v[32:35]
	v_mfma_f32_16x16x32_bf16 v[20:23], v[170:173], v[206:209], v[20:23]
	v_mfma_f32_16x16x32_bf16 v[16:19], v[178:181], v[206:209], v[16:19]
	v_mfma_f32_16x16x32_bf16 v[4:7], v[170:173], v[214:217], v[4:7]
	v_mfma_f32_16x16x32_bf16 v[0:3], v[178:181], v[214:217], v[0:3]
	v_mfma_f32_16x16x32_bf16 v[52:55], v[174:177], v[190:193], v[52:55]
	v_mfma_f32_16x16x32_bf16 v[48:51], v[182:185], v[190:193], v[48:51]
	v_mfma_f32_16x16x32_bf16 v[36:39], v[174:177], v[202:205], v[36:39]
	v_mfma_f32_16x16x32_bf16 v[32:35], v[182:185], v[202:205], v[32:35]
	v_mfma_f32_16x16x32_bf16 v[20:23], v[174:177], v[210:213], v[20:23]
	v_mfma_f32_16x16x32_bf16 v[16:19], v[182:185], v[210:213], v[16:19]
	v_mfma_f32_16x16x32_bf16 v[4:7], v[174:177], v[218:221], v[4:7]
	v_mfma_f32_16x16x32_bf16 v[0:3], v[182:185], v[218:221], v[0:3]
	s_setprio 0
	s_barrier
	s_add_u32 s0, s0, 0x100
	s_addc_u32 s1, s1, 0
	s_add_u32 s62, s62, 0x100
	s_addc_u32 s63, s63, 0
	s_cmp_ge_i32 s97, s79
	s_mov_b32 s60, s97
	s_cbranch_scc0 .LBB0_460

; #define PG8_STAGE(bufoff, gbase, voff) do { _Pragma("unroll") for (int _i = 0; _i < 2; ++_i) \
;         __builtin_amdgcn_global_load_lds((const unsigned*)((const char*)(gbase) + (voff)[_i]), (PG8_LAS unsigned*)(lds + (bufoff) + ldsw + _i * 8192), 16, 0, 0); } while (0)
; #define PG8_LDA(dst, b, h) do { _Pragma("unroll") for (int m = 0; m < 4; ++m) _Pragma("unroll") for (int k = 0; k < 2; ++k) dst[m][k] = *(const PG8_LAS bf16x8*)(lds + PG8_SA(b, h) + aoff + m * 2048 + k * 1024); } while (0)
; #define PG8_LDB(dst, b, h) do { _Pragma("unroll") for (int n = 0; n < 2; ++n) _Pragma("unroll") for (int k = 0; k < 2; ++k) dst[n][k] = *(const PG8_LAS bf16x8*)(lds + PG8_SB(b, h) + boff + n * 2048 + k * 1024); } while (0)
; #define PG8_MMA(ai, bj, At, Bt) do { __builtin_amdgcn_s_setprio(1); _Pragma("unroll") for (int m = 0; m < 4; ++m) _Pragma("unroll") for (int n = 0; n < 2; ++n) _Pragma("unroll") for (int k = 0; k < 2; ++k) \
;         acc[ai][bj][m][n] = __builtin_amdgcn_mfma_f32_16x16x32_bf16(Bt[n][k], At[m][k], acc[ai][bj][m][n], 0, 0, 0); __builtin_amdgcn_s_setprio(0); } while (0)
; #define PG8_WAIT_V(n) asm volatile("s_waitcnt vmcnt(" #n ")" ::: "memory")
; #define PG8_BAR __builtin_amdgcn_s_barrier()
; template <class Epi, class Sched, bool ALIGN_EPI = false, bool SP2 = false>
; __device__ __forceinline__ void gemm_phase(PG8_LAS unsigned char* lds, const Gemm g, const Sched& S, const Epi& E) {
;     ...
;         for (int t = 0; t < nt; t += 2) {
;             const bool last = (t == nt - 2);
;             const char* a1 = cA + (size_t)(t + 1) * kstep;
;             const char* a2 = last ? nA : cA + (size_t)(t + 2) * kstep; const char* b2 = last ? nB : cB + (size_t)(t + 2) * kstep;
;             const char* a3 = a2 + kstep; const char* b3 = b2 + kstep;
;             if (last && has_next) S.a_ready(nxt);
;             if constexpr (SP2) {
;             PG8_LDB(B0, 0, 0); PG8_LDB(B1, 0, 1); PG8_SCHED; PG8_LDA(At, 0, 0); PG8_STAGE(PG8_SA(1, 1), a1 + hstep, voffA);
;             PG8_WAIT_V(8); PG8_WAIT_L(0); PG8_BAR; PG8_MMA(0, 0, At, B0); PG8_MMA(0, 1, At, B1); PG8_BAR; PG8_SCHED;
;     ...
; #pragma unroll
;         for (int a = 0; a < 2; ++a)
; #pragma unroll
;             for (int b = 0; b < 2; ++b)
; #pragma unroll
;                 for (int m = 0; m < 4; ++m)
; #pragma unroll
;                     for (int n = 0; n < 2; ++n) acc[a][b][m][n] = (f32x4){0.f, 0.f, 0.f, 0.f};
.LBB0_533:
	v_mov_b32_e32 v123, 0
	s_andn2_b64 vcc, exec, s[44:45]
	v_mov_b32_e32 v122, v123
	v_mov_b32_e32 v121, v123
	v_mov_b32_e32 v120, v123
	v_mov_b32_e32 v127, v123
	v_mov_b32_e32 v126, v123
	v_mov_b32_e32 v125, v123
	v_mov_b32_e32 v124, v123
	v_mov_b32_e32 v111, v123
	v_mov_b32_e32 v110, v123
	v_mov_b32_e32 v109, v123
	v_mov_b32_e32 v108, v123
	v_mov_b32_e32 v107, v123
	v_mov_b32_e32 v106, v123
	v_mov_b32_e32 v105, v123
	v_mov_b32_e32 v104, v123
	v_mov_b32_e32 v95, v123
	v_mov_b32_e32 v94, v123
	v_mov_b32_e32 v93, v123
	v_mov_b32_e32 v92, v123
	v_mov_b32_e32 v91, v123
	v_mov_b32_e32 v90, v123
	v_mov_b32_e32 v89, v123
	v_mov_b32_e32 v88, v123
	v_mov_b32_e32 v79, v123
	v_mov_b32_e32 v78, v123
	v_mov_b32_e32 v77, v123
	v_mov_b32_e32 v76, v123
	v_mov_b32_e32 v75, v123
	v_mov_b32_e32 v74, v123
	v_mov_b32_e32 v73, v123
	v_mov_b32_e32 v72, v123
	v_mov_b32_e32 v119, v123
	v_mov_b32_e32 v118, v123
	v_mov_b32_e32 v117, v123
	v_mov_b32_e32 v116, v123
	v_mov_b32_e32 v115, v123
	v_mov_b32_e32 v114, v123
	v_mov_b32_e32 v113, v123
	v_mov_b32_e32 v112, v123
	v_mov_b32_e32 v103, v123
	v_mov_b32_e32 v102, v123
	v_mov_b32_e32 v101, v123
	v_mov_b32_e32 v100, v123
	v_mov_b32_e32 v99, v123
	v_mov_b32_e32 v98, v123
	v_mov_b32_e32 v97, v123
	v_mov_b32_e32 v96, v123
	v_mov_b32_e32 v87, v123
	v_mov_b32_e32 v86, v123
	v_mov_b32_e32 v85, v123
	v_mov_b32_e32 v84, v123
	v_mov_b32_e32 v83, v123
	v_mov_b32_e32 v82, v123
	v_mov_b32_e32 v81, v123
	v_mov_b32_e32 v80, v123
	v_mov_b32_e32 v71, v123
	v_mov_b32_e32 v70, v123
	v_mov_b32_e32 v69, v123
	v_mov_b32_e32 v68, v123
	v_mov_b32_e32 v67, v123
	v_mov_b32_e32 v66, v123
	v_mov_b32_e32 v65, v123
	v_mov_b32_e32 v64, v123
	v_mov_b32_e32 v63, v123
	v_mov_b32_e32 v62, v123
	v_mov_b32_e32 v61, v123
	v_mov_b32_e32 v60, v123
	v_mov_b32_e32 v59, v123
	v_mov_b32_e32 v58, v123
	v_mov_b32_e32 v57, v123
	v_mov_b32_e32 v56, v123
	v_mov_b32_e32 v47, v123
	v_mov_b32_e32 v46, v123
	v_mov_b32_e32 v45, v123
	v_mov_b32_e32 v44, v123
	v_mov_b32_e32 v43, v123
	v_mov_b32_e32 v42, v123
	v_mov_b32_e32 v41, v123
	v_mov_b32_e32 v40, v123
	v_mov_b32_e32 v31, v123
	v_mov_b32_e32 v30, v123
	v_mov_b32_e32 v29, v123
	v_mov_b32_e32 v28, v123
	v_mov_b32_e32 v27, v123
	v_mov_b32_e32 v26, v123
	v_mov_b32_e32 v25, v123
	v_mov_b32_e32 v24, v123
	v_mov_b32_e32 v15, v123
	v_mov_b32_e32 v14, v123
	v_mov_b32_e32 v13, v123
	v_mov_b32_e32 v12, v123
	v_mov_b32_e32 v11, v123
	v_mov_b32_e32 v10, v123
	v_mov_b32_e32 v9, v123
	v_mov_b32_e32 v8, v123
	v_mov_b32_e32 v55, v123
	v_mov_b32_e32 v54, v123
	v_mov_b32_e32 v53, v123
	v_mov_b32_e32 v52, v123
	v_mov_b32_e32 v51, v123
	v_mov_b32_e32 v50, v123
	v_mov_b32_e32 v49, v123
	v_mov_b32_e32 v48, v123
	v_mov_b32_e32 v39, v123
	v_mov_b32_e32 v38, v123
	v_mov_b32_e32 v37, v123
	v_mov_b32_e32 v36, v123
	v_mov_b32_e32 v35, v123
	v_mov_b32_e32 v34, v123
	v_mov_b32_e32 v33, v123
	v_mov_b32_e32 v32, v123
	v_mov_b32_e32 v23, v123
	v_mov_b32_e32 v22, v123
	v_mov_b32_e32 v21, v123
	v_mov_b32_e32 v20, v123
	v_mov_b32_e32 v19, v123
	v_mov_b32_e32 v18, v123
	v_mov_b32_e32 v17, v123
	v_mov_b32_e32 v16, v123
	v_mov_b32_e32 v7, v123
	v_mov_b32_e32 v6, v123
	v_mov_b32_e32 v5, v123
	v_mov_b32_e32 v4, v123
	v_mov_b32_e32 v3, v123
	v_mov_b32_e32 v2, v123
	v_mov_b32_e32 v1, v123
	v_mov_b32_e32 v0, v123
	s_cbranch_vccnz .LBB0_536
	s_add_u32 s58, s58, 0x80
	s_addc_u32 s59, s59, 0
	s_add_u32 s95, s60, 0x100
	s_addc_u32 s96, s61, 0
	s_mov_b32 s60, 0
	v_add_u32_e32 v198, s8, v134
	v_add_u32_e32 v199, s8, v138
	v_add_u32_e32 v226, s8, v132
	v_add_u32_e32 v227, s8, v136
	v_add_u32_e32 v228, 0x80, v134
	v_add_u32_e32 v229, 0x80, v138
	v_add_u32_e32 v230, 0x80, v198
	v_add_u32_e32 v231, 0x80, v199
	v_add_u32_e32 v232, 0x80, v132
	v_add_u32_e32 v233, 0x80, v136
.LBB0_535:
	ds_read_b128 v[128:131], v166
	ds_read_b128 v[156:159], v166 offset:1024
	ds_read_b128 v[160:163], v166 offset:2048
	ds_read_b128 v[170:173], v166 offset:3072
	ds_read_b128 v[174:177], v167
	ds_read_b128 v[178:181], v167 offset:1024
	ds_read_b128 v[182:185], v167 offset:2048
	ds_read_b128 v[186:189], v167 offset:3072
	s_add_i32 s97, s60, 2
	s_add_u32 s16, s58, 0x80
	s_addc_u32 s17, s59, 0
	s_cmp_eq_u32 s76, s60
	s_cselect_b32 s60, s0, s16
	s_cselect_b32 s61, s1, s17
	s_cselect_b32 vcc_hi, s57, s96
	s_cselect_b32 vcc_lo, s56, s95
	s_add_i32 m0, s62, 0xc000
	ds_read_b128 v[190:193], v168
	ds_read_b128 v[194:197], v168 offset:1024
	ds_read_b128 v[202:205], v168 offset:2048
	ds_read_b128 v[206:209], v168 offset:3072
	ds_read_b128 v[210:213], v168 offset:4096
	ds_read_b128 v[214:217], v168 offset:5120
	ds_read_b128 v[218:221], v168 offset:6144
	ds_read_b128 v[222:225], v168 offset:7168
	global_load_lds_dwordx4 v148, s[58:59]
	s_add_i32 m0, s62, 0xe000
	s_nop 0
	global_load_lds_dwordx4 v150, s[58:59]
	s_waitcnt vmcnt(8)
	s_waitcnt lgkmcnt(0)
	s_barrier
; #define PG8_STAGE(bufoff, gbase, voff) do { _Pragma("unroll") for (int _i = 0; _i < 2; ++_i) \
;         __builtin_amdgcn_global_load_lds((const unsigned*)((const char*)(gbase) + (voff)[_i]), (PG8_LAS unsigned*)(lds + (bufoff) + ldsw + _i * 8192), 16, 0, 0); } while (0)
; #define PG8_LDA(dst, b, h) do { _Pragma("unroll") for (int m = 0; m < 4; ++m) _Pragma("unroll") for (int k = 0; k < 2; ++k) dst[m][k] = *(const PG8_LAS bf16x8*)(lds + PG8_SA(b, h) + aoff + m * 2048 + k * 1024); } while (0)
; #define PG8_MMA(ai, bj, At, Bt) do { __builtin_amdgcn_s_setprio(1); _Pragma("unroll") for (int m = 0; m < 4; ++m) _Pragma("unroll") for (int n = 0; n < 2; ++n) _Pragma("unroll") for (int k = 0; k < 2; ++k) \
;         acc[ai][bj][m][n] = __builtin_amdgcn_mfma_f32_16x16x32_bf16(Bt[n][k], At[m][k], acc[ai][bj][m][n], 0, 0, 0); __builtin_amdgcn_s_setprio(0); } while (0)
; #define PG8_WAIT_V(n) asm volatile("s_waitcnt vmcnt(" #n ")" ::: "memory")
; #define PG8_WAIT_L(n) asm volatile("s_waitcnt lgkmcnt(" #n ")" ::: "memory")
; #define PG8_BAR __builtin_amdgcn_s_barrier()
; #define PG8_SCHED __builtin_amdgcn_sched_barrier(0)
; template <class Epi, class Sched, bool ALIGN_EPI = false, bool SP2 = false>
; __device__ __forceinline__ void gemm_phase(PG8_LAS unsigned char* lds, const Gemm g, const Sched& S, const Epi& E) {
;     ...
;             PG8_WAIT_V(8); PG8_WAIT_L(0); PG8_BAR; PG8_MMA(0, 0, At, B0); PG8_MMA(0, 1, At, B1); PG8_BAR; PG8_SCHED;
;             PG8_LDA(At, 0, 1); PG8_STAGE(PG8_SB(0, 0), b2, voffB); PG8_STAGE(PG8_SB(0, 1), b2 + hstep, voffB); PG8_STAGE(PG8_SA(0, 0), a2, voffA);
;             PG8_WAIT_V(8); PG8_WAIT_L(0); PG8_BAR; PG8_MMA(1, 0, At, B0); PG8_MMA(1, 1, At, B1); PG8_BAR; PG8_SCHED;
	s_setprio 1
	s_waitcnt lgkmcnt(0)
	v_mfma_f32_16x16x32_bf16 v[120:123], v[128:131], v[190:193], v[120:123]
	v_mfma_f32_16x16x32_bf16 v[124:127], v[160:163], v[190:193], v[124:127]
	v_mfma_f32_16x16x32_bf16 v[108:111], v[128:131], v[202:205], v[108:111]
	v_mfma_f32_16x16x32_bf16 v[104:107], v[160:163], v[202:205], v[104:107]
	v_mfma_f32_16x16x32_bf16 v[92:95], v[128:131], v[210:213], v[92:95]
	v_mfma_f32_16x16x32_bf16 v[88:91], v[160:163], v[210:213], v[88:91]
	v_mfma_f32_16x16x32_bf16 v[76:79], v[128:131], v[218:221], v[76:79]
	v_mfma_f32_16x16x32_bf16 v[72:75], v[160:163], v[218:221], v[72:75]
	v_mfma_f32_16x16x32_bf16 v[120:123], v[156:159], v[194:197], v[120:123]
	v_mfma_f32_16x16x32_bf16 v[124:127], v[170:173], v[194:197], v[124:127]
	v_mfma_f32_16x16x32_bf16 v[108:111], v[156:159], v[206:209], v[108:111]
	v_mfma_f32_16x16x32_bf16 v[104:107], v[170:173], v[206:209], v[104:107]
	v_mfma_f32_16x16x32_bf16 v[92:95], v[156:159], v[214:217], v[92:95]
	v_mfma_f32_16x16x32_bf16 v[88:91], v[170:173], v[214:217], v[88:91]
	v_mfma_f32_16x16x32_bf16 v[76:79], v[156:159], v[222:225], v[76:79]
	v_mfma_f32_16x16x32_bf16 v[72:75], v[170:173], v[222:225], v[72:75]
	s_setprio 0
	s_setprio 1
	v_mfma_f32_16x16x32_bf16 v[116:119], v[174:177], v[190:193], v[116:119]
	v_mfma_f32_16x16x32_bf16 v[112:115], v[182:185], v[190:193], v[112:115]
	v_mfma_f32_16x16x32_bf16 v[100:103], v[174:177], v[202:205], v[100:103]
	v_mfma_f32_16x16x32_bf16 v[96:99], v[182:185], v[202:205], v[96:99]
	v_mfma_f32_16x16x32_bf16 v[84:87], v[174:177], v[210:213], v[84:87]
	v_mfma_f32_16x16x32_bf16 v[80:83], v[182:185], v[210:213], v[80:83]
	v_mfma_f32_16x16x32_bf16 v[68:71], v[174:177], v[218:221], v[68:71]
	v_mfma_f32_16x16x32_bf16 v[64:67], v[182:185], v[218:221], v[64:67]
	v_mfma_f32_16x16x32_bf16 v[116:119], v[178:181], v[194:197], v[116:119]
	v_mfma_f32_16x16x32_bf16 v[112:115], v[186:189], v[194:197], v[112:115]
	v_mfma_f32_16x16x32_bf16 v[100:103], v[178:181], v[206:209], v[100:103]
	v_mfma_f32_16x16x32_bf16 v[96:99], v[186:189], v[206:209], v[96:99]
	v_mfma_f32_16x16x32_bf16 v[84:87], v[178:181], v[214:217], v[84:87]
	v_mfma_f32_16x16x32_bf16 v[80:83], v[186:189], v[214:217], v[80:83]
	v_mfma_f32_16x16x32_bf16 v[68:71], v[178:181], v[222:225], v[68:71]
	v_mfma_f32_16x16x32_bf16 v[64:67], v[186:189], v[222:225], v[64:67]
	s_setprio 0
	s_barrier
	s_add_i32 s16, s79, s49
	s_mov_b32 m0, s16
	ds_read_b128 v[190:193], v168 offset:16384
	ds_read_b128 v[194:197], v168 offset:17408
	ds_read_b128 v[202:205], v168 offset:18432
	ds_read_b128 v[206:209], v168 offset:19456
	ds_read_b128 v[210:213], v168 offset:20480
	ds_read_b128 v[214:217], v168 offset:21504
	ds_read_b128 v[218:221], v168 offset:22528
	ds_read_b128 v[222:225], v168 offset:23552
	global_load_lds_dwordx4 v134, vcc
	s_add_i32 m0, s16, 0x2000
	s_add_i32 s16, s80, s49
	global_load_lds_dwordx4 v138, vcc
	s_mov_b32 m0, s16
	s_nop 0
	global_load_lds_dwordx4 v198, vcc
	s_add_i32 m0, s16, 0x2000
	s_nop 0
	global_load_lds_dwordx4 v199, vcc
	s_mov_b32 m0, s62
	s_nop 0
	global_load_lds_dwordx4 v132, s[60:61]
	s_mov_b32 m0, s63
	s_nop 0
	global_load_lds_dwordx4 v136, s[60:61]
	s_waitcnt vmcnt(8)
	s_waitcnt lgkmcnt(0)
	s_barrier
	s_setprio 1
	s_waitcnt lgkmcnt(0)
	v_mfma_f32_16x16x32_bf16 v[60:63], v[128:131], v[190:193], v[60:63]
	v_mfma_f32_16x16x32_bf16 v[56:59], v[160:163], v[190:193], v[56:59]
	v_mfma_f32_16x16x32_bf16 v[44:47], v[128:131], v[202:205], v[44:47]
	v_mfma_f32_16x16x32_bf16 v[40:43], v[160:163], v[202:205], v[40:43]
	v_mfma_f32_16x16x32_bf16 v[28:31], v[128:131], v[210:213], v[28:31]
	v_mfma_f32_16x16x32_bf16 v[24:27], v[160:163], v[210:213], v[24:27]
	v_mfma_f32_16x16x32_bf16 v[12:15], v[128:131], v[218:221], v[12:15]
	v_mfma_f32_16x16x32_bf16 v[8:11], v[160:163], v[218:221], v[8:11]
	v_mfma_f32_16x16x32_bf16 v[60:63], v[156:159], v[194:197], v[60:63]
	v_mfma_f32_16x16x32_bf16 v[56:59], v[170:173], v[194:197], v[56:59]
	v_mfma_f32_16x16x32_bf16 v[44:47], v[156:159], v[206:209], v[44:47]
	v_mfma_f32_16x16x32_bf16 v[40:43], v[170:173], v[206:209], v[40:43]
	v_mfma_f32_16x16x32_bf16 v[28:31], v[156:159], v[214:217], v[28:31]
	v_mfma_f32_16x16x32_bf16 v[24:27], v[170:173], v[214:217], v[24:27]
	v_mfma_f32_16x16x32_bf16 v[12:15], v[156:159], v[222:225], v[12:15]
	v_mfma_f32_16x16x32_bf16 v[8:11], v[170:173], v[222:225], v[8:11]
	s_setprio 0
	s_setprio 1
	v_mfma_f32_16x16x32_bf16 v[52:55], v[174:177], v[190:193], v[52:55]
	v_mfma_f32_16x16x32_bf16 v[48:51], v[182:185], v[190:193], v[48:51]
	v_mfma_f32_16x16x32_bf16 v[36:39], v[174:177], v[202:205], v[36:39]
	v_mfma_f32_16x16x32_bf16 v[32:35], v[182:185], v[202:205], v[32:35]
	v_mfma_f32_16x16x32_bf16 v[20:23], v[174:177], v[210:213], v[20:23]
	v_mfma_f32_16x16x32_bf16 v[16:19], v[182:185], v[210:213], v[16:19]
	v_mfma_f32_16x16x32_bf16 v[4:7], v[174:177], v[218:221], v[4:7]
	v_mfma_f32_16x16x32_bf16 v[0:3], v[182:185], v[218:221], v[0:3]
	v_mfma_f32_16x16x32_bf16 v[52:55], v[178:181], v[194:197], v[52:55]
	v_mfma_f32_16x16x32_bf16 v[48:51], v[186:189], v[194:197], v[48:51]
	v_mfma_f32_16x16x32_bf16 v[36:39], v[178:181], v[206:209], v[36:39]
	v_mfma_f32_16x16x32_bf16 v[32:35], v[186:189], v[206:209], v[32:35]
	v_mfma_f32_16x16x32_bf16 v[20:23], v[178:181], v[214:217], v[20:23]
	v_mfma_f32_16x16x32_bf16 v[16:19], v[186:189], v[214:217], v[16:19]
	v_mfma_f32_16x16x32_bf16 v[4:7], v[178:181], v[222:225], v[4:7]
	v_mfma_f32_16x16x32_bf16 v[0:3], v[186:189], v[222:225], v[0:3]
	s_setprio 0
	s_barrier
; #define PG8_STAGE(bufoff, gbase, voff) do { _Pragma("unroll") for (int _i = 0; _i < 2; ++_i) \
;         __builtin_amdgcn_global_load_lds((const unsigned*)((const char*)(gbase) + (voff)[_i]), (PG8_LAS unsigned*)(lds + (bufoff) + ldsw + _i * 8192), 16, 0, 0); } while (0)
; #define PG8_LDA(dst, b, h) do { _Pragma("unroll") for (int m = 0; m < 4; ++m) _Pragma("unroll") for (int k = 0; k < 2; ++k) dst[m][k] = *(const PG8_LAS bf16x8*)(lds + PG8_SA(b, h) + aoff + m * 2048 + k * 1024); } while (0)
; #define PG8_LDB(dst, b, h) do { _Pragma("unroll") for (int n = 0; n < 2; ++n) _Pragma("unroll") for (int k = 0; k < 2; ++k) dst[n][k] = *(const PG8_LAS bf16x8*)(lds + PG8_SB(b, h) + boff + n * 2048 + k * 1024); } while (0)
; #define PG8_MMA(ai, bj, At, Bt) do { __builtin_amdgcn_s_setprio(1); _Pragma("unroll") for (int m = 0; m < 4; ++m) _Pragma("unroll") for (int n = 0; n < 2; ++n) _Pragma("unroll") for (int k = 0; k < 2; ++k) \
;         acc[ai][bj][m][n] = __builtin_amdgcn_mfma_f32_16x16x32_bf16(Bt[n][k], At[m][k], acc[ai][bj][m][n], 0, 0, 0); __builtin_amdgcn_s_setprio(0); } while (0)
; #define PG8_WAIT_V(n) asm volatile("s_waitcnt vmcnt(" #n ")" ::: "memory")
; #define PG8_WAIT_L(n) asm volatile("s_waitcnt lgkmcnt(" #n ")" ::: "memory")
; #define PG8_BAR __builtin_amdgcn_s_barrier()
; #define PG8_SCHED __builtin_amdgcn_sched_barrier(0)
; template <class Epi, class Sched, bool ALIGN_EPI = false, bool SP2 = false>
; __device__ __forceinline__ void gemm_phase(PG8_LAS unsigned char* lds, const Gemm g, const Sched& S, const Epi& E) {
;     ...
;             PG8_LDB(B0, 1, 0); PG8_LDB(B1, 1, 1); PG8_SCHED; PG8_LDA(At, 1, 0); PG8_STAGE(PG8_SA(0, 1), a2 + hstep, voffA);
;             PG8_WAIT_V(8); PG8_WAIT_L(0); PG8_BAR; PG8_MMA(0, 0, At, B0); PG8_MMA(0, 1, At, B1); PG8_BAR; PG8_SCHED;
;             PG8_LDA(At, 1, 1); PG8_STAGE(PG8_SB(1, 0), b3, voffB); PG8_STAGE(PG8_SB(1, 1), b3 + hstep, voffB); PG8_STAGE(PG8_SA(1, 0), a3, voffA);
;             PG8_WAIT_V(8); PG8_WAIT_L(0); PG8_BAR; PG8_MMA(1, 0, At, B0); PG8_MMA(1, 1, At, B1); PG8_BAR; PG8_SCHED;
	s_add_i32 s16, 0, 0x18000
	v_add_u32_e32 v140, s16, v165
	s_add_i32 s17, 0, 0x1c000
	ds_read_b128 v[128:131], v140
	ds_read_b128 v[156:159], v140 offset:1024
	ds_read_b128 v[160:163], v140 offset:2048
	ds_read_b128 v[170:173], v140 offset:3072
	v_add_u32_e32 v140, s17, v165
	ds_read_b128 v[174:177], v140
	ds_read_b128 v[178:181], v140 offset:1024
	ds_read_b128 v[182:185], v140 offset:2048
	ds_read_b128 v[186:189], v140 offset:3072
	s_mov_b32 m0, s70
	ds_read_b128 v[190:193], v168 offset:32768
	ds_read_b128 v[194:197], v168 offset:33792
	ds_read_b128 v[202:205], v168 offset:34816
	ds_read_b128 v[206:209], v168 offset:35840
	ds_read_b128 v[210:213], v168 offset:36864
	ds_read_b128 v[214:217], v168 offset:37888
	ds_read_b128 v[218:221], v168 offset:38912
	ds_read_b128 v[222:225], v168 offset:39936
	global_load_lds_dwordx4 v226, s[60:61]
	s_mov_b32 m0, s71
	s_nop 0
	global_load_lds_dwordx4 v227, s[60:61]
	s_waitcnt vmcnt(8)
	s_waitcnt lgkmcnt(0)
	s_barrier
	s_setprio 1
	s_waitcnt lgkmcnt(0)
	v_mfma_f32_16x16x32_bf16 v[120:123], v[128:131], v[190:193], v[120:123]
	v_mfma_f32_16x16x32_bf16 v[124:127], v[160:163], v[190:193], v[124:127]
	v_mfma_f32_16x16x32_bf16 v[108:111], v[128:131], v[202:205], v[108:111]
	v_mfma_f32_16x16x32_bf16 v[104:107], v[160:163], v[202:205], v[104:107]
	v_mfma_f32_16x16x32_bf16 v[92:95], v[128:131], v[210:213], v[92:95]
	v_mfma_f32_16x16x32_bf16 v[88:91], v[160:163], v[210:213], v[88:91]
	v_mfma_f32_16x16x32_bf16 v[76:79], v[128:131], v[218:221], v[76:79]
	v_mfma_f32_16x16x32_bf16 v[72:75], v[160:163], v[218:221], v[72:75]
	v_mfma_f32_16x16x32_bf16 v[120:123], v[156:159], v[194:197], v[120:123]
	v_mfma_f32_16x16x32_bf16 v[124:127], v[170:173], v[194:197], v[124:127]
	v_mfma_f32_16x16x32_bf16 v[108:111], v[156:159], v[206:209], v[108:111]
	v_mfma_f32_16x16x32_bf16 v[104:107], v[170:173], v[206:209], v[104:107]
	v_mfma_f32_16x16x32_bf16 v[92:95], v[156:159], v[214:217], v[92:95]
	v_mfma_f32_16x16x32_bf16 v[88:91], v[170:173], v[214:217], v[88:91]
	v_mfma_f32_16x16x32_bf16 v[76:79], v[156:159], v[222:225], v[76:79]
	v_mfma_f32_16x16x32_bf16 v[72:75], v[170:173], v[222:225], v[72:75]
	s_setprio 0
	s_setprio 1
	v_mfma_f32_16x16x32_bf16 v[116:119], v[174:177], v[190:193], v[116:119]
	v_mfma_f32_16x16x32_bf16 v[112:115], v[182:185], v[190:193], v[112:115]
	v_mfma_f32_16x16x32_bf16 v[100:103], v[174:177], v[202:205], v[100:103]
	v_mfma_f32_16x16x32_bf16 v[96:99], v[182:185], v[202:205], v[96:99]
	v_mfma_f32_16x16x32_bf16 v[84:87], v[174:177], v[210:213], v[84:87]
	v_mfma_f32_16x16x32_bf16 v[80:83], v[182:185], v[210:213], v[80:83]
	v_mfma_f32_16x16x32_bf16 v[68:71], v[174:177], v[218:221], v[68:71]
	v_mfma_f32_16x16x32_bf16 v[64:67], v[182:185], v[218:221], v[64:67]
	v_mfma_f32_16x16x32_bf16 v[116:119], v[178:181], v[194:197], v[116:119]
	v_mfma_f32_16x16x32_bf16 v[112:115], v[186:189], v[194:197], v[112:115]
	v_mfma_f32_16x16x32_bf16 v[100:103], v[178:181], v[206:209], v[100:103]
	v_mfma_f32_16x16x32_bf16 v[96:99], v[186:189], v[206:209], v[96:99]
	v_mfma_f32_16x16x32_bf16 v[84:87], v[178:181], v[214:217], v[84:87]
	v_mfma_f32_16x16x32_bf16 v[80:83], v[186:189], v[214:217], v[80:83]
	v_mfma_f32_16x16x32_bf16 v[68:71], v[178:181], v[222:225], v[68:71]
	v_mfma_f32_16x16x32_bf16 v[64:67], v[186:189], v[222:225], v[64:67]
	s_setprio 0
	s_barrier
	s_add_i32 s16, s16, s49
	s_mov_b32 m0, s16
	ds_read_b128 v[190:193], v168 offset:49152
	ds_read_b128 v[194:197], v168 offset:50176
	ds_read_b128 v[202:205], v168 offset:51200
	ds_read_b128 v[206:209], v168 offset:52224
	ds_read_b128 v[210:213], v168 offset:53248
	ds_read_b128 v[214:217], v168 offset:54272
	ds_read_b128 v[218:221], v168 offset:55296
	ds_read_b128 v[222:225], v168 offset:56320
	global_load_lds_dwordx4 v228, vcc
	s_add_i32 m0, s16, 0x2000
	s_add_i32 s16, s17, s49
	global_load_lds_dwordx4 v229, vcc
	s_mov_b32 m0, s16
	s_nop 0
	global_load_lds_dwordx4 v230, vcc
	s_add_i32 m0, s16, 0x2000
	s_nop 0
	global_load_lds_dwordx4 v231, vcc
	s_mov_b32 m0, s72
	s_nop 0
	global_load_lds_dwordx4 v232, s[60:61]
	s_mov_b32 m0, s73
	s_nop 0
	global_load_lds_dwordx4 v233, s[60:61]
	s_waitcnt vmcnt(8)
	s_waitcnt lgkmcnt(0)
	s_barrier
	s_setprio 1
	s_waitcnt lgkmcnt(0)
	v_mfma_f32_16x16x32_bf16 v[60:63], v[128:131], v[190:193], v[60:63]
	v_mfma_f32_16x16x32_bf16 v[56:59], v[160:163], v[190:193], v[56:59]
	v_mfma_f32_16x16x32_bf16 v[44:47], v[128:131], v[202:205], v[44:47]
	v_mfma_f32_16x16x32_bf16 v[40:43], v[160:163], v[202:205], v[40:43]
	v_mfma_f32_16x16x32_bf16 v[28:31], v[128:131], v[210:213], v[28:31]
	v_mfma_f32_16x16x32_bf16 v[24:27], v[160:163], v[210:213], v[24:27]
	v_mfma_f32_16x16x32_bf16 v[12:15], v[128:131], v[218:221], v[12:15]
	v_mfma_f32_16x16x32_bf16 v[8:11], v[160:163], v[218:221], v[8:11]
	v_mfma_f32_16x16x32_bf16 v[60:63], v[156:159], v[194:197], v[60:63]
	v_mfma_f32_16x16x32_bf16 v[56:59], v[170:173], v[194:197], v[56:59]
	v_mfma_f32_16x16x32_bf16 v[44:47], v[156:159], v[206:209], v[44:47]
	v_mfma_f32_16x16x32_bf16 v[40:43], v[170:173], v[206:209], v[40:43]
	v_mfma_f32_16x16x32_bf16 v[28:31], v[156:159], v[214:217], v[28:31]
	v_mfma_f32_16x16x32_bf16 v[24:27], v[170:173], v[214:217], v[24:27]
	v_mfma_f32_16x16x32_bf16 v[12:15], v[156:159], v[222:225], v[12:15]
	v_mfma_f32_16x16x32_bf16 v[8:11], v[170:173], v[222:225], v[8:11]
	s_setprio 0
	s_setprio 1
	v_mfma_f32_16x16x32_bf16 v[52:55], v[174:177], v[190:193], v[52:55]
	v_mfma_f32_16x16x32_bf16 v[48:51], v[182:185], v[190:193], v[48:51]
	v_mfma_f32_16x16x32_bf16 v[36:39], v[174:177], v[202:205], v[36:39]
	v_mfma_f32_16x16x32_bf16 v[32:35], v[182:185], v[202:205], v[32:35]
	v_mfma_f32_16x16x32_bf16 v[20:23], v[174:177], v[210:213], v[20:23]
	v_mfma_f32_16x16x32_bf16 v[16:19], v[182:185], v[210:213], v[16:19]
	v_mfma_f32_16x16x32_bf16 v[4:7], v[174:177], v[218:221], v[4:7]
	v_mfma_f32_16x16x32_bf16 v[0:3], v[182:185], v[218:221], v[0:3]
	v_mfma_f32_16x16x32_bf16 v[52:55], v[178:181], v[194:197], v[52:55]
	v_mfma_f32_16x16x32_bf16 v[48:51], v[186:189], v[194:197], v[48:51]
	v_mfma_f32_16x16x32_bf16 v[36:39], v[178:181], v[206:209], v[36:39]
	v_mfma_f32_16x16x32_bf16 v[32:35], v[186:189], v[206:209], v[32:35]
	v_mfma_f32_16x16x32_bf16 v[20:23], v[178:181], v[214:217], v[20:23]
	v_mfma_f32_16x16x32_bf16 v[16:19], v[186:189], v[214:217], v[16:19]
	v_mfma_f32_16x16x32_bf16 v[4:7], v[178:181], v[222:225], v[4:7]
	v_mfma_f32_16x16x32_bf16 v[0:3], v[186:189], v[222:225], v[0:3]
	s_setprio 0
	s_barrier
	s_add_u32 s58, s58, 0x100
	s_addc_u32 s59, s59, 0
	s_add_u32 s95, s95, 0x100
	s_addc_u32 s96, s96, 0
	s_cmp_ge_i32 s97, s74
	s_mov_b32 s60, s97
	s_cbranch_scc0 .LBB0_535

; #define PG8_STAGE(bufoff, gbase, voff) do { _Pragma("unroll") for (int _i = 0; _i < 2; ++_i) \
;         __builtin_amdgcn_global_load_lds((const unsigned*)((const char*)(gbase) + (voff)[_i]), (PG8_LAS unsigned*)(lds + (bufoff) + ldsw + _i * 8192), 16, 0, 0); } while (0)
; #define PG8_LDA(dst, b, h) do { _Pragma("unroll") for (int m = 0; m < 4; ++m) _Pragma("unroll") for (int k = 0; k < 2; ++k) dst[m][k] = *(const PG8_LAS bf16x8*)(lds + PG8_SA(b, h) + aoff + m * 2048 + k * 1024); } while (0)
; #define PG8_LDB(dst, b, h) do { _Pragma("unroll") for (int n = 0; n < 2; ++n) _Pragma("unroll") for (int k = 0; k < 2; ++k) dst[n][k] = *(const PG8_LAS bf16x8*)(lds + PG8_SB(b, h) + boff + n * 2048 + k * 1024); } while (0)
; #define PG8_MMA(ai, bj, At, Bt) do { __builtin_amdgcn_s_setprio(1); _Pragma("unroll") for (int m = 0; m < 4; ++m) _Pragma("unroll") for (int n = 0; n < 2; ++n) _Pragma("unroll") for (int k = 0; k < 2; ++k) \
;         acc[ai][bj][m][n] = __builtin_amdgcn_mfma_f32_16x16x32_bf16(Bt[n][k], At[m][k], acc[ai][bj][m][n], 0, 0, 0); __builtin_amdgcn_s_setprio(0); } while (0)
; #define PG8_WAIT_V(n) asm volatile("s_waitcnt vmcnt(" #n ")" ::: "memory")
; #define PG8_BAR __builtin_amdgcn_s_barrier()
; template <class Epi, class Sched, bool ALIGN_EPI = false, bool SP2 = false>
; __device__ __forceinline__ void gemm_phase(PG8_LAS unsigned char* lds, const Gemm g, const Sched& S, const Epi& E) {
;     ...
;         for (int t = 0; t < nt; t += 2) {
;             const bool last = (t == nt - 2);
;             const char* a1 = cA + (size_t)(t + 1) * kstep;
;             const char* a2 = last ? nA : cA + (size_t)(t + 2) * kstep; const char* b2 = last ? nB : cB + (size_t)(t + 2) * kstep;
;             const char* a3 = a2 + kstep; const char* b3 = b2 + kstep;
;             if (last && has_next) S.a_ready(nxt);
;             if constexpr (SP2) {
;             PG8_LDB(B0, 0, 0); PG8_LDB(B1, 0, 1); PG8_SCHED; PG8_LDA(At, 0, 0); PG8_STAGE(PG8_SA(1, 1), a1 + hstep, voffA);
;             PG8_WAIT_V(8); PG8_WAIT_L(0); PG8_BAR; PG8_MMA(0, 0, At, B0); PG8_MMA(0, 1, At, B1); PG8_BAR; PG8_SCHED;
;     ...
; #pragma unroll
;         for (int a = 0; a < 2; ++a)
; #pragma unroll
;             for (int b = 0; b < 2; ++b)
; #pragma unroll
;                 for (int m = 0; m < 4; ++m)
; #pragma unroll
;                     for (int n = 0; n < 2; ++n) acc[a][b][m][n] = (f32x4){0.f, 0.f, 0.f, 0.f};
.LBB0_726:
	v_mov_b32_e32 v123, 0
	s_andn2_b64 vcc, exec, s[46:47]
	v_mov_b32_e32 v122, v123
	v_mov_b32_e32 v121, v123
	v_mov_b32_e32 v120, v123
	v_mov_b32_e32 v127, v123
	v_mov_b32_e32 v126, v123
	v_mov_b32_e32 v125, v123
	v_mov_b32_e32 v124, v123
	v_mov_b32_e32 v111, v123
	v_mov_b32_e32 v110, v123
	v_mov_b32_e32 v109, v123
	v_mov_b32_e32 v108, v123
	v_mov_b32_e32 v107, v123
	v_mov_b32_e32 v106, v123
	v_mov_b32_e32 v105, v123
	v_mov_b32_e32 v104, v123
	v_mov_b32_e32 v95, v123
	v_mov_b32_e32 v94, v123
	v_mov_b32_e32 v93, v123
	v_mov_b32_e32 v92, v123
	v_mov_b32_e32 v91, v123
	v_mov_b32_e32 v90, v123
	v_mov_b32_e32 v89, v123
	v_mov_b32_e32 v88, v123
	v_mov_b32_e32 v79, v123
	v_mov_b32_e32 v78, v123
	v_mov_b32_e32 v77, v123
	v_mov_b32_e32 v76, v123
	v_mov_b32_e32 v75, v123
	v_mov_b32_e32 v74, v123
	v_mov_b32_e32 v73, v123
	v_mov_b32_e32 v72, v123
	v_mov_b32_e32 v119, v123
	v_mov_b32_e32 v118, v123
	v_mov_b32_e32 v117, v123
	v_mov_b32_e32 v116, v123
	v_mov_b32_e32 v115, v123
	v_mov_b32_e32 v114, v123
	v_mov_b32_e32 v113, v123
	v_mov_b32_e32 v112, v123
	v_mov_b32_e32 v103, v123
	v_mov_b32_e32 v102, v123
	v_mov_b32_e32 v101, v123
	v_mov_b32_e32 v100, v123
	v_mov_b32_e32 v99, v123
	v_mov_b32_e32 v98, v123
	v_mov_b32_e32 v97, v123
	v_mov_b32_e32 v96, v123
	v_mov_b32_e32 v87, v123
	v_mov_b32_e32 v86, v123
	v_mov_b32_e32 v85, v123
	v_mov_b32_e32 v84, v123
	v_mov_b32_e32 v83, v123
	v_mov_b32_e32 v82, v123
	v_mov_b32_e32 v81, v123
	v_mov_b32_e32 v80, v123
	v_mov_b32_e32 v71, v123
	v_mov_b32_e32 v70, v123
	v_mov_b32_e32 v69, v123
	v_mov_b32_e32 v68, v123
	v_mov_b32_e32 v67, v123
	v_mov_b32_e32 v66, v123
	v_mov_b32_e32 v65, v123
	v_mov_b32_e32 v64, v123
	v_mov_b32_e32 v63, v123
	v_mov_b32_e32 v62, v123
	v_mov_b32_e32 v61, v123
	v_mov_b32_e32 v60, v123
	v_mov_b32_e32 v59, v123
	v_mov_b32_e32 v58, v123
	v_mov_b32_e32 v57, v123
	v_mov_b32_e32 v56, v123
	v_mov_b32_e32 v47, v123
	v_mov_b32_e32 v46, v123
	v_mov_b32_e32 v45, v123
	v_mov_b32_e32 v44, v123
	v_mov_b32_e32 v43, v123
	v_mov_b32_e32 v42, v123
	v_mov_b32_e32 v41, v123
	v_mov_b32_e32 v40, v123
	v_mov_b32_e32 v31, v123
	v_mov_b32_e32 v30, v123
	v_mov_b32_e32 v29, v123
	v_mov_b32_e32 v28, v123
	v_mov_b32_e32 v27, v123
	v_mov_b32_e32 v26, v123
	v_mov_b32_e32 v25, v123
	v_mov_b32_e32 v24, v123
	v_mov_b32_e32 v15, v123
	v_mov_b32_e32 v14, v123
	v_mov_b32_e32 v13, v123
	v_mov_b32_e32 v12, v123
	v_mov_b32_e32 v11, v123
	v_mov_b32_e32 v10, v123
	v_mov_b32_e32 v9, v123
	v_mov_b32_e32 v8, v123
	v_mov_b32_e32 v55, v123
	v_mov_b32_e32 v54, v123
	v_mov_b32_e32 v53, v123
	v_mov_b32_e32 v52, v123
	v_mov_b32_e32 v51, v123
	v_mov_b32_e32 v50, v123
	v_mov_b32_e32 v49, v123
	v_mov_b32_e32 v48, v123
	v_mov_b32_e32 v39, v123
	v_mov_b32_e32 v38, v123
	v_mov_b32_e32 v37, v123
	v_mov_b32_e32 v36, v123
	v_mov_b32_e32 v35, v123
	v_mov_b32_e32 v34, v123
	v_mov_b32_e32 v33, v123
	v_mov_b32_e32 v32, v123
	v_mov_b32_e32 v23, v123
	v_mov_b32_e32 v22, v123
	v_mov_b32_e32 v21, v123
	v_mov_b32_e32 v20, v123
	v_mov_b32_e32 v19, v123
	v_mov_b32_e32 v18, v123
	v_mov_b32_e32 v17, v123
	v_mov_b32_e32 v16, v123
	v_mov_b32_e32 v7, v123
	v_mov_b32_e32 v6, v123
	v_mov_b32_e32 v5, v123
	v_mov_b32_e32 v4, v123
	v_mov_b32_e32 v3, v123
	v_mov_b32_e32 v2, v123
	v_mov_b32_e32 v1, v123
	v_mov_b32_e32 v0, v123
	s_cbranch_vccnz .LBB0_729
	s_add_u32 s6, s6, 0x80
	s_addc_u32 s7, s7, 0
	s_add_u32 s79, s52, 0x100
	s_addc_u32 s80, s53, 0
	s_mov_b32 s52, 0
	v_add_u32_e32 v164, s10, v134
	v_add_u32_e32 v165, s10, v138
	v_add_u32_e32 v218, s10, v132
	v_add_u32_e32 v219, s10, v136
	v_add_u32_e32 v220, 0x80, v134
	v_add_u32_e32 v221, 0x80, v138
	v_add_u32_e32 v222, 0x80, v164
	v_add_u32_e32 v223, 0x80, v165
	v_add_u32_e32 v224, 0x80, v132
	v_add_u32_e32 v225, 0x80, v136
.LBB0_728:
	ds_read_b128 v[128:131], v169
	ds_read_b128 v[148:151], v169 offset:1024
	ds_read_b128 v[152:155], v169 offset:2048
	ds_read_b128 v[156:159], v169 offset:3072
	ds_read_b128 v[160:163], v170
	ds_read_b128 v[172:175], v170 offset:1024
	ds_read_b128 v[176:179], v170 offset:2048
	ds_read_b128 v[180:183], v170 offset:3072
	s_add_i32 s81, s52, 2
	s_add_u32 s16, s6, 0x80
	s_addc_u32 s17, s7, 0
	s_cmp_eq_u32 s69, s52
	s_cselect_b32 s52, s0, s16
	s_cselect_b32 s53, s1, s17
	s_cselect_b32 s83, s51, s80
	s_cselect_b32 s82, s50, s79
	s_add_i32 m0, s56, 0xc000
	ds_read_b128 v[184:187], v171
	ds_read_b128 v[188:191], v171 offset:1024
	ds_read_b128 v[192:195], v171 offset:2048
	ds_read_b128 v[196:199], v171 offset:3072
	ds_read_b128 v[202:205], v171 offset:4096
	ds_read_b128 v[206:209], v171 offset:5120
	ds_read_b128 v[210:213], v171 offset:6144
	ds_read_b128 v[214:217], v171 offset:7168
	global_load_lds_dwordx4 v140, s[6:7]
	s_add_i32 m0, s56, 0xe000
	s_nop 0
	global_load_lds_dwordx4 v142, s[6:7]
	s_waitcnt vmcnt(8)
	s_waitcnt lgkmcnt(0)
	s_barrier
; #define PG8_STAGE(bufoff, gbase, voff) do { _Pragma("unroll") for (int _i = 0; _i < 2; ++_i) \
;         __builtin_amdgcn_global_load_lds((const unsigned*)((const char*)(gbase) + (voff)[_i]), (PG8_LAS unsigned*)(lds + (bufoff) + ldsw + _i * 8192), 16, 0, 0); } while (0)
; #define PG8_LDA(dst, b, h) do { _Pragma("unroll") for (int m = 0; m < 4; ++m) _Pragma("unroll") for (int k = 0; k < 2; ++k) dst[m][k] = *(const PG8_LAS bf16x8*)(lds + PG8_SA(b, h) + aoff + m * 2048 + k * 1024); } while (0)
; #define PG8_MMA(ai, bj, At, Bt) do { __builtin_amdgcn_s_setprio(1); _Pragma("unroll") for (int m = 0; m < 4; ++m) _Pragma("unroll") for (int n = 0; n < 2; ++n) _Pragma("unroll") for (int k = 0; k < 2; ++k) \
;         acc[ai][bj][m][n] = __builtin_amdgcn_mfma_f32_16x16x32_bf16(Bt[n][k], At[m][k], acc[ai][bj][m][n], 0, 0, 0); __builtin_amdgcn_s_setprio(0); } while (0)
; #define PG8_WAIT_V(n) asm volatile("s_waitcnt vmcnt(" #n ")" ::: "memory")
; #define PG8_WAIT_L(n) asm volatile("s_waitcnt lgkmcnt(" #n ")" ::: "memory")
; #define PG8_BAR __builtin_amdgcn_s_barrier()
; #define PG8_SCHED __builtin_amdgcn_sched_barrier(0)
; template <class Epi, class Sched, bool ALIGN_EPI = false, bool SP2 = false>
; __device__ __forceinline__ void gemm_phase(PG8_LAS unsigned char* lds, const Gemm g, const Sched& S, const Epi& E) {
;     ...
;             PG8_WAIT_V(8); PG8_WAIT_L(0); PG8_BAR; PG8_MMA(0, 0, At, B0); PG8_MMA(0, 1, At, B1); PG8_BAR; PG8_SCHED;
;             PG8_LDA(At, 0, 1); PG8_STAGE(PG8_SB(0, 0), b2, voffB); PG8_STAGE(PG8_SB(0, 1), b2 + hstep, voffB); PG8_STAGE(PG8_SA(0, 0), a2, voffA);
;             PG8_WAIT_V(8); PG8_WAIT_L(0); PG8_BAR; PG8_MMA(1, 0, At, B0); PG8_MMA(1, 1, At, B1); PG8_BAR; PG8_SCHED;
	s_setprio 1
	s_waitcnt lgkmcnt(0)
	v_mfma_f32_16x16x32_bf16 v[120:123], v[128:131], v[184:187], v[120:123]
	v_mfma_f32_16x16x32_bf16 v[124:127], v[152:155], v[184:187], v[124:127]
	v_mfma_f32_16x16x32_bf16 v[108:111], v[128:131], v[192:195], v[108:111]
	v_mfma_f32_16x16x32_bf16 v[104:107], v[152:155], v[192:195], v[104:107]
	v_mfma_f32_16x16x32_bf16 v[92:95], v[128:131], v[202:205], v[92:95]
	v_mfma_f32_16x16x32_bf16 v[88:91], v[152:155], v[202:205], v[88:91]
	v_mfma_f32_16x16x32_bf16 v[76:79], v[128:131], v[210:213], v[76:79]
	v_mfma_f32_16x16x32_bf16 v[72:75], v[152:155], v[210:213], v[72:75]
	v_mfma_f32_16x16x32_bf16 v[120:123], v[148:151], v[188:191], v[120:123]
	v_mfma_f32_16x16x32_bf16 v[124:127], v[156:159], v[188:191], v[124:127]
	v_mfma_f32_16x16x32_bf16 v[108:111], v[148:151], v[196:199], v[108:111]
	v_mfma_f32_16x16x32_bf16 v[104:107], v[156:159], v[196:199], v[104:107]
	v_mfma_f32_16x16x32_bf16 v[92:95], v[148:151], v[206:209], v[92:95]
	v_mfma_f32_16x16x32_bf16 v[88:91], v[156:159], v[206:209], v[88:91]
	v_mfma_f32_16x16x32_bf16 v[76:79], v[148:151], v[214:217], v[76:79]
	v_mfma_f32_16x16x32_bf16 v[72:75], v[156:159], v[214:217], v[72:75]
	s_setprio 0
	s_setprio 1
	v_mfma_f32_16x16x32_bf16 v[116:119], v[160:163], v[184:187], v[116:119]
	v_mfma_f32_16x16x32_bf16 v[112:115], v[176:179], v[184:187], v[112:115]
	v_mfma_f32_16x16x32_bf16 v[100:103], v[160:163], v[192:195], v[100:103]
	v_mfma_f32_16x16x32_bf16 v[96:99], v[176:179], v[192:195], v[96:99]
	v_mfma_f32_16x16x32_bf16 v[84:87], v[160:163], v[202:205], v[84:87]
	v_mfma_f32_16x16x32_bf16 v[80:83], v[176:179], v[202:205], v[80:83]
	v_mfma_f32_16x16x32_bf16 v[68:71], v[160:163], v[210:213], v[68:71]
	v_mfma_f32_16x16x32_bf16 v[64:67], v[176:179], v[210:213], v[64:67]
	v_mfma_f32_16x16x32_bf16 v[116:119], v[172:175], v[188:191], v[116:119]
	v_mfma_f32_16x16x32_bf16 v[112:115], v[180:183], v[188:191], v[112:115]
	v_mfma_f32_16x16x32_bf16 v[100:103], v[172:175], v[196:199], v[100:103]
	v_mfma_f32_16x16x32_bf16 v[96:99], v[180:183], v[196:199], v[96:99]
	v_mfma_f32_16x16x32_bf16 v[84:87], v[172:175], v[206:209], v[84:87]
	v_mfma_f32_16x16x32_bf16 v[80:83], v[180:183], v[206:209], v[80:83]
	v_mfma_f32_16x16x32_bf16 v[68:71], v[172:175], v[214:217], v[68:71]
	v_mfma_f32_16x16x32_bf16 v[64:67], v[180:183], v[214:217], v[64:67]
	s_setprio 0
	s_barrier
	s_add_i32 s16, s71, s55
	s_mov_b32 m0, s16
	ds_read_b128 v[184:187], v171 offset:16384
	ds_read_b128 v[188:191], v171 offset:17408
	ds_read_b128 v[192:195], v171 offset:18432
	ds_read_b128 v[196:199], v171 offset:19456
	ds_read_b128 v[202:205], v171 offset:20480
	ds_read_b128 v[206:209], v171 offset:21504
	ds_read_b128 v[210:213], v171 offset:22528
	ds_read_b128 v[214:217], v171 offset:23552
	global_load_lds_dwordx4 v134, s[82:83]
	s_add_i32 m0, s16, 0x2000
	s_add_i32 s16, s72, s55
	global_load_lds_dwordx4 v138, s[82:83]
	s_mov_b32 m0, s16
	s_nop 0
	global_load_lds_dwordx4 v164, s[82:83]
	s_add_i32 m0, s16, 0x2000
	s_nop 0
	global_load_lds_dwordx4 v165, s[82:83]
	s_mov_b32 m0, s56
	s_nop 0
	global_load_lds_dwordx4 v132, s[52:53]
	s_mov_b32 m0, s57
	s_nop 0
	global_load_lds_dwordx4 v136, s[52:53]
	s_waitcnt vmcnt(8)
	s_waitcnt lgkmcnt(0)
	s_barrier
	s_setprio 1
	s_waitcnt lgkmcnt(0)
	v_mfma_f32_16x16x32_bf16 v[60:63], v[128:131], v[184:187], v[60:63]
	v_mfma_f32_16x16x32_bf16 v[56:59], v[152:155], v[184:187], v[56:59]
	v_mfma_f32_16x16x32_bf16 v[44:47], v[128:131], v[192:195], v[44:47]
	v_mfma_f32_16x16x32_bf16 v[40:43], v[152:155], v[192:195], v[40:43]
	v_mfma_f32_16x16x32_bf16 v[28:31], v[128:131], v[202:205], v[28:31]
	v_mfma_f32_16x16x32_bf16 v[24:27], v[152:155], v[202:205], v[24:27]
	v_mfma_f32_16x16x32_bf16 v[12:15], v[128:131], v[210:213], v[12:15]
	v_mfma_f32_16x16x32_bf16 v[8:11], v[152:155], v[210:213], v[8:11]
	v_mfma_f32_16x16x32_bf16 v[60:63], v[148:151], v[188:191], v[60:63]
	v_mfma_f32_16x16x32_bf16 v[56:59], v[156:159], v[188:191], v[56:59]
	v_mfma_f32_16x16x32_bf16 v[44:47], v[148:151], v[196:199], v[44:47]
	v_mfma_f32_16x16x32_bf16 v[40:43], v[156:159], v[196:199], v[40:43]
	v_mfma_f32_16x16x32_bf16 v[28:31], v[148:151], v[206:209], v[28:31]
	v_mfma_f32_16x16x32_bf16 v[24:27], v[156:159], v[206:209], v[24:27]
	v_mfma_f32_16x16x32_bf16 v[12:15], v[148:151], v[214:217], v[12:15]
	v_mfma_f32_16x16x32_bf16 v[8:11], v[156:159], v[214:217], v[8:11]
	s_setprio 0
	s_setprio 1
	v_mfma_f32_16x16x32_bf16 v[52:55], v[160:163], v[184:187], v[52:55]
	v_mfma_f32_16x16x32_bf16 v[48:51], v[176:179], v[184:187], v[48:51]
	v_mfma_f32_16x16x32_bf16 v[36:39], v[160:163], v[192:195], v[36:39]
	v_mfma_f32_16x16x32_bf16 v[32:35], v[176:179], v[192:195], v[32:35]
	v_mfma_f32_16x16x32_bf16 v[20:23], v[160:163], v[202:205], v[20:23]
	v_mfma_f32_16x16x32_bf16 v[16:19], v[176:179], v[202:205], v[16:19]
	v_mfma_f32_16x16x32_bf16 v[4:7], v[160:163], v[210:213], v[4:7]
	v_mfma_f32_16x16x32_bf16 v[0:3], v[176:179], v[210:213], v[0:3]
	v_mfma_f32_16x16x32_bf16 v[52:55], v[172:175], v[188:191], v[52:55]
	v_mfma_f32_16x16x32_bf16 v[48:51], v[180:183], v[188:191], v[48:51]
	v_mfma_f32_16x16x32_bf16 v[36:39], v[172:175], v[196:199], v[36:39]
	v_mfma_f32_16x16x32_bf16 v[32:35], v[180:183], v[196:199], v[32:35]
	v_mfma_f32_16x16x32_bf16 v[20:23], v[172:175], v[206:209], v[20:23]
	v_mfma_f32_16x16x32_bf16 v[16:19], v[180:183], v[206:209], v[16:19]
	v_mfma_f32_16x16x32_bf16 v[4:7], v[172:175], v[214:217], v[4:7]
	v_mfma_f32_16x16x32_bf16 v[0:3], v[180:183], v[214:217], v[0:3]
	s_setprio 0
	s_barrier
; #define PG8_STAGE(bufoff, gbase, voff) do { _Pragma("unroll") for (int _i = 0; _i < 2; ++_i) \
;         __builtin_amdgcn_global_load_lds((const unsigned*)((const char*)(gbase) + (voff)[_i]), (PG8_LAS unsigned*)(lds + (bufoff) + ldsw + _i * 8192), 16, 0, 0); } while (0)
; #define PG8_LDA(dst, b, h) do { _Pragma("unroll") for (int m = 0; m < 4; ++m) _Pragma("unroll") for (int k = 0; k < 2; ++k) dst[m][k] = *(const PG8_LAS bf16x8*)(lds + PG8_SA(b, h) + aoff + m * 2048 + k * 1024); } while (0)
; #define PG8_LDB(dst, b, h) do { _Pragma("unroll") for (int n = 0; n < 2; ++n) _Pragma("unroll") for (int k = 0; k < 2; ++k) dst[n][k] = *(const PG8_LAS bf16x8*)(lds + PG8_SB(b, h) + boff + n * 2048 + k * 1024); } while (0)
; #define PG8_MMA(ai, bj, At, Bt) do { __builtin_amdgcn_s_setprio(1); _Pragma("unroll") for (int m = 0; m < 4; ++m) _Pragma("unroll") for (int n = 0; n < 2; ++n) _Pragma("unroll") for (int k = 0; k < 2; ++k) \
;         acc[ai][bj][m][n] = __builtin_amdgcn_mfma_f32_16x16x32_bf16(Bt[n][k], At[m][k], acc[ai][bj][m][n], 0, 0, 0); __builtin_amdgcn_s_setprio(0); } while (0)
; #define PG8_WAIT_V(n) asm volatile("s_waitcnt vmcnt(" #n ")" ::: "memory")
; #define PG8_WAIT_L(n) asm volatile("s_waitcnt lgkmcnt(" #n ")" ::: "memory")
; #define PG8_BAR __builtin_amdgcn_s_barrier()
; #define PG8_SCHED __builtin_amdgcn_sched_barrier(0)
; template <class Epi, class Sched, bool ALIGN_EPI = false, bool SP2 = false>
; __device__ __forceinline__ void gemm_phase(PG8_LAS unsigned char* lds, const Gemm g, const Sched& S, const Epi& E) {
;     ...
;             PG8_LDB(B0, 1, 0); PG8_LDB(B1, 1, 1); PG8_SCHED; PG8_LDA(At, 1, 0); PG8_STAGE(PG8_SA(0, 1), a2 + hstep, voffA);
;             PG8_WAIT_V(8); PG8_WAIT_L(0); PG8_BAR; PG8_MMA(0, 0, At, B0); PG8_MMA(0, 1, At, B1); PG8_BAR; PG8_SCHED;
;             PG8_LDA(At, 1, 1); PG8_STAGE(PG8_SB(1, 0), b3, voffB); PG8_STAGE(PG8_SB(1, 1), b3 + hstep, voffB); PG8_STAGE(PG8_SA(1, 0), a3, voffA);
;             PG8_WAIT_V(8); PG8_WAIT_L(0); PG8_BAR; PG8_MMA(1, 0, At, B0); PG8_MMA(1, 1, At, B1); PG8_BAR; PG8_SCHED;
	s_add_i32 s16, 0, 0x18000
	s_add_i32 s17, 0, 0x1c000
	v_add_u32_e32 v156, s16, v167
	v_add_u32_e32 v180, s17, v167
	ds_read_b128 v[128:131], v156
	ds_read_b128 v[148:151], v156 offset:1024
	ds_read_b128 v[152:155], v156 offset:2048
	ds_read_b128 v[156:159], v156 offset:3072
	ds_read_b128 v[160:163], v180
	ds_read_b128 v[172:175], v180 offset:1024
	ds_read_b128 v[176:179], v180 offset:2048
	ds_read_b128 v[180:183], v180 offset:3072
	s_mov_b32 m0, s58
	ds_read_b128 v[184:187], v171 offset:32768
	ds_read_b128 v[188:191], v171 offset:33792
	ds_read_b128 v[192:195], v171 offset:34816
	ds_read_b128 v[196:199], v171 offset:35840
	ds_read_b128 v[202:205], v171 offset:36864
	ds_read_b128 v[206:209], v171 offset:37888
	ds_read_b128 v[210:213], v171 offset:38912
	ds_read_b128 v[214:217], v171 offset:39936
	global_load_lds_dwordx4 v218, s[52:53]
	s_mov_b32 m0, s59
	s_nop 0
	global_load_lds_dwordx4 v219, s[52:53]
	s_waitcnt vmcnt(8)
	s_waitcnt lgkmcnt(0)
	s_barrier
	s_setprio 1
	s_waitcnt lgkmcnt(0)
	v_mfma_f32_16x16x32_bf16 v[120:123], v[128:131], v[184:187], v[120:123]
	v_mfma_f32_16x16x32_bf16 v[124:127], v[152:155], v[184:187], v[124:127]
	v_mfma_f32_16x16x32_bf16 v[108:111], v[128:131], v[192:195], v[108:111]
	v_mfma_f32_16x16x32_bf16 v[104:107], v[152:155], v[192:195], v[104:107]
	v_mfma_f32_16x16x32_bf16 v[92:95], v[128:131], v[202:205], v[92:95]
	v_mfma_f32_16x16x32_bf16 v[88:91], v[152:155], v[202:205], v[88:91]
	v_mfma_f32_16x16x32_bf16 v[76:79], v[128:131], v[210:213], v[76:79]
	v_mfma_f32_16x16x32_bf16 v[72:75], v[152:155], v[210:213], v[72:75]
	v_mfma_f32_16x16x32_bf16 v[120:123], v[148:151], v[188:191], v[120:123]
	v_mfma_f32_16x16x32_bf16 v[124:127], v[156:159], v[188:191], v[124:127]
	v_mfma_f32_16x16x32_bf16 v[108:111], v[148:151], v[196:199], v[108:111]
	v_mfma_f32_16x16x32_bf16 v[104:107], v[156:159], v[196:199], v[104:107]
	v_mfma_f32_16x16x32_bf16 v[92:95], v[148:151], v[206:209], v[92:95]
	v_mfma_f32_16x16x32_bf16 v[88:91], v[156:159], v[206:209], v[88:91]
	v_mfma_f32_16x16x32_bf16 v[76:79], v[148:151], v[214:217], v[76:79]
	v_mfma_f32_16x16x32_bf16 v[72:75], v[156:159], v[214:217], v[72:75]
	s_setprio 0
	s_setprio 1
	v_mfma_f32_16x16x32_bf16 v[116:119], v[160:163], v[184:187], v[116:119]
	v_mfma_f32_16x16x32_bf16 v[112:115], v[176:179], v[184:187], v[112:115]
	v_mfma_f32_16x16x32_bf16 v[100:103], v[160:163], v[192:195], v[100:103]
	v_mfma_f32_16x16x32_bf16 v[96:99], v[176:179], v[192:195], v[96:99]
	v_mfma_f32_16x16x32_bf16 v[84:87], v[160:163], v[202:205], v[84:87]
	v_mfma_f32_16x16x32_bf16 v[80:83], v[176:179], v[202:205], v[80:83]
	v_mfma_f32_16x16x32_bf16 v[68:71], v[160:163], v[210:213], v[68:71]
	v_mfma_f32_16x16x32_bf16 v[64:67], v[176:179], v[210:213], v[64:67]
	v_mfma_f32_16x16x32_bf16 v[116:119], v[172:175], v[188:191], v[116:119]
	v_mfma_f32_16x16x32_bf16 v[112:115], v[180:183], v[188:191], v[112:115]
	v_mfma_f32_16x16x32_bf16 v[100:103], v[172:175], v[196:199], v[100:103]
	v_mfma_f32_16x16x32_bf16 v[96:99], v[180:183], v[196:199], v[96:99]
	v_mfma_f32_16x16x32_bf16 v[84:87], v[172:175], v[206:209], v[84:87]
	v_mfma_f32_16x16x32_bf16 v[80:83], v[180:183], v[206:209], v[80:83]
	v_mfma_f32_16x16x32_bf16 v[68:71], v[172:175], v[214:217], v[68:71]
	v_mfma_f32_16x16x32_bf16 v[64:67], v[180:183], v[214:217], v[64:67]
	s_setprio 0
	s_barrier
	s_add_i32 s16, s16, s55
	s_mov_b32 m0, s16
	ds_read_b128 v[184:187], v171 offset:49152
	ds_read_b128 v[188:191], v171 offset:50176
	ds_read_b128 v[192:195], v171 offset:51200
	ds_read_b128 v[196:199], v171 offset:52224
	ds_read_b128 v[202:205], v171 offset:53248
	ds_read_b128 v[206:209], v171 offset:54272
	ds_read_b128 v[210:213], v171 offset:55296
	ds_read_b128 v[214:217], v171 offset:56320
	global_load_lds_dwordx4 v220, s[82:83]
	s_add_i32 m0, s16, 0x2000
	s_add_i32 s16, s17, s55
	global_load_lds_dwordx4 v221, s[82:83]
	s_mov_b32 m0, s16
	s_nop 0
	global_load_lds_dwordx4 v222, s[82:83]
	s_add_i32 m0, s16, 0x2000
	s_nop 0
	global_load_lds_dwordx4 v223, s[82:83]
	s_mov_b32 m0, s62
	s_nop 0
	global_load_lds_dwordx4 v224, s[52:53]
	s_mov_b32 m0, s63
	s_nop 0
	global_load_lds_dwordx4 v225, s[52:53]
	s_waitcnt vmcnt(8)
	s_waitcnt lgkmcnt(0)
	s_barrier
	s_setprio 1
	s_waitcnt lgkmcnt(0)
	v_mfma_f32_16x16x32_bf16 v[60:63], v[128:131], v[184:187], v[60:63]
	v_mfma_f32_16x16x32_bf16 v[56:59], v[152:155], v[184:187], v[56:59]
	v_mfma_f32_16x16x32_bf16 v[44:47], v[128:131], v[192:195], v[44:47]
	v_mfma_f32_16x16x32_bf16 v[40:43], v[152:155], v[192:195], v[40:43]
	v_mfma_f32_16x16x32_bf16 v[28:31], v[128:131], v[202:205], v[28:31]
	v_mfma_f32_16x16x32_bf16 v[24:27], v[152:155], v[202:205], v[24:27]
	v_mfma_f32_16x16x32_bf16 v[12:15], v[128:131], v[210:213], v[12:15]
	v_mfma_f32_16x16x32_bf16 v[8:11], v[152:155], v[210:213], v[8:11]
	v_mfma_f32_16x16x32_bf16 v[60:63], v[148:151], v[188:191], v[60:63]
	v_mfma_f32_16x16x32_bf16 v[56:59], v[156:159], v[188:191], v[56:59]
	v_mfma_f32_16x16x32_bf16 v[44:47], v[148:151], v[196:199], v[44:47]
	v_mfma_f32_16x16x32_bf16 v[40:43], v[156:159], v[196:199], v[40:43]
	v_mfma_f32_16x16x32_bf16 v[28:31], v[148:151], v[206:209], v[28:31]
	v_mfma_f32_16x16x32_bf16 v[24:27], v[156:159], v[206:209], v[24:27]
	v_mfma_f32_16x16x32_bf16 v[12:15], v[148:151], v[214:217], v[12:15]
	v_mfma_f32_16x16x32_bf16 v[8:11], v[156:159], v[214:217], v[8:11]
	s_setprio 0
	s_setprio 1
	v_mfma_f32_16x16x32_bf16 v[52:55], v[160:163], v[184:187], v[52:55]
	v_mfma_f32_16x16x32_bf16 v[48:51], v[176:179], v[184:187], v[48:51]
	v_mfma_f32_16x16x32_bf16 v[36:39], v[160:163], v[192:195], v[36:39]
	v_mfma_f32_16x16x32_bf16 v[32:35], v[176:179], v[192:195], v[32:35]
	v_mfma_f32_16x16x32_bf16 v[20:23], v[160:163], v[202:205], v[20:23]
	v_mfma_f32_16x16x32_bf16 v[16:19], v[176:179], v[202:205], v[16:19]
	v_mfma_f32_16x16x32_bf16 v[4:7], v[160:163], v[210:213], v[4:7]
	v_mfma_f32_16x16x32_bf16 v[0:3], v[176:179], v[210:213], v[0:3]
	v_mfma_f32_16x16x32_bf16 v[52:55], v[172:175], v[188:191], v[52:55]
	v_mfma_f32_16x16x32_bf16 v[48:51], v[180:183], v[188:191], v[48:51]
	v_mfma_f32_16x16x32_bf16 v[36:39], v[172:175], v[196:199], v[36:39]
	v_mfma_f32_16x16x32_bf16 v[32:35], v[180:183], v[196:199], v[32:35]
	v_mfma_f32_16x16x32_bf16 v[20:23], v[172:175], v[206:209], v[20:23]
	v_mfma_f32_16x16x32_bf16 v[16:19], v[180:183], v[206:209], v[16:19]
	v_mfma_f32_16x16x32_bf16 v[4:7], v[172:175], v[214:217], v[4:7]
	v_mfma_f32_16x16x32_bf16 v[0:3], v[180:183], v[214:217], v[0:3]
	s_setprio 0
	s_barrier
	s_add_u32 s6, s6, 0x100
	s_addc_u32 s7, s7, 0
	s_add_u32 s79, s79, 0x100
	s_addc_u32 s80, s80, 0
	s_cmp_ge_i32 s81, s68
	s_mov_b32 s52, s81
	s_cbranch_scc0 .LBB0_728

; #define PG8_STAGE(bufoff, gbase, voff) do { _Pragma("unroll") for (int _i = 0; _i < 2; ++_i) \
;         __builtin_amdgcn_global_load_lds((const unsigned*)((const char*)(gbase) + (voff)[_i]), (PG8_LAS unsigned*)(lds + (bufoff) + ldsw + _i * 8192), 16, 0, 0); } while (0)
; #define PG8_LDA(dst, b, h) do { _Pragma("unroll") for (int m = 0; m < 4; ++m) _Pragma("unroll") for (int k = 0; k < 2; ++k) dst[m][k] = *(const PG8_LAS bf16x8*)(lds + PG8_SA(b, h) + aoff + m * 2048 + k * 1024); } while (0)
; #define PG8_LDB(dst, b, h) do { _Pragma("unroll") for (int n = 0; n < 2; ++n) _Pragma("unroll") for (int k = 0; k < 2; ++k) dst[n][k] = *(const PG8_LAS bf16x8*)(lds + PG8_SB(b, h) + boff + n * 2048 + k * 1024); } while (0)
; #define PG8_MMA(ai, bj, At, Bt) do { __builtin_amdgcn_s_setprio(1); _Pragma("unroll") for (int m = 0; m < 4; ++m) _Pragma("unroll") for (int n = 0; n < 2; ++n) _Pragma("unroll") for (int k = 0; k < 2; ++k) \
;         acc[ai][bj][m][n] = __builtin_amdgcn_mfma_f32_16x16x32_bf16(Bt[n][k], At[m][k], acc[ai][bj][m][n], 0, 0, 0); __builtin_amdgcn_s_setprio(0); } while (0)
; #define PG8_WAIT_V(n) asm volatile("s_waitcnt vmcnt(" #n ")" ::: "memory")
; #define PG8_BAR __builtin_amdgcn_s_barrier()
; template <class Epi, class Sched, bool ALIGN_EPI = false, bool SP2 = false>
; __device__ __forceinline__ void gemm_phase(PG8_LAS unsigned char* lds, const Gemm g, const Sched& S, const Epi& E) {
;     ...
;         for (int t = 0; t < nt; t += 2) {
;             const bool last = (t == nt - 2);
;             const char* a1 = cA + (size_t)(t + 1) * kstep;
;             const char* a2 = last ? nA : cA + (size_t)(t + 2) * kstep; const char* b2 = last ? nB : cB + (size_t)(t + 2) * kstep;
;             const char* a3 = a2 + kstep; const char* b3 = b2 + kstep;
;             if (last && has_next) S.a_ready(nxt);
;             if constexpr (SP2) {
;             PG8_LDB(B0, 0, 0); PG8_LDB(B1, 0, 1); PG8_SCHED; PG8_LDA(At, 0, 0); PG8_STAGE(PG8_SA(1, 1), a1 + hstep, voffA);
;             PG8_WAIT_V(8); PG8_WAIT_L(0); PG8_BAR; PG8_MMA(0, 0, At, B0); PG8_MMA(0, 1, At, B1); PG8_BAR; PG8_SCHED;
;     ...
; #pragma unroll
;         for (int a = 0; a < 2; ++a)
; #pragma unroll
;             for (int b = 0; b < 2; ++b)
; #pragma unroll
;                 for (int m = 0; m < 4; ++m)
; #pragma unroll
;                     for (int n = 0; n < 2; ++n) acc[a][b][m][n] = (f32x4){0.f, 0.f, 0.f, 0.f};
.LBB0_873:
	v_mov_b32_e32 v127, 0
	s_andn2_b64 vcc, exec, s[44:45]
	v_mov_b32_e32 v126, v127
	v_mov_b32_e32 v125, v127
	v_mov_b32_e32 v124, v127
	v_mov_b32_e32 v123, v127
	v_mov_b32_e32 v122, v127
	v_mov_b32_e32 v121, v127
	v_mov_b32_e32 v120, v127
	v_mov_b32_e32 v111, v127
	v_mov_b32_e32 v110, v127
	v_mov_b32_e32 v109, v127
	v_mov_b32_e32 v108, v127
	v_mov_b32_e32 v107, v127
	v_mov_b32_e32 v106, v127
	v_mov_b32_e32 v105, v127
	v_mov_b32_e32 v104, v127
	v_mov_b32_e32 v95, v127
	v_mov_b32_e32 v94, v127
	v_mov_b32_e32 v93, v127
	v_mov_b32_e32 v92, v127
	v_mov_b32_e32 v91, v127
	v_mov_b32_e32 v90, v127
	v_mov_b32_e32 v89, v127
	v_mov_b32_e32 v88, v127
	v_mov_b32_e32 v79, v127
	v_mov_b32_e32 v78, v127
	v_mov_b32_e32 v77, v127
	v_mov_b32_e32 v76, v127
	v_mov_b32_e32 v75, v127
	v_mov_b32_e32 v74, v127
	v_mov_b32_e32 v73, v127
	v_mov_b32_e32 v72, v127
	v_mov_b32_e32 v119, v127
	v_mov_b32_e32 v118, v127
	v_mov_b32_e32 v117, v127
	v_mov_b32_e32 v116, v127
	v_mov_b32_e32 v115, v127
	v_mov_b32_e32 v114, v127
	v_mov_b32_e32 v113, v127
	v_mov_b32_e32 v112, v127
	v_mov_b32_e32 v103, v127
	v_mov_b32_e32 v102, v127
	v_mov_b32_e32 v101, v127
	v_mov_b32_e32 v100, v127
	v_mov_b32_e32 v99, v127
	v_mov_b32_e32 v98, v127
	v_mov_b32_e32 v97, v127
	v_mov_b32_e32 v96, v127
	v_mov_b32_e32 v87, v127
	v_mov_b32_e32 v86, v127
	v_mov_b32_e32 v85, v127
	v_mov_b32_e32 v84, v127
	v_mov_b32_e32 v83, v127
	v_mov_b32_e32 v82, v127
	v_mov_b32_e32 v81, v127
	v_mov_b32_e32 v80, v127
	v_mov_b32_e32 v71, v127
	v_mov_b32_e32 v70, v127
	v_mov_b32_e32 v69, v127
	v_mov_b32_e32 v68, v127
	v_mov_b32_e32 v67, v127
	v_mov_b32_e32 v66, v127
	v_mov_b32_e32 v65, v127
	v_mov_b32_e32 v64, v127
	v_mov_b32_e32 v63, v127
	v_mov_b32_e32 v62, v127
	v_mov_b32_e32 v61, v127
	v_mov_b32_e32 v60, v127
	v_mov_b32_e32 v59, v127
	v_mov_b32_e32 v58, v127
	v_mov_b32_e32 v57, v127
	v_mov_b32_e32 v56, v127
	v_mov_b32_e32 v47, v127
	v_mov_b32_e32 v46, v127
	v_mov_b32_e32 v45, v127
	v_mov_b32_e32 v44, v127
	v_mov_b32_e32 v43, v127
	v_mov_b32_e32 v42, v127
	v_mov_b32_e32 v41, v127
	v_mov_b32_e32 v40, v127
	v_mov_b32_e32 v31, v127
	v_mov_b32_e32 v30, v127
	v_mov_b32_e32 v29, v127
	v_mov_b32_e32 v28, v127
	v_mov_b32_e32 v27, v127
	v_mov_b32_e32 v26, v127
	v_mov_b32_e32 v25, v127
	v_mov_b32_e32 v24, v127
	v_mov_b32_e32 v15, v127
	v_mov_b32_e32 v14, v127
	v_mov_b32_e32 v13, v127
	v_mov_b32_e32 v12, v127
	v_mov_b32_e32 v11, v127
	v_mov_b32_e32 v10, v127
	v_mov_b32_e32 v9, v127
	v_mov_b32_e32 v8, v127
	v_mov_b32_e32 v55, v127
	v_mov_b32_e32 v54, v127
	v_mov_b32_e32 v53, v127
	v_mov_b32_e32 v52, v127
	v_mov_b32_e32 v51, v127
	v_mov_b32_e32 v50, v127
	v_mov_b32_e32 v49, v127
	v_mov_b32_e32 v48, v127
	v_mov_b32_e32 v39, v127
	v_mov_b32_e32 v38, v127
	v_mov_b32_e32 v37, v127
	v_mov_b32_e32 v36, v127
	v_mov_b32_e32 v35, v127
	v_mov_b32_e32 v34, v127
	v_mov_b32_e32 v33, v127
	v_mov_b32_e32 v32, v127
	v_mov_b32_e32 v23, v127
	v_mov_b32_e32 v22, v127
	v_mov_b32_e32 v21, v127
	v_mov_b32_e32 v20, v127
	v_mov_b32_e32 v19, v127
	v_mov_b32_e32 v18, v127
	v_mov_b32_e32 v17, v127
	v_mov_b32_e32 v16, v127
	v_mov_b32_e32 v7, v127
	v_mov_b32_e32 v6, v127
	s_waitcnt lgkmcnt(0)
	v_mov_b32_e32 v5, v127
	v_mov_b32_e32 v4, v127
	v_mov_b32_e32 v3, v127
	v_mov_b32_e32 v2, v127
	v_mov_b32_e32 v1, v127
	v_mov_b32_e32 v0, v127
	s_cbranch_vccnz .LBB0_876
	s_add_u32 s50, s50, 0x80
	s_addc_u32 s51, s51, 0
	s_add_u32 s78, s52, 0x100
	s_addc_u32 s79, s53, 0
	s_mov_b32 s52, 0
	v_add_u32_e32 v218, s12, v130
	v_add_u32_e32 v219, s12, v134
	v_add_u32_e32 v220, s12, v128
	v_add_u32_e32 v221, s12, v132
	v_add_u32_e32 v222, 0x80, v130
	v_add_u32_e32 v223, 0x80, v134
	v_add_u32_e32 v224, 0x80, v218
	v_add_u32_e32 v225, 0x80, v219
	v_add_u32_e32 v226, 0x80, v128
	v_add_u32_e32 v227, 0x80, v132
.LBB0_875:
	ds_read_b128 v[144:147], v151
	ds_read_b128 v[156:159], v151 offset:1024
	ds_read_b128 v[160:163], v151 offset:2048
	ds_read_b128 v[164:167], v151 offset:3072
	ds_read_b128 v[168:171], v152
	ds_read_b128 v[172:175], v152 offset:1024
	ds_read_b128 v[176:179], v152 offset:2048
	ds_read_b128 v[180:183], v152 offset:3072
	s_add_i32 s80, s52, 2
	s_add_u32 s16, s50, 0x80
	s_addc_u32 s17, s51, 0
	s_cmp_eq_u32 s68, s52
	s_cselect_b32 s52, s0, s16
	s_cselect_b32 s53, s1, s17
	s_cselect_b32 s83, s49, s79
	s_cselect_b32 s82, s48, s78
	s_add_i32 m0, s56, 0xc000
	ds_read_b128 v[184:187], v153
	ds_read_b128 v[188:191], v153 offset:1024
	ds_read_b128 v[192:195], v153 offset:2048
	ds_read_b128 v[196:199], v153 offset:3072
	ds_read_b128 v[202:205], v153 offset:4096
	ds_read_b128 v[206:209], v153 offset:5120
	ds_read_b128 v[210:213], v153 offset:6144
	ds_read_b128 v[214:217], v153 offset:7168
	global_load_lds_dwordx4 v136, s[50:51]
	s_add_i32 m0, s56, 0xe000
	s_nop 0
	global_load_lds_dwordx4 v138, s[50:51]
	s_waitcnt vmcnt(8)
	s_waitcnt lgkmcnt(0)
	s_barrier
; #define PG8_STAGE(bufoff, gbase, voff) do { _Pragma("unroll") for (int _i = 0; _i < 2; ++_i) \
;         __builtin_amdgcn_global_load_lds((const unsigned*)((const char*)(gbase) + (voff)[_i]), (PG8_LAS unsigned*)(lds + (bufoff) + ldsw + _i * 8192), 16, 0, 0); } while (0)
; #define PG8_LDA(dst, b, h) do { _Pragma("unroll") for (int m = 0; m < 4; ++m) _Pragma("unroll") for (int k = 0; k < 2; ++k) dst[m][k] = *(const PG8_LAS bf16x8*)(lds + PG8_SA(b, h) + aoff + m * 2048 + k * 1024); } while (0)
; #define PG8_MMA(ai, bj, At, Bt) do { __builtin_amdgcn_s_setprio(1); _Pragma("unroll") for (int m = 0; m < 4; ++m) _Pragma("unroll") for (int n = 0; n < 2; ++n) _Pragma("unroll") for (int k = 0; k < 2; ++k) \
;         acc[ai][bj][m][n] = __builtin_amdgcn_mfma_f32_16x16x32_bf16(Bt[n][k], At[m][k], acc[ai][bj][m][n], 0, 0, 0); __builtin_amdgcn_s_setprio(0); } while (0)
; #define PG8_WAIT_V(n) asm volatile("s_waitcnt vmcnt(" #n ")" ::: "memory")
; #define PG8_WAIT_L(n) asm volatile("s_waitcnt lgkmcnt(" #n ")" ::: "memory")
; #define PG8_BAR __builtin_amdgcn_s_barrier()
; #define PG8_SCHED __builtin_amdgcn_sched_barrier(0)
; template <class Epi, class Sched, bool ALIGN_EPI = false, bool SP2 = false>
; __device__ __forceinline__ void gemm_phase(PG8_LAS unsigned char* lds, const Gemm g, const Sched& S, const Epi& E) {
;     ...
;             PG8_WAIT_V(8); PG8_WAIT_L(0); PG8_BAR; PG8_MMA(0, 0, At, B0); PG8_MMA(0, 1, At, B1); PG8_BAR; PG8_SCHED;
;             PG8_LDA(At, 0, 1); PG8_STAGE(PG8_SB(0, 0), b2, voffB); PG8_STAGE(PG8_SB(0, 1), b2 + hstep, voffB); PG8_STAGE(PG8_SA(0, 0), a2, voffA);
;             PG8_WAIT_V(8); PG8_WAIT_L(0); PG8_BAR; PG8_MMA(1, 0, At, B0); PG8_MMA(1, 1, At, B1); PG8_BAR; PG8_SCHED;
	s_setprio 1
	s_waitcnt lgkmcnt(0)
	v_mfma_f32_16x16x32_bf16 v[124:127], v[144:147], v[184:187], v[124:127]
	v_mfma_f32_16x16x32_bf16 v[120:123], v[160:163], v[184:187], v[120:123]
	v_mfma_f32_16x16x32_bf16 v[108:111], v[144:147], v[192:195], v[108:111]
	v_mfma_f32_16x16x32_bf16 v[104:107], v[160:163], v[192:195], v[104:107]
	v_mfma_f32_16x16x32_bf16 v[92:95], v[144:147], v[202:205], v[92:95]
	v_mfma_f32_16x16x32_bf16 v[88:91], v[160:163], v[202:205], v[88:91]
	v_mfma_f32_16x16x32_bf16 v[76:79], v[144:147], v[210:213], v[76:79]
	v_mfma_f32_16x16x32_bf16 v[72:75], v[160:163], v[210:213], v[72:75]
	v_mfma_f32_16x16x32_bf16 v[124:127], v[156:159], v[188:191], v[124:127]
	v_mfma_f32_16x16x32_bf16 v[120:123], v[164:167], v[188:191], v[120:123]
	v_mfma_f32_16x16x32_bf16 v[108:111], v[156:159], v[196:199], v[108:111]
	v_mfma_f32_16x16x32_bf16 v[104:107], v[164:167], v[196:199], v[104:107]
	v_mfma_f32_16x16x32_bf16 v[92:95], v[156:159], v[206:209], v[92:95]
	v_mfma_f32_16x16x32_bf16 v[88:91], v[164:167], v[206:209], v[88:91]
	v_mfma_f32_16x16x32_bf16 v[76:79], v[156:159], v[214:217], v[76:79]
	v_mfma_f32_16x16x32_bf16 v[72:75], v[164:167], v[214:217], v[72:75]
	s_setprio 0
	s_setprio 1
	v_mfma_f32_16x16x32_bf16 v[116:119], v[168:171], v[184:187], v[116:119]
	v_mfma_f32_16x16x32_bf16 v[112:115], v[176:179], v[184:187], v[112:115]
	v_mfma_f32_16x16x32_bf16 v[100:103], v[168:171], v[192:195], v[100:103]
	v_mfma_f32_16x16x32_bf16 v[96:99], v[176:179], v[192:195], v[96:99]
	v_mfma_f32_16x16x32_bf16 v[84:87], v[168:171], v[202:205], v[84:87]
	v_mfma_f32_16x16x32_bf16 v[80:83], v[176:179], v[202:205], v[80:83]
	v_mfma_f32_16x16x32_bf16 v[68:71], v[168:171], v[210:213], v[68:71]
	v_mfma_f32_16x16x32_bf16 v[64:67], v[176:179], v[210:213], v[64:67]
	v_mfma_f32_16x16x32_bf16 v[116:119], v[172:175], v[188:191], v[116:119]
	v_mfma_f32_16x16x32_bf16 v[112:115], v[180:183], v[188:191], v[112:115]
	v_mfma_f32_16x16x32_bf16 v[100:103], v[172:175], v[196:199], v[100:103]
	v_mfma_f32_16x16x32_bf16 v[96:99], v[180:183], v[196:199], v[96:99]
	v_mfma_f32_16x16x32_bf16 v[84:87], v[172:175], v[206:209], v[84:87]
	v_mfma_f32_16x16x32_bf16 v[80:83], v[180:183], v[206:209], v[80:83]
	v_mfma_f32_16x16x32_bf16 v[68:71], v[172:175], v[214:217], v[68:71]
	v_mfma_f32_16x16x32_bf16 v[64:67], v[180:183], v[214:217], v[64:67]
	s_setprio 0
	s_barrier
	s_add_i32 s16, s72, s55
	s_mov_b32 m0, s16
	ds_read_b128 v[184:187], v153 offset:16384
	ds_read_b128 v[188:191], v153 offset:17408
	ds_read_b128 v[192:195], v153 offset:18432
	ds_read_b128 v[196:199], v153 offset:19456
	ds_read_b128 v[202:205], v153 offset:20480
	ds_read_b128 v[206:209], v153 offset:21504
	ds_read_b128 v[210:213], v153 offset:22528
	ds_read_b128 v[214:217], v153 offset:23552
	global_load_lds_dwordx4 v130, s[82:83]
	s_add_i32 m0, s16, 0x2000
	s_add_i32 s16, s73, s55
	global_load_lds_dwordx4 v134, s[82:83]
	s_mov_b32 m0, s16
	s_nop 0
	global_load_lds_dwordx4 v218, s[82:83]
	s_add_i32 m0, s16, 0x2000
	s_nop 0
	global_load_lds_dwordx4 v219, s[82:83]
	s_mov_b32 m0, s56
	s_nop 0
	global_load_lds_dwordx4 v128, s[52:53]
	s_mov_b32 m0, s57
	s_nop 0
	global_load_lds_dwordx4 v132, s[52:53]
	s_waitcnt vmcnt(8)
	s_waitcnt lgkmcnt(0)
	s_barrier
	s_setprio 1
	s_waitcnt lgkmcnt(0)
	v_mfma_f32_16x16x32_bf16 v[60:63], v[144:147], v[184:187], v[60:63]
	v_mfma_f32_16x16x32_bf16 v[56:59], v[160:163], v[184:187], v[56:59]
	v_mfma_f32_16x16x32_bf16 v[44:47], v[144:147], v[192:195], v[44:47]
	v_mfma_f32_16x16x32_bf16 v[40:43], v[160:163], v[192:195], v[40:43]
	v_mfma_f32_16x16x32_bf16 v[28:31], v[144:147], v[202:205], v[28:31]
	v_mfma_f32_16x16x32_bf16 v[24:27], v[160:163], v[202:205], v[24:27]
	v_mfma_f32_16x16x32_bf16 v[12:15], v[144:147], v[210:213], v[12:15]
	v_mfma_f32_16x16x32_bf16 v[8:11], v[160:163], v[210:213], v[8:11]
	v_mfma_f32_16x16x32_bf16 v[60:63], v[156:159], v[188:191], v[60:63]
	v_mfma_f32_16x16x32_bf16 v[56:59], v[164:167], v[188:191], v[56:59]
	v_mfma_f32_16x16x32_bf16 v[44:47], v[156:159], v[196:199], v[44:47]
	v_mfma_f32_16x16x32_bf16 v[40:43], v[164:167], v[196:199], v[40:43]
	v_mfma_f32_16x16x32_bf16 v[28:31], v[156:159], v[206:209], v[28:31]
	v_mfma_f32_16x16x32_bf16 v[24:27], v[164:167], v[206:209], v[24:27]
	v_mfma_f32_16x16x32_bf16 v[12:15], v[156:159], v[214:217], v[12:15]
	v_mfma_f32_16x16x32_bf16 v[8:11], v[164:167], v[214:217], v[8:11]
	s_setprio 0
	s_setprio 1
	v_mfma_f32_16x16x32_bf16 v[52:55], v[168:171], v[184:187], v[52:55]
	v_mfma_f32_16x16x32_bf16 v[48:51], v[176:179], v[184:187], v[48:51]
	v_mfma_f32_16x16x32_bf16 v[36:39], v[168:171], v[192:195], v[36:39]
	v_mfma_f32_16x16x32_bf16 v[32:35], v[176:179], v[192:195], v[32:35]
	v_mfma_f32_16x16x32_bf16 v[20:23], v[168:171], v[202:205], v[20:23]
	v_mfma_f32_16x16x32_bf16 v[16:19], v[176:179], v[202:205], v[16:19]
	v_mfma_f32_16x16x32_bf16 v[4:7], v[168:171], v[210:213], v[4:7]
	v_mfma_f32_16x16x32_bf16 v[0:3], v[176:179], v[210:213], v[0:3]
	v_mfma_f32_16x16x32_bf16 v[52:55], v[172:175], v[188:191], v[52:55]
	v_mfma_f32_16x16x32_bf16 v[48:51], v[180:183], v[188:191], v[48:51]
	v_mfma_f32_16x16x32_bf16 v[36:39], v[172:175], v[196:199], v[36:39]
	v_mfma_f32_16x16x32_bf16 v[32:35], v[180:183], v[196:199], v[32:35]
	v_mfma_f32_16x16x32_bf16 v[20:23], v[172:175], v[206:209], v[20:23]
	v_mfma_f32_16x16x32_bf16 v[16:19], v[180:183], v[206:209], v[16:19]
	v_mfma_f32_16x16x32_bf16 v[4:7], v[172:175], v[214:217], v[4:7]
	v_mfma_f32_16x16x32_bf16 v[0:3], v[180:183], v[214:217], v[0:3]
	s_setprio 0
	s_barrier
; #define PG8_STAGE(bufoff, gbase, voff) do { _Pragma("unroll") for (int _i = 0; _i < 2; ++_i) \
;         __builtin_amdgcn_global_load_lds((const unsigned*)((const char*)(gbase) + (voff)[_i]), (PG8_LAS unsigned*)(lds + (bufoff) + ldsw + _i * 8192), 16, 0, 0); } while (0)
; #define PG8_LDA(dst, b, h) do { _Pragma("unroll") for (int m = 0; m < 4; ++m) _Pragma("unroll") for (int k = 0; k < 2; ++k) dst[m][k] = *(const PG8_LAS bf16x8*)(lds + PG8_SA(b, h) + aoff + m * 2048 + k * 1024); } while (0)
; #define PG8_LDB(dst, b, h) do { _Pragma("unroll") for (int n = 0; n < 2; ++n) _Pragma("unroll") for (int k = 0; k < 2; ++k) dst[n][k] = *(const PG8_LAS bf16x8*)(lds + PG8_SB(b, h) + boff + n * 2048 + k * 1024); } while (0)
; #define PG8_MMA(ai, bj, At, Bt) do { __builtin_amdgcn_s_setprio(1); _Pragma("unroll") for (int m = 0; m < 4; ++m) _Pragma("unroll") for (int n = 0; n < 2; ++n) _Pragma("unroll") for (int k = 0; k < 2; ++k) \
;         acc[ai][bj][m][n] = __builtin_amdgcn_mfma_f32_16x16x32_bf16(Bt[n][k], At[m][k], acc[ai][bj][m][n], 0, 0, 0); __builtin_amdgcn_s_setprio(0); } while (0)
; #define PG8_WAIT_V(n) asm volatile("s_waitcnt vmcnt(" #n ")" ::: "memory")
; #define PG8_WAIT_L(n) asm volatile("s_waitcnt lgkmcnt(" #n ")" ::: "memory")
; #define PG8_BAR __builtin_amdgcn_s_barrier()
; #define PG8_SCHED __builtin_amdgcn_sched_barrier(0)
; template <class Epi, class Sched, bool ALIGN_EPI = false, bool SP2 = false>
; __device__ __forceinline__ void gemm_phase(PG8_LAS unsigned char* lds, const Gemm g, const Sched& S, const Epi& E) {
;     ...
;             PG8_LDB(B0, 1, 0); PG8_LDB(B1, 1, 1); PG8_SCHED; PG8_LDA(At, 1, 0); PG8_STAGE(PG8_SA(0, 1), a2 + hstep, voffA);
;             PG8_WAIT_V(8); PG8_WAIT_L(0); PG8_BAR; PG8_MMA(0, 0, At, B0); PG8_MMA(0, 1, At, B1); PG8_BAR; PG8_SCHED;
;             PG8_LDA(At, 1, 1); PG8_STAGE(PG8_SB(1, 0), b3, voffB); PG8_STAGE(PG8_SB(1, 1), b3 + hstep, voffB); PG8_STAGE(PG8_SA(1, 0), a3, voffA);
;             PG8_WAIT_V(8); PG8_WAIT_L(0); PG8_BAR; PG8_MMA(1, 0, At, B0); PG8_MMA(1, 1, At, B1); PG8_BAR; PG8_SCHED;
	s_add_i32 s16, 0, 0x18000
	v_add_u32_e32 v155, s16, v149
	s_add_i32 s17, 0, 0x1c000
	ds_read_b128 v[144:147], v155
	ds_read_b128 v[156:159], v155 offset:1024
	ds_read_b128 v[160:163], v155 offset:2048
	ds_read_b128 v[164:167], v155 offset:3072
	v_add_u32_e32 v155, s17, v149
	ds_read_b128 v[168:171], v155
	ds_read_b128 v[172:175], v155 offset:1024
	ds_read_b128 v[176:179], v155 offset:2048
	ds_read_b128 v[180:183], v155 offset:3072
	s_mov_b32 m0, s58
	ds_read_b128 v[184:187], v153 offset:32768
	ds_read_b128 v[188:191], v153 offset:33792
	ds_read_b128 v[192:195], v153 offset:34816
	ds_read_b128 v[196:199], v153 offset:35840
	ds_read_b128 v[202:205], v153 offset:36864
	ds_read_b128 v[206:209], v153 offset:37888
	ds_read_b128 v[210:213], v153 offset:38912
	ds_read_b128 v[214:217], v153 offset:39936
	global_load_lds_dwordx4 v220, s[52:53]
	s_mov_b32 m0, s59
	s_nop 0
	global_load_lds_dwordx4 v221, s[52:53]
	s_waitcnt vmcnt(8)
	s_waitcnt lgkmcnt(0)
	s_barrier
	s_setprio 1
	s_waitcnt lgkmcnt(0)
	v_mfma_f32_16x16x32_bf16 v[124:127], v[144:147], v[184:187], v[124:127]
	v_mfma_f32_16x16x32_bf16 v[120:123], v[160:163], v[184:187], v[120:123]
	v_mfma_f32_16x16x32_bf16 v[108:111], v[144:147], v[192:195], v[108:111]
	v_mfma_f32_16x16x32_bf16 v[104:107], v[160:163], v[192:195], v[104:107]
	v_mfma_f32_16x16x32_bf16 v[92:95], v[144:147], v[202:205], v[92:95]
	v_mfma_f32_16x16x32_bf16 v[88:91], v[160:163], v[202:205], v[88:91]
	v_mfma_f32_16x16x32_bf16 v[76:79], v[144:147], v[210:213], v[76:79]
	v_mfma_f32_16x16x32_bf16 v[72:75], v[160:163], v[210:213], v[72:75]
	v_mfma_f32_16x16x32_bf16 v[124:127], v[156:159], v[188:191], v[124:127]
	v_mfma_f32_16x16x32_bf16 v[120:123], v[164:167], v[188:191], v[120:123]
	v_mfma_f32_16x16x32_bf16 v[108:111], v[156:159], v[196:199], v[108:111]
	v_mfma_f32_16x16x32_bf16 v[104:107], v[164:167], v[196:199], v[104:107]
	v_mfma_f32_16x16x32_bf16 v[92:95], v[156:159], v[206:209], v[92:95]
	v_mfma_f32_16x16x32_bf16 v[88:91], v[164:167], v[206:209], v[88:91]
	v_mfma_f32_16x16x32_bf16 v[76:79], v[156:159], v[214:217], v[76:79]
	v_mfma_f32_16x16x32_bf16 v[72:75], v[164:167], v[214:217], v[72:75]
	s_setprio 0
	s_setprio 1
	v_mfma_f32_16x16x32_bf16 v[116:119], v[168:171], v[184:187], v[116:119]
	v_mfma_f32_16x16x32_bf16 v[112:115], v[176:179], v[184:187], v[112:115]
	v_mfma_f32_16x16x32_bf16 v[100:103], v[168:171], v[192:195], v[100:103]
	v_mfma_f32_16x16x32_bf16 v[96:99], v[176:179], v[192:195], v[96:99]
	v_mfma_f32_16x16x32_bf16 v[84:87], v[168:171], v[202:205], v[84:87]
	v_mfma_f32_16x16x32_bf16 v[80:83], v[176:179], v[202:205], v[80:83]
	v_mfma_f32_16x16x32_bf16 v[68:71], v[168:171], v[210:213], v[68:71]
	v_mfma_f32_16x16x32_bf16 v[64:67], v[176:179], v[210:213], v[64:67]
	v_mfma_f32_16x16x32_bf16 v[116:119], v[172:175], v[188:191], v[116:119]
	v_mfma_f32_16x16x32_bf16 v[112:115], v[180:183], v[188:191], v[112:115]
	v_mfma_f32_16x16x32_bf16 v[100:103], v[172:175], v[196:199], v[100:103]
	v_mfma_f32_16x16x32_bf16 v[96:99], v[180:183], v[196:199], v[96:99]
	v_mfma_f32_16x16x32_bf16 v[84:87], v[172:175], v[206:209], v[84:87]
	v_mfma_f32_16x16x32_bf16 v[80:83], v[180:183], v[206:209], v[80:83]
	v_mfma_f32_16x16x32_bf16 v[68:71], v[172:175], v[214:217], v[68:71]
	v_mfma_f32_16x16x32_bf16 v[64:67], v[180:183], v[214:217], v[64:67]
	s_setprio 0
	s_barrier
	s_add_i32 s16, s16, s55
	s_mov_b32 m0, s16
	ds_read_b128 v[184:187], v153 offset:49152
	ds_read_b128 v[188:191], v153 offset:50176
	ds_read_b128 v[192:195], v153 offset:51200
	ds_read_b128 v[196:199], v153 offset:52224
	ds_read_b128 v[202:205], v153 offset:53248
	ds_read_b128 v[206:209], v153 offset:54272
	ds_read_b128 v[210:213], v153 offset:55296
	ds_read_b128 v[214:217], v153 offset:56320
	global_load_lds_dwordx4 v222, s[82:83]
	s_add_i32 m0, s16, 0x2000
	s_add_i32 s16, s17, s55
	global_load_lds_dwordx4 v223, s[82:83]
	s_mov_b32 m0, s16
	s_nop 0
	global_load_lds_dwordx4 v224, s[82:83]
	s_add_i32 m0, s16, 0x2000
	s_nop 0
	global_load_lds_dwordx4 v225, s[82:83]
	s_mov_b32 m0, s60
	s_nop 0
	global_load_lds_dwordx4 v226, s[52:53]
	s_mov_b32 m0, s61
	s_nop 0
	global_load_lds_dwordx4 v227, s[52:53]
	s_waitcnt vmcnt(8)
	s_waitcnt lgkmcnt(0)
	s_barrier
	s_setprio 1
	s_waitcnt lgkmcnt(0)
	v_mfma_f32_16x16x32_bf16 v[60:63], v[144:147], v[184:187], v[60:63]
	v_mfma_f32_16x16x32_bf16 v[56:59], v[160:163], v[184:187], v[56:59]
	v_mfma_f32_16x16x32_bf16 v[44:47], v[144:147], v[192:195], v[44:47]
	v_mfma_f32_16x16x32_bf16 v[40:43], v[160:163], v[192:195], v[40:43]
	v_mfma_f32_16x16x32_bf16 v[28:31], v[144:147], v[202:205], v[28:31]
	v_mfma_f32_16x16x32_bf16 v[24:27], v[160:163], v[202:205], v[24:27]
	v_mfma_f32_16x16x32_bf16 v[12:15], v[144:147], v[210:213], v[12:15]
	v_mfma_f32_16x16x32_bf16 v[8:11], v[160:163], v[210:213], v[8:11]
	v_mfma_f32_16x16x32_bf16 v[60:63], v[156:159], v[188:191], v[60:63]
	v_mfma_f32_16x16x32_bf16 v[56:59], v[164:167], v[188:191], v[56:59]
	v_mfma_f32_16x16x32_bf16 v[44:47], v[156:159], v[196:199], v[44:47]
	v_mfma_f32_16x16x32_bf16 v[40:43], v[164:167], v[196:199], v[40:43]
	v_mfma_f32_16x16x32_bf16 v[28:31], v[156:159], v[206:209], v[28:31]
	v_mfma_f32_16x16x32_bf16 v[24:27], v[164:167], v[206:209], v[24:27]
	v_mfma_f32_16x16x32_bf16 v[12:15], v[156:159], v[214:217], v[12:15]
	v_mfma_f32_16x16x32_bf16 v[8:11], v[164:167], v[214:217], v[8:11]
	s_setprio 0
	s_setprio 1
	v_mfma_f32_16x16x32_bf16 v[52:55], v[168:171], v[184:187], v[52:55]
	v_mfma_f32_16x16x32_bf16 v[48:51], v[176:179], v[184:187], v[48:51]
	v_mfma_f32_16x16x32_bf16 v[36:39], v[168:171], v[192:195], v[36:39]
	v_mfma_f32_16x16x32_bf16 v[32:35], v[176:179], v[192:195], v[32:35]
	v_mfma_f32_16x16x32_bf16 v[20:23], v[168:171], v[202:205], v[20:23]
	v_mfma_f32_16x16x32_bf16 v[16:19], v[176:179], v[202:205], v[16:19]
	v_mfma_f32_16x16x32_bf16 v[4:7], v[168:171], v[210:213], v[4:7]
	v_mfma_f32_16x16x32_bf16 v[0:3], v[176:179], v[210:213], v[0:3]
	v_mfma_f32_16x16x32_bf16 v[52:55], v[172:175], v[188:191], v[52:55]
	v_mfma_f32_16x16x32_bf16 v[48:51], v[180:183], v[188:191], v[48:51]
	v_mfma_f32_16x16x32_bf16 v[36:39], v[172:175], v[196:199], v[36:39]
	v_mfma_f32_16x16x32_bf16 v[32:35], v[180:183], v[196:199], v[32:35]
	v_mfma_f32_16x16x32_bf16 v[20:23], v[172:175], v[206:209], v[20:23]
	v_mfma_f32_16x16x32_bf16 v[16:19], v[180:183], v[206:209], v[16:19]
	v_mfma_f32_16x16x32_bf16 v[4:7], v[172:175], v[214:217], v[4:7]
	v_mfma_f32_16x16x32_bf16 v[0:3], v[180:183], v[214:217], v[0:3]
	s_setprio 0
	s_barrier
	s_add_u32 s50, s50, 0x100
	s_addc_u32 s51, s51, 0
	s_add_u32 s78, s78, 0x100
	s_addc_u32 s79, s79, 0
	s_cmp_ge_i32 s80, s63
	s_mov_b32 s52, s80
	s_cbranch_scc0 .LBB0_875

; #define PG8_STAGE(bufoff, gbase, voff) do { _Pragma("unroll") for (int _i = 0; _i < 2; ++_i) \
;         __builtin_amdgcn_global_load_lds((const unsigned*)((const char*)(gbase) + (voff)[_i]), (PG8_LAS unsigned*)(lds + (bufoff) + ldsw + _i * 8192), 16, 0, 0); } while (0)
; #define PG8_LDA(dst, b, h) do { _Pragma("unroll") for (int m = 0; m < 4; ++m) _Pragma("unroll") for (int k = 0; k < 2; ++k) dst[m][k] = *(const PG8_LAS bf16x8*)(lds + PG8_SA(b, h) + aoff + m * 2048 + k * 1024); } while (0)
; #define PG8_LDB(dst, b, h) do { _Pragma("unroll") for (int n = 0; n < 2; ++n) _Pragma("unroll") for (int k = 0; k < 2; ++k) dst[n][k] = *(const PG8_LAS bf16x8*)(lds + PG8_SB(b, h) + boff + n * 2048 + k * 1024); } while (0)
; #define PG8_MMA(ai, bj, At, Bt) do { __builtin_amdgcn_s_setprio(1); _Pragma("unroll") for (int m = 0; m < 4; ++m) _Pragma("unroll") for (int n = 0; n < 2; ++n) _Pragma("unroll") for (int k = 0; k < 2; ++k) \
;         acc[ai][bj][m][n] = __builtin_amdgcn_mfma_f32_16x16x32_bf16(Bt[n][k], At[m][k], acc[ai][bj][m][n], 0, 0, 0); __builtin_amdgcn_s_setprio(0); } while (0)
; #define PG8_WAIT_V(n) asm volatile("s_waitcnt vmcnt(" #n ")" ::: "memory")
; #define PG8_BAR __builtin_amdgcn_s_barrier()
; template <class Epi, class Sched, bool ALIGN_EPI = false, bool SP2 = false>
; __device__ __forceinline__ void gemm_phase(PG8_LAS unsigned char* lds, const Gemm g, const Sched& S, const Epi& E) {
;     ...
;         for (int t = 0; t < nt; t += 2) {
;             const bool last = (t == nt - 2);
;             const char* a1 = cA + (size_t)(t + 1) * kstep;
;             const char* a2 = last ? nA : cA + (size_t)(t + 2) * kstep; const char* b2 = last ? nB : cB + (size_t)(t + 2) * kstep;
;             const char* a3 = a2 + kstep; const char* b3 = b2 + kstep;
;             if (last && has_next) S.a_ready(nxt);
;             if constexpr (SP2) {
;             PG8_LDB(B0, 0, 0); PG8_LDB(B1, 0, 1); PG8_SCHED; PG8_LDA(At, 0, 0); PG8_STAGE(PG8_SA(1, 1), a1 + hstep, voffA);
;             PG8_WAIT_V(8); PG8_WAIT_L(0); PG8_BAR; PG8_MMA(0, 0, At, B0); PG8_MMA(0, 1, At, B1); PG8_BAR; PG8_SCHED;
;     ...
; #pragma unroll
;         for (int a = 0; a < 2; ++a)
; #pragma unroll
;             for (int b = 0; b < 2; ++b)
; #pragma unroll
;                 for (int m = 0; m < 4; ++m)
; #pragma unroll
;                     for (int n = 0; n < 2; ++n) acc[a][b][m][n] = (f32x4){0.f, 0.f, 0.f, 0.f};
.LBB0_1019:
	v_mov_b32_e32 v127, 0
	s_and_b64 vcc, exec, s[4:5]
	v_mov_b32_e32 v126, v127
	v_mov_b32_e32 v125, v127
	v_mov_b32_e32 v124, v127
	v_mov_b32_e32 v119, v127
	v_mov_b32_e32 v118, v127
	v_mov_b32_e32 v117, v127
	v_mov_b32_e32 v116, v127
	v_mov_b32_e32 v111, v127
	v_mov_b32_e32 v110, v127
	v_mov_b32_e32 v109, v127
	v_mov_b32_e32 v108, v127
	v_mov_b32_e32 v103, v127
	v_mov_b32_e32 v102, v127
	v_mov_b32_e32 v101, v127
	v_mov_b32_e32 v100, v127
	v_mov_b32_e32 v95, v127
	v_mov_b32_e32 v94, v127
	v_mov_b32_e32 v93, v127
	v_mov_b32_e32 v92, v127
	v_mov_b32_e32 v87, v127
	v_mov_b32_e32 v86, v127
	v_mov_b32_e32 v85, v127
	v_mov_b32_e32 v84, v127
	v_mov_b32_e32 v79, v127
	v_mov_b32_e32 v78, v127
	v_mov_b32_e32 v77, v127
	v_mov_b32_e32 v76, v127
	v_mov_b32_e32 v71, v127
	v_mov_b32_e32 v70, v127
	v_mov_b32_e32 v69, v127
	v_mov_b32_e32 v68, v127
	v_mov_b32_e32 v123, v127
	v_mov_b32_e32 v122, v127
	v_mov_b32_e32 v121, v127
	v_mov_b32_e32 v120, v127
	v_mov_b32_e32 v115, v127
	v_mov_b32_e32 v114, v127
	v_mov_b32_e32 v113, v127
	v_mov_b32_e32 v112, v127
	v_mov_b32_e32 v107, v127
	v_mov_b32_e32 v106, v127
	v_mov_b32_e32 v105, v127
	v_mov_b32_e32 v104, v127
	v_mov_b32_e32 v99, v127
	v_mov_b32_e32 v98, v127
	v_mov_b32_e32 v97, v127
	v_mov_b32_e32 v96, v127
	v_mov_b32_e32 v91, v127
	v_mov_b32_e32 v90, v127
	v_mov_b32_e32 v89, v127
	v_mov_b32_e32 v88, v127
	v_mov_b32_e32 v83, v127
	v_mov_b32_e32 v82, v127
	v_mov_b32_e32 v81, v127
	v_mov_b32_e32 v80, v127
	v_mov_b32_e32 v75, v127
	v_mov_b32_e32 v74, v127
	v_mov_b32_e32 v73, v127
	v_mov_b32_e32 v72, v127
	v_mov_b32_e32 v67, v127
	v_mov_b32_e32 v66, v127
	v_mov_b32_e32 v65, v127
	v_mov_b32_e32 v64, v127
	v_mov_b32_e32 v63, v127
	v_mov_b32_e32 v62, v127
	v_mov_b32_e32 v61, v127
	v_mov_b32_e32 v60, v127
	v_mov_b32_e32 v55, v127
	v_mov_b32_e32 v54, v127
	v_mov_b32_e32 v53, v127
	v_mov_b32_e32 v52, v127
	v_mov_b32_e32 v47, v127
	v_mov_b32_e32 v46, v127
	v_mov_b32_e32 v45, v127
	v_mov_b32_e32 v44, v127
	v_mov_b32_e32 v39, v127
	v_mov_b32_e32 v38, v127
	v_mov_b32_e32 v37, v127
	v_mov_b32_e32 v36, v127
	v_mov_b32_e32 v31, v127
	v_mov_b32_e32 v30, v127
	v_mov_b32_e32 v29, v127
	v_mov_b32_e32 v28, v127
	v_mov_b32_e32 v23, v127
	v_mov_b32_e32 v22, v127
	v_mov_b32_e32 v21, v127
	v_mov_b32_e32 v20, v127
	v_mov_b32_e32 v15, v127
	v_mov_b32_e32 v14, v127
	v_mov_b32_e32 v13, v127
	v_mov_b32_e32 v12, v127
	v_mov_b32_e32 v7, v127
	v_mov_b32_e32 v6, v127
	v_mov_b32_e32 v5, v127
	v_mov_b32_e32 v4, v127
	v_mov_b32_e32 v59, v127
	v_mov_b32_e32 v58, v127
	v_mov_b32_e32 v57, v127
	v_mov_b32_e32 v56, v127
	v_mov_b32_e32 v51, v127
	v_mov_b32_e32 v50, v127
	v_mov_b32_e32 v49, v127
	v_mov_b32_e32 v48, v127
	v_mov_b32_e32 v43, v127
	v_mov_b32_e32 v42, v127
	v_mov_b32_e32 v41, v127
	v_mov_b32_e32 v40, v127
	v_mov_b32_e32 v35, v127
	v_mov_b32_e32 v34, v127
	v_mov_b32_e32 v33, v127
	v_mov_b32_e32 v32, v127
	v_mov_b32_e32 v27, v127
	v_mov_b32_e32 v26, v127
	v_mov_b32_e32 v25, v127
	v_mov_b32_e32 v24, v127
	v_mov_b32_e32 v19, v127
	v_mov_b32_e32 v18, v127
	v_mov_b32_e32 v17, v127
	v_mov_b32_e32 v16, v127
	v_mov_b32_e32 v11, v127
	v_mov_b32_e32 v10, v127
	v_mov_b32_e32 v9, v127
	v_mov_b32_e32 v8, v127
	v_mov_b32_e32 v3, v127
	v_mov_b32_e32 v2, v127
	v_mov_b32_e32 v1, v127
	v_mov_b32_e32 v0, v127
	s_cbranch_vccnz .LBB0_1022
	s_add_u32 s42, s42, 0x80
	s_addc_u32 s43, s43, 0
	s_add_u32 s68, s44, 0x100
	s_addc_u32 s69, s45, 0
	s_mov_b32 s44, 0
	v_add_u32_e32 v198, s10, v132
	v_add_u32_e32 v199, s10, v128
	v_add_u32_e32 v218, s10, v134
	v_add_u32_e32 v219, s10, v130
	v_add_u32_e32 v220, 0x80, v132
	v_add_u32_e32 v221, 0x80, v128
	v_add_u32_e32 v222, 0x80, v198
	v_add_u32_e32 v223, 0x80, v199
	v_add_u32_e32 v224, 0x80, v134
	v_add_u32_e32 v225, 0x80, v130
.LBB0_1021:
	ds_read_b128 v[150:153], v147
	ds_read_b128 v[154:157], v147 offset:1024
	ds_read_b128 v[158:161], v147 offset:2048
	ds_read_b128 v[162:165], v147 offset:3072
	ds_read_b128 v[166:169], v148
	ds_read_b128 v[170:173], v148 offset:1024
	ds_read_b128 v[174:177], v148 offset:2048
	ds_read_b128 v[178:181], v148 offset:3072
	s_add_i32 s70, s44, 2
	s_add_u32 s16, s42, 0x80
	s_addc_u32 s17, s43, 0
	s_cmp_eq_u32 s58, s44
	s_cselect_b32 s44, s0, s16
	s_cselect_b32 s45, s1, s17
	s_cselect_b32 s73, s41, s69
	s_cselect_b32 s72, s40, s68
	s_add_i32 m0, s50, 0xc000
	ds_read_b128 v[182:185], v149
	ds_read_b128 v[186:189], v149 offset:1024
	ds_read_b128 v[190:193], v149 offset:2048
	ds_read_b128 v[194:197], v149 offset:3072
	ds_read_b128 v[202:205], v149 offset:4096
	ds_read_b128 v[206:209], v149 offset:5120
	ds_read_b128 v[210:213], v149 offset:6144
	ds_read_b128 v[214:217], v149 offset:7168
	global_load_lds_dwordx4 v136, s[42:43]
	s_add_i32 m0, s50, 0xe000
	s_nop 0
	global_load_lds_dwordx4 v138, s[42:43]
	s_waitcnt vmcnt(8)
	s_waitcnt lgkmcnt(0)
	s_barrier
; #define PG8_STAGE(bufoff, gbase, voff) do { _Pragma("unroll") for (int _i = 0; _i < 2; ++_i) \
;         __builtin_amdgcn_global_load_lds((const unsigned*)((const char*)(gbase) + (voff)[_i]), (PG8_LAS unsigned*)(lds + (bufoff) + ldsw + _i * 8192), 16, 0, 0); } while (0)
; #define PG8_LDA(dst, b, h) do { _Pragma("unroll") for (int m = 0; m < 4; ++m) _Pragma("unroll") for (int k = 0; k < 2; ++k) dst[m][k] = *(const PG8_LAS bf16x8*)(lds + PG8_SA(b, h) + aoff + m * 2048 + k * 1024); } while (0)
; #define PG8_MMA(ai, bj, At, Bt) do { __builtin_amdgcn_s_setprio(1); _Pragma("unroll") for (int m = 0; m < 4; ++m) _Pragma("unroll") for (int n = 0; n < 2; ++n) _Pragma("unroll") for (int k = 0; k < 2; ++k) \
;         acc[ai][bj][m][n] = __builtin_amdgcn_mfma_f32_16x16x32_bf16(Bt[n][k], At[m][k], acc[ai][bj][m][n], 0, 0, 0); __builtin_amdgcn_s_setprio(0); } while (0)
; #define PG8_WAIT_V(n) asm volatile("s_waitcnt vmcnt(" #n ")" ::: "memory")
; #define PG8_WAIT_L(n) asm volatile("s_waitcnt lgkmcnt(" #n ")" ::: "memory")
; #define PG8_BAR __builtin_amdgcn_s_barrier()
; #define PG8_SCHED __builtin_amdgcn_sched_barrier(0)
; template <class Epi, class Sched, bool ALIGN_EPI = false, bool SP2 = false>
; __device__ __forceinline__ void gemm_phase(PG8_LAS unsigned char* lds, const Gemm g, const Sched& S, const Epi& E) {
;     ...
;             PG8_WAIT_V(8); PG8_WAIT_L(0); PG8_BAR; PG8_MMA(0, 0, At, B0); PG8_MMA(0, 1, At, B1); PG8_BAR; PG8_SCHED;
;             PG8_LDA(At, 0, 1); PG8_STAGE(PG8_SB(0, 0), b2, voffB); PG8_STAGE(PG8_SB(0, 1), b2 + hstep, voffB); PG8_STAGE(PG8_SA(0, 0), a2, voffA);
;             PG8_WAIT_V(8); PG8_WAIT_L(0); PG8_BAR; PG8_MMA(1, 0, At, B0); PG8_MMA(1, 1, At, B1); PG8_BAR; PG8_SCHED;
	s_setprio 1
	s_waitcnt lgkmcnt(0)
	v_mfma_f32_16x16x32_bf16 v[124:127], v[150:153], v[182:185], v[124:127]
	v_mfma_f32_16x16x32_bf16 v[116:119], v[158:161], v[182:185], v[116:119]
	v_mfma_f32_16x16x32_bf16 v[108:111], v[150:153], v[190:193], v[108:111]
	v_mfma_f32_16x16x32_bf16 v[100:103], v[158:161], v[190:193], v[100:103]
	v_mfma_f32_16x16x32_bf16 v[92:95], v[150:153], v[202:205], v[92:95]
	v_mfma_f32_16x16x32_bf16 v[84:87], v[158:161], v[202:205], v[84:87]
	v_mfma_f32_16x16x32_bf16 v[76:79], v[150:153], v[210:213], v[76:79]
	v_mfma_f32_16x16x32_bf16 v[68:71], v[158:161], v[210:213], v[68:71]
	v_mfma_f32_16x16x32_bf16 v[124:127], v[154:157], v[186:189], v[124:127]
	v_mfma_f32_16x16x32_bf16 v[116:119], v[162:165], v[186:189], v[116:119]
	v_mfma_f32_16x16x32_bf16 v[108:111], v[154:157], v[194:197], v[108:111]
	v_mfma_f32_16x16x32_bf16 v[100:103], v[162:165], v[194:197], v[100:103]
	v_mfma_f32_16x16x32_bf16 v[92:95], v[154:157], v[206:209], v[92:95]
	v_mfma_f32_16x16x32_bf16 v[84:87], v[162:165], v[206:209], v[84:87]
	v_mfma_f32_16x16x32_bf16 v[76:79], v[154:157], v[214:217], v[76:79]
	v_mfma_f32_16x16x32_bf16 v[68:71], v[162:165], v[214:217], v[68:71]
	s_setprio 0
	s_setprio 1
	v_mfma_f32_16x16x32_bf16 v[120:123], v[166:169], v[182:185], v[120:123]
	v_mfma_f32_16x16x32_bf16 v[112:115], v[174:177], v[182:185], v[112:115]
	v_mfma_f32_16x16x32_bf16 v[104:107], v[166:169], v[190:193], v[104:107]
	v_mfma_f32_16x16x32_bf16 v[96:99], v[174:177], v[190:193], v[96:99]
	v_mfma_f32_16x16x32_bf16 v[88:91], v[166:169], v[202:205], v[88:91]
	v_mfma_f32_16x16x32_bf16 v[80:83], v[174:177], v[202:205], v[80:83]
	v_mfma_f32_16x16x32_bf16 v[72:75], v[166:169], v[210:213], v[72:75]
	v_mfma_f32_16x16x32_bf16 v[64:67], v[174:177], v[210:213], v[64:67]
	v_mfma_f32_16x16x32_bf16 v[120:123], v[170:173], v[186:189], v[120:123]
	v_mfma_f32_16x16x32_bf16 v[112:115], v[178:181], v[186:189], v[112:115]
	v_mfma_f32_16x16x32_bf16 v[104:107], v[170:173], v[194:197], v[104:107]
	v_mfma_f32_16x16x32_bf16 v[96:99], v[178:181], v[194:197], v[96:99]
	v_mfma_f32_16x16x32_bf16 v[88:91], v[170:173], v[206:209], v[88:91]
	v_mfma_f32_16x16x32_bf16 v[80:83], v[178:181], v[206:209], v[80:83]
	v_mfma_f32_16x16x32_bf16 v[72:75], v[170:173], v[214:217], v[72:75]
	v_mfma_f32_16x16x32_bf16 v[64:67], v[178:181], v[214:217], v[64:67]
	s_setprio 0
	s_barrier
	s_add_i32 s16, s61, s47
	s_mov_b32 m0, s16
	ds_read_b128 v[182:185], v149 offset:16384
	ds_read_b128 v[186:189], v149 offset:17408
	ds_read_b128 v[190:193], v149 offset:18432
	ds_read_b128 v[194:197], v149 offset:19456
	ds_read_b128 v[202:205], v149 offset:20480
	ds_read_b128 v[206:209], v149 offset:21504
	ds_read_b128 v[210:213], v149 offset:22528
	ds_read_b128 v[214:217], v149 offset:23552
	global_load_lds_dwordx4 v132, s[72:73]
	s_add_i32 m0, s16, 0x2000
	s_add_i32 s16, s62, s47
	global_load_lds_dwordx4 v128, s[72:73]
	s_mov_b32 m0, s16
	s_nop 0
	global_load_lds_dwordx4 v198, s[72:73]
	s_add_i32 m0, s16, 0x2000
	s_nop 0
	global_load_lds_dwordx4 v199, s[72:73]
	s_mov_b32 m0, s50
	s_nop 0
	global_load_lds_dwordx4 v134, s[44:45]
	s_mov_b32 m0, s51
	s_nop 0
	global_load_lds_dwordx4 v130, s[44:45]
	s_waitcnt vmcnt(8)
	s_waitcnt lgkmcnt(0)
	s_barrier
	s_setprio 1
	s_waitcnt lgkmcnt(0)
	v_mfma_f32_16x16x32_bf16 v[60:63], v[150:153], v[182:185], v[60:63]
	v_mfma_f32_16x16x32_bf16 v[52:55], v[158:161], v[182:185], v[52:55]
	v_mfma_f32_16x16x32_bf16 v[44:47], v[150:153], v[190:193], v[44:47]
	v_mfma_f32_16x16x32_bf16 v[36:39], v[158:161], v[190:193], v[36:39]
	v_mfma_f32_16x16x32_bf16 v[28:31], v[150:153], v[202:205], v[28:31]
	v_mfma_f32_16x16x32_bf16 v[20:23], v[158:161], v[202:205], v[20:23]
	v_mfma_f32_16x16x32_bf16 v[12:15], v[150:153], v[210:213], v[12:15]
	v_mfma_f32_16x16x32_bf16 v[4:7], v[158:161], v[210:213], v[4:7]
	v_mfma_f32_16x16x32_bf16 v[60:63], v[154:157], v[186:189], v[60:63]
	v_mfma_f32_16x16x32_bf16 v[52:55], v[162:165], v[186:189], v[52:55]
	v_mfma_f32_16x16x32_bf16 v[44:47], v[154:157], v[194:197], v[44:47]
	v_mfma_f32_16x16x32_bf16 v[36:39], v[162:165], v[194:197], v[36:39]
	v_mfma_f32_16x16x32_bf16 v[28:31], v[154:157], v[206:209], v[28:31]
	v_mfma_f32_16x16x32_bf16 v[20:23], v[162:165], v[206:209], v[20:23]
	v_mfma_f32_16x16x32_bf16 v[12:15], v[154:157], v[214:217], v[12:15]
	v_mfma_f32_16x16x32_bf16 v[4:7], v[162:165], v[214:217], v[4:7]
	s_setprio 0
	s_setprio 1
	v_mfma_f32_16x16x32_bf16 v[56:59], v[166:169], v[182:185], v[56:59]
	v_mfma_f32_16x16x32_bf16 v[48:51], v[174:177], v[182:185], v[48:51]
	v_mfma_f32_16x16x32_bf16 v[40:43], v[166:169], v[190:193], v[40:43]
	v_mfma_f32_16x16x32_bf16 v[32:35], v[174:177], v[190:193], v[32:35]
	v_mfma_f32_16x16x32_bf16 v[24:27], v[166:169], v[202:205], v[24:27]
	v_mfma_f32_16x16x32_bf16 v[16:19], v[174:177], v[202:205], v[16:19]
	v_mfma_f32_16x16x32_bf16 v[8:11], v[166:169], v[210:213], v[8:11]
	v_mfma_f32_16x16x32_bf16 v[0:3], v[174:177], v[210:213], v[0:3]
	v_mfma_f32_16x16x32_bf16 v[56:59], v[170:173], v[186:189], v[56:59]
	v_mfma_f32_16x16x32_bf16 v[48:51], v[178:181], v[186:189], v[48:51]
	v_mfma_f32_16x16x32_bf16 v[40:43], v[170:173], v[194:197], v[40:43]
	v_mfma_f32_16x16x32_bf16 v[32:35], v[178:181], v[194:197], v[32:35]
	v_mfma_f32_16x16x32_bf16 v[24:27], v[170:173], v[206:209], v[24:27]
	v_mfma_f32_16x16x32_bf16 v[16:19], v[178:181], v[206:209], v[16:19]
	v_mfma_f32_16x16x32_bf16 v[8:11], v[170:173], v[214:217], v[8:11]
	v_mfma_f32_16x16x32_bf16 v[0:3], v[178:181], v[214:217], v[0:3]
	s_setprio 0
	s_barrier
; #define PG8_STAGE(bufoff, gbase, voff) do { _Pragma("unroll") for (int _i = 0; _i < 2; ++_i) \
;         __builtin_amdgcn_global_load_lds((const unsigned*)((const char*)(gbase) + (voff)[_i]), (PG8_LAS unsigned*)(lds + (bufoff) + ldsw + _i * 8192), 16, 0, 0); } while (0)
; #define PG8_LDA(dst, b, h) do { _Pragma("unroll") for (int m = 0; m < 4; ++m) _Pragma("unroll") for (int k = 0; k < 2; ++k) dst[m][k] = *(const PG8_LAS bf16x8*)(lds + PG8_SA(b, h) + aoff + m * 2048 + k * 1024); } while (0)
; #define PG8_LDB(dst, b, h) do { _Pragma("unroll") for (int n = 0; n < 2; ++n) _Pragma("unroll") for (int k = 0; k < 2; ++k) dst[n][k] = *(const PG8_LAS bf16x8*)(lds + PG8_SB(b, h) + boff + n * 2048 + k * 1024); } while (0)
; #define PG8_MMA(ai, bj, At, Bt) do { __builtin_amdgcn_s_setprio(1); _Pragma("unroll") for (int m = 0; m < 4; ++m) _Pragma("unroll") for (int n = 0; n < 2; ++n) _Pragma("unroll") for (int k = 0; k < 2; ++k) \
;         acc[ai][bj][m][n] = __builtin_amdgcn_mfma_f32_16x16x32_bf16(Bt[n][k], At[m][k], acc[ai][bj][m][n], 0, 0, 0); __builtin_amdgcn_s_setprio(0); } while (0)
; #define PG8_WAIT_V(n) asm volatile("s_waitcnt vmcnt(" #n ")" ::: "memory")
; #define PG8_WAIT_L(n) asm volatile("s_waitcnt lgkmcnt(" #n ")" ::: "memory")
; #define PG8_BAR __builtin_amdgcn_s_barrier()
; #define PG8_SCHED __builtin_amdgcn_sched_barrier(0)
; template <class Epi, class Sched, bool ALIGN_EPI = false, bool SP2 = false>
; __device__ __forceinline__ void gemm_phase(PG8_LAS unsigned char* lds, const Gemm g, const Sched& S, const Epi& E) {
;     ...
;             PG8_LDB(B0, 1, 0); PG8_LDB(B1, 1, 1); PG8_SCHED; PG8_LDA(At, 1, 0); PG8_STAGE(PG8_SA(0, 1), a2 + hstep, voffA);
;             PG8_WAIT_V(8); PG8_WAIT_L(0); PG8_BAR; PG8_MMA(0, 0, At, B0); PG8_MMA(0, 1, At, B1); PG8_BAR; PG8_SCHED;
;             PG8_LDA(At, 1, 1); PG8_STAGE(PG8_SB(1, 0), b3, voffB); PG8_STAGE(PG8_SB(1, 1), b3 + hstep, voffB); PG8_STAGE(PG8_SA(1, 0), a3, voffA);
;             PG8_WAIT_V(8); PG8_WAIT_L(0); PG8_BAR; PG8_MMA(1, 0, At, B0); PG8_MMA(1, 1, At, B1); PG8_BAR; PG8_SCHED;
	s_add_i32 s16, 0, 0x18000
	s_add_i32 s17, 0, 0x1c000
	v_add_u32_e32 v162, s16, v145
	v_add_u32_e32 v178, s17, v145
	ds_read_b128 v[150:153], v162
	ds_read_b128 v[154:157], v162 offset:1024
	ds_read_b128 v[158:161], v162 offset:2048
	ds_read_b128 v[162:165], v162 offset:3072
	ds_read_b128 v[166:169], v178
	ds_read_b128 v[170:173], v178 offset:1024
	ds_read_b128 v[174:177], v178 offset:2048
	ds_read_b128 v[178:181], v178 offset:3072
	s_mov_b32 m0, s52
	ds_read_b128 v[182:185], v149 offset:32768
	ds_read_b128 v[186:189], v149 offset:33792
	ds_read_b128 v[190:193], v149 offset:34816
	ds_read_b128 v[194:197], v149 offset:35840
	ds_read_b128 v[202:205], v149 offset:36864
	ds_read_b128 v[206:209], v149 offset:37888
	ds_read_b128 v[210:213], v149 offset:38912
	ds_read_b128 v[214:217], v149 offset:39936
	global_load_lds_dwordx4 v218, s[44:45]
	s_mov_b32 m0, s53
	s_nop 0
	global_load_lds_dwordx4 v219, s[44:45]
	s_waitcnt vmcnt(8)
	s_waitcnt lgkmcnt(0)
	s_barrier
	s_setprio 1
	s_waitcnt lgkmcnt(0)
	v_mfma_f32_16x16x32_bf16 v[124:127], v[150:153], v[182:185], v[124:127]
	v_mfma_f32_16x16x32_bf16 v[116:119], v[158:161], v[182:185], v[116:119]
	v_mfma_f32_16x16x32_bf16 v[108:111], v[150:153], v[190:193], v[108:111]
	v_mfma_f32_16x16x32_bf16 v[100:103], v[158:161], v[190:193], v[100:103]
	v_mfma_f32_16x16x32_bf16 v[92:95], v[150:153], v[202:205], v[92:95]
	v_mfma_f32_16x16x32_bf16 v[84:87], v[158:161], v[202:205], v[84:87]
	v_mfma_f32_16x16x32_bf16 v[76:79], v[150:153], v[210:213], v[76:79]
	v_mfma_f32_16x16x32_bf16 v[68:71], v[158:161], v[210:213], v[68:71]
	v_mfma_f32_16x16x32_bf16 v[124:127], v[154:157], v[186:189], v[124:127]
	v_mfma_f32_16x16x32_bf16 v[116:119], v[162:165], v[186:189], v[116:119]
	v_mfma_f32_16x16x32_bf16 v[108:111], v[154:157], v[194:197], v[108:111]
	v_mfma_f32_16x16x32_bf16 v[100:103], v[162:165], v[194:197], v[100:103]
	v_mfma_f32_16x16x32_bf16 v[92:95], v[154:157], v[206:209], v[92:95]
	v_mfma_f32_16x16x32_bf16 v[84:87], v[162:165], v[206:209], v[84:87]
	v_mfma_f32_16x16x32_bf16 v[76:79], v[154:157], v[214:217], v[76:79]
	v_mfma_f32_16x16x32_bf16 v[68:71], v[162:165], v[214:217], v[68:71]
	s_setprio 0
	s_setprio 1
	v_mfma_f32_16x16x32_bf16 v[120:123], v[166:169], v[182:185], v[120:123]
	v_mfma_f32_16x16x32_bf16 v[112:115], v[174:177], v[182:185], v[112:115]
	v_mfma_f32_16x16x32_bf16 v[104:107], v[166:169], v[190:193], v[104:107]
	v_mfma_f32_16x16x32_bf16 v[96:99], v[174:177], v[190:193], v[96:99]
	v_mfma_f32_16x16x32_bf16 v[88:91], v[166:169], v[202:205], v[88:91]
	v_mfma_f32_16x16x32_bf16 v[80:83], v[174:177], v[202:205], v[80:83]
	v_mfma_f32_16x16x32_bf16 v[72:75], v[166:169], v[210:213], v[72:75]
	v_mfma_f32_16x16x32_bf16 v[64:67], v[174:177], v[210:213], v[64:67]
	v_mfma_f32_16x16x32_bf16 v[120:123], v[170:173], v[186:189], v[120:123]
	v_mfma_f32_16x16x32_bf16 v[112:115], v[178:181], v[186:189], v[112:115]
	v_mfma_f32_16x16x32_bf16 v[104:107], v[170:173], v[194:197], v[104:107]
	v_mfma_f32_16x16x32_bf16 v[96:99], v[178:181], v[194:197], v[96:99]
	v_mfma_f32_16x16x32_bf16 v[88:91], v[170:173], v[206:209], v[88:91]
	v_mfma_f32_16x16x32_bf16 v[80:83], v[178:181], v[206:209], v[80:83]
	v_mfma_f32_16x16x32_bf16 v[72:75], v[170:173], v[214:217], v[72:75]
	v_mfma_f32_16x16x32_bf16 v[64:67], v[178:181], v[214:217], v[64:67]
	s_setprio 0
	s_barrier
	s_add_i32 s16, s16, s47
	s_mov_b32 m0, s16
	ds_read_b128 v[182:185], v149 offset:49152
	ds_read_b128 v[186:189], v149 offset:50176
	ds_read_b128 v[190:193], v149 offset:51200
	ds_read_b128 v[194:197], v149 offset:52224
	ds_read_b128 v[202:205], v149 offset:53248
	ds_read_b128 v[206:209], v149 offset:54272
	ds_read_b128 v[210:213], v149 offset:55296
	ds_read_b128 v[214:217], v149 offset:56320
	global_load_lds_dwordx4 v220, s[72:73]
	s_add_i32 m0, s16, 0x2000
	s_add_i32 s16, s17, s47
	global_load_lds_dwordx4 v221, s[72:73]
	s_mov_b32 m0, s16
	s_nop 0
	global_load_lds_dwordx4 v222, s[72:73]
	s_add_i32 m0, s16, 0x2000
	s_nop 0
	global_load_lds_dwordx4 v223, s[72:73]
	s_mov_b32 m0, s55
	s_nop 0
	global_load_lds_dwordx4 v224, s[44:45]
	s_mov_b32 m0, s56
	s_nop 0
	global_load_lds_dwordx4 v225, s[44:45]
	s_waitcnt vmcnt(8)
	s_waitcnt lgkmcnt(0)
	s_barrier
	s_setprio 1
	s_waitcnt lgkmcnt(0)
	v_mfma_f32_16x16x32_bf16 v[60:63], v[150:153], v[182:185], v[60:63]
	v_mfma_f32_16x16x32_bf16 v[52:55], v[158:161], v[182:185], v[52:55]
	v_mfma_f32_16x16x32_bf16 v[44:47], v[150:153], v[190:193], v[44:47]
	v_mfma_f32_16x16x32_bf16 v[36:39], v[158:161], v[190:193], v[36:39]
	v_mfma_f32_16x16x32_bf16 v[28:31], v[150:153], v[202:205], v[28:31]
	v_mfma_f32_16x16x32_bf16 v[20:23], v[158:161], v[202:205], v[20:23]
	v_mfma_f32_16x16x32_bf16 v[12:15], v[150:153], v[210:213], v[12:15]
	v_mfma_f32_16x16x32_bf16 v[4:7], v[158:161], v[210:213], v[4:7]
	v_mfma_f32_16x16x32_bf16 v[60:63], v[154:157], v[186:189], v[60:63]
	v_mfma_f32_16x16x32_bf16 v[52:55], v[162:165], v[186:189], v[52:55]
	v_mfma_f32_16x16x32_bf16 v[44:47], v[154:157], v[194:197], v[44:47]
	v_mfma_f32_16x16x32_bf16 v[36:39], v[162:165], v[194:197], v[36:39]
	v_mfma_f32_16x16x32_bf16 v[28:31], v[154:157], v[206:209], v[28:31]
	v_mfma_f32_16x16x32_bf16 v[20:23], v[162:165], v[206:209], v[20:23]
	v_mfma_f32_16x16x32_bf16 v[12:15], v[154:157], v[214:217], v[12:15]
	v_mfma_f32_16x16x32_bf16 v[4:7], v[162:165], v[214:217], v[4:7]
	s_setprio 0
	s_setprio 1
	v_mfma_f32_16x16x32_bf16 v[56:59], v[166:169], v[182:185], v[56:59]
	v_mfma_f32_16x16x32_bf16 v[48:51], v[174:177], v[182:185], v[48:51]
	v_mfma_f32_16x16x32_bf16 v[40:43], v[166:169], v[190:193], v[40:43]
	v_mfma_f32_16x16x32_bf16 v[32:35], v[174:177], v[190:193], v[32:35]
	v_mfma_f32_16x16x32_bf16 v[24:27], v[166:169], v[202:205], v[24:27]
	v_mfma_f32_16x16x32_bf16 v[16:19], v[174:177], v[202:205], v[16:19]
	v_mfma_f32_16x16x32_bf16 v[8:11], v[166:169], v[210:213], v[8:11]
	v_mfma_f32_16x16x32_bf16 v[0:3], v[174:177], v[210:213], v[0:3]
	v_mfma_f32_16x16x32_bf16 v[56:59], v[170:173], v[186:189], v[56:59]
	v_mfma_f32_16x16x32_bf16 v[48:51], v[178:181], v[186:189], v[48:51]
	v_mfma_f32_16x16x32_bf16 v[40:43], v[170:173], v[194:197], v[40:43]
	v_mfma_f32_16x16x32_bf16 v[32:35], v[178:181], v[194:197], v[32:35]
	v_mfma_f32_16x16x32_bf16 v[24:27], v[170:173], v[206:209], v[24:27]
	v_mfma_f32_16x16x32_bf16 v[16:19], v[178:181], v[206:209], v[16:19]
	v_mfma_f32_16x16x32_bf16 v[8:11], v[170:173], v[214:217], v[8:11]
	v_mfma_f32_16x16x32_bf16 v[0:3], v[178:181], v[214:217], v[0:3]
	s_setprio 0
	s_barrier
	s_add_u32 s42, s42, 0x100
	s_addc_u32 s43, s43, 0
	s_add_u32 s68, s68, 0x100
	s_addc_u32 s69, s69, 0
	s_cmp_ge_i32 s70, s57
	s_mov_b32 s44, s70
	s_cbranch_scc0 .LBB0_1021

; #define PG8_STAGE(bufoff, gbase, voff) do { _Pragma("unroll") for (int _i = 0; _i < 2; ++_i) \
;         __builtin_amdgcn_global_load_lds((const unsigned*)((const char*)(gbase) + (voff)[_i]), (PG8_LAS unsigned*)(lds + (bufoff) + ldsw + _i * 8192), 16, 0, 0); } while (0)
; #define PG8_LDA(dst, b, h) do { _Pragma("unroll") for (int m = 0; m < 4; ++m) _Pragma("unroll") for (int k = 0; k < 2; ++k) dst[m][k] = *(const PG8_LAS bf16x8*)(lds + PG8_SA(b, h) + aoff + m * 2048 + k * 1024); } while (0)
; #define PG8_LDB(dst, b, h) do { _Pragma("unroll") for (int n = 0; n < 2; ++n) _Pragma("unroll") for (int k = 0; k < 2; ++k) dst[n][k] = *(const PG8_LAS bf16x8*)(lds + PG8_SB(b, h) + boff + n * 2048 + k * 1024); } while (0)
; #define PG8_MMA(ai, bj, At, Bt) do { __builtin_amdgcn_s_setprio(1); _Pragma("unroll") for (int m = 0; m < 4; ++m) _Pragma("unroll") for (int n = 0; n < 2; ++n) _Pragma("unroll") for (int k = 0; k < 2; ++k) \
;         acc[ai][bj][m][n] = __builtin_amdgcn_mfma_f32_16x16x32_bf16(Bt[n][k], At[m][k], acc[ai][bj][m][n], 0, 0, 0); __builtin_amdgcn_s_setprio(0); } while (0)
; #define PG8_WAIT_V(n) asm volatile("s_waitcnt vmcnt(" #n ")" ::: "memory")
; #define PG8_BAR __builtin_amdgcn_s_barrier()
; template <class Epi, class Sched, bool ALIGN_EPI = false, bool SP2 = false>
; __device__ __forceinline__ void gemm_phase(PG8_LAS unsigned char* lds, const Gemm g, const Sched& S, const Epi& E) {
;     ...
;         for (int t = 0; t < nt; t += 2) {
;             const bool last = (t == nt - 2);
;             const char* a1 = cA + (size_t)(t + 1) * kstep;
;             const char* a2 = last ? nA : cA + (size_t)(t + 2) * kstep; const char* b2 = last ? nB : cB + (size_t)(t + 2) * kstep;
;             const char* a3 = a2 + kstep; const char* b3 = b2 + kstep;
;             if (last && has_next) S.a_ready(nxt);
;             if constexpr (SP2) {
;             PG8_LDB(B0, 0, 0); PG8_LDB(B1, 0, 1); PG8_SCHED; PG8_LDA(At, 0, 0); PG8_STAGE(PG8_SA(1, 1), a1 + hstep, voffA);
;             PG8_WAIT_V(8); PG8_WAIT_L(0); PG8_BAR; PG8_MMA(0, 0, At, B0); PG8_MMA(0, 1, At, B1); PG8_BAR; PG8_SCHED;
;     ...
; #pragma unroll
;         for (int a = 0; a < 2; ++a)
; #pragma unroll
;             for (int b = 0; b < 2; ++b)
; #pragma unroll
;                 for (int m = 0; m < 4; ++m)
; #pragma unroll
;                     for (int n = 0; n < 2; ++n) acc[a][b][m][n] = (f32x4){0.f, 0.f, 0.f, 0.f};
.LBB0_1102:
	v_mov_b32_e32 v127, 0
	s_andn2_b64 vcc, exec, s[38:39]
	v_mov_b32_e32 v126, v127
	v_mov_b32_e32 v125, v127
	v_mov_b32_e32 v124, v127
	v_mov_b32_e32 v123, v127
	v_mov_b32_e32 v122, v127
	v_mov_b32_e32 v121, v127
	v_mov_b32_e32 v120, v127
	v_mov_b32_e32 v111, v127
	v_mov_b32_e32 v110, v127
	v_mov_b32_e32 v109, v127
	v_mov_b32_e32 v108, v127
	v_mov_b32_e32 v107, v127
	v_mov_b32_e32 v106, v127
	v_mov_b32_e32 v105, v127
	v_mov_b32_e32 v104, v127
	v_mov_b32_e32 v95, v127
	v_mov_b32_e32 v94, v127
	v_mov_b32_e32 v93, v127
	v_mov_b32_e32 v92, v127
	v_mov_b32_e32 v91, v127
	v_mov_b32_e32 v90, v127
	v_mov_b32_e32 v89, v127
	v_mov_b32_e32 v88, v127
	v_mov_b32_e32 v79, v127
	v_mov_b32_e32 v78, v127
	v_mov_b32_e32 v77, v127
	v_mov_b32_e32 v76, v127
	v_mov_b32_e32 v75, v127
	v_mov_b32_e32 v74, v127
	v_mov_b32_e32 v73, v127
	v_mov_b32_e32 v72, v127
	v_mov_b32_e32 v119, v127
	v_mov_b32_e32 v118, v127
	v_mov_b32_e32 v117, v127
	v_mov_b32_e32 v116, v127
	v_mov_b32_e32 v115, v127
	v_mov_b32_e32 v114, v127
	v_mov_b32_e32 v113, v127
	v_mov_b32_e32 v112, v127
	v_mov_b32_e32 v103, v127
	v_mov_b32_e32 v102, v127
	v_mov_b32_e32 v101, v127
	v_mov_b32_e32 v100, v127
	v_mov_b32_e32 v99, v127
	v_mov_b32_e32 v98, v127
	v_mov_b32_e32 v97, v127
	v_mov_b32_e32 v96, v127
	v_mov_b32_e32 v87, v127
	v_mov_b32_e32 v86, v127
	v_mov_b32_e32 v85, v127
	v_mov_b32_e32 v84, v127
	v_mov_b32_e32 v83, v127
	v_mov_b32_e32 v82, v127
	v_mov_b32_e32 v81, v127
	v_mov_b32_e32 v80, v127
	v_mov_b32_e32 v71, v127
	v_mov_b32_e32 v70, v127
	v_mov_b32_e32 v69, v127
	v_mov_b32_e32 v68, v127
	v_mov_b32_e32 v67, v127
	v_mov_b32_e32 v66, v127
	v_mov_b32_e32 v65, v127
	v_mov_b32_e32 v64, v127
	v_mov_b32_e32 v63, v127
	v_mov_b32_e32 v62, v127
	v_mov_b32_e32 v61, v127
	v_mov_b32_e32 v60, v127
	v_mov_b32_e32 v59, v127
	v_mov_b32_e32 v58, v127
	v_mov_b32_e32 v57, v127
	v_mov_b32_e32 v56, v127
	v_mov_b32_e32 v47, v127
	v_mov_b32_e32 v46, v127
	v_mov_b32_e32 v45, v127
	v_mov_b32_e32 v44, v127
	v_mov_b32_e32 v43, v127
	v_mov_b32_e32 v42, v127
	v_mov_b32_e32 v41, v127
	v_mov_b32_e32 v40, v127
	v_mov_b32_e32 v31, v127
	v_mov_b32_e32 v30, v127
	v_mov_b32_e32 v29, v127
	v_mov_b32_e32 v28, v127
	v_mov_b32_e32 v27, v127
	v_mov_b32_e32 v26, v127
	v_mov_b32_e32 v25, v127
	v_mov_b32_e32 v24, v127
	v_mov_b32_e32 v15, v127
	v_mov_b32_e32 v14, v127
	v_mov_b32_e32 v13, v127
	v_mov_b32_e32 v12, v127
	v_mov_b32_e32 v11, v127
	v_mov_b32_e32 v10, v127
	v_mov_b32_e32 v9, v127
	v_mov_b32_e32 v8, v127
	v_mov_b32_e32 v55, v127
	v_mov_b32_e32 v54, v127
	v_mov_b32_e32 v53, v127
	v_mov_b32_e32 v52, v127
	v_mov_b32_e32 v51, v127
	v_mov_b32_e32 v50, v127
	v_mov_b32_e32 v49, v127
	v_mov_b32_e32 v48, v127
	v_mov_b32_e32 v39, v127
	v_mov_b32_e32 v38, v127
	v_mov_b32_e32 v37, v127
	v_mov_b32_e32 v36, v127
	v_mov_b32_e32 v35, v127
	v_mov_b32_e32 v34, v127
	v_mov_b32_e32 v33, v127
	v_mov_b32_e32 v32, v127
	v_mov_b32_e32 v23, v127
	v_mov_b32_e32 v22, v127
	v_mov_b32_e32 v21, v127
	v_mov_b32_e32 v20, v127
	v_mov_b32_e32 v19, v127
	v_mov_b32_e32 v18, v127
	v_mov_b32_e32 v17, v127
	v_mov_b32_e32 v16, v127
	v_mov_b32_e32 v7, v127
	v_mov_b32_e32 v6, v127
	s_waitcnt lgkmcnt(0)
	v_mov_b32_e32 v5, v127
	v_mov_b32_e32 v4, v127
	v_mov_b32_e32 v3, v127
	v_mov_b32_e32 v2, v127
	v_mov_b32_e32 v1, v127
	v_mov_b32_e32 v0, v127
	s_cbranch_vccnz .LBB0_1105
	s_add_u32 s44, s44, 0x8000
	s_addc_u32 s45, s45, 0
	s_add_u32 s68, s46, 0x100
	s_addc_u32 s69, s47, 0
	s_mov_b32 s46, 0
	v_add_u32_e32 v218, s8, v130
	v_add_u32_e32 v219, s8, v134
	v_add_u32_e32 v220, 0x2000, v128
	v_add_u32_e32 v221, 0x2000, v132
	v_add_u32_e32 v222, 0x80, v130
	v_add_u32_e32 v223, 0x80, v134
	v_add_u32_e32 v224, 0x80, v218
	v_add_u32_e32 v225, 0x80, v219
	v_add_u32_e32 v226, 0x8000, v128
	v_add_u32_e32 v227, 0x8000, v132
.LBB0_1104:
	ds_read_b128 v[144:147], v151
	ds_read_b128 v[156:159], v151 offset:1024
	ds_read_b128 v[160:163], v151 offset:2048
	ds_read_b128 v[164:167], v151 offset:3072
	ds_read_b128 v[168:171], v152
	ds_read_b128 v[172:175], v152 offset:1024
	ds_read_b128 v[176:179], v152 offset:2048
	ds_read_b128 v[180:183], v152 offset:3072
	s_add_i32 s70, s46, 2
	s_add_u32 s16, s44, 0x8000
	s_addc_u32 s17, s45, 0
	s_cmp_eq_u32 s58, s46
	s_cselect_b32 s46, s0, s16
	s_cselect_b32 s47, s1, s17
	s_cselect_b32 s73, s43, s69
	s_cselect_b32 s72, s42, s68
	s_add_i32 m0, s50, 0xc000
	ds_read_b128 v[184:187], v153
	ds_read_b128 v[188:191], v153 offset:1024
	ds_read_b128 v[192:195], v153 offset:2048
	ds_read_b128 v[196:199], v153 offset:3072
	ds_read_b128 v[202:205], v153 offset:4096
	ds_read_b128 v[206:209], v153 offset:5120
	ds_read_b128 v[210:213], v153 offset:6144
	ds_read_b128 v[214:217], v153 offset:7168
	global_load_lds_dwordx4 v136, s[44:45]
	s_add_i32 m0, s50, 0xe000
	s_nop 0
	global_load_lds_dwordx4 v138, s[44:45]
	s_waitcnt vmcnt(8)
	s_waitcnt lgkmcnt(0)
	s_barrier
; #define PG8_STAGE(bufoff, gbase, voff) do { _Pragma("unroll") for (int _i = 0; _i < 2; ++_i) \
;         __builtin_amdgcn_global_load_lds((const unsigned*)((const char*)(gbase) + (voff)[_i]), (PG8_LAS unsigned*)(lds + (bufoff) + ldsw + _i * 8192), 16, 0, 0); } while (0)
; #define PG8_LDA(dst, b, h) do { _Pragma("unroll") for (int m = 0; m < 4; ++m) _Pragma("unroll") for (int k = 0; k < 2; ++k) dst[m][k] = *(const PG8_LAS bf16x8*)(lds + PG8_SA(b, h) + aoff + m * 2048 + k * 1024); } while (0)
; #define PG8_MMA(ai, bj, At, Bt) do { __builtin_amdgcn_s_setprio(1); _Pragma("unroll") for (int m = 0; m < 4; ++m) _Pragma("unroll") for (int n = 0; n < 2; ++n) _Pragma("unroll") for (int k = 0; k < 2; ++k) \
;         acc[ai][bj][m][n] = __builtin_amdgcn_mfma_f32_16x16x32_bf16(Bt[n][k], At[m][k], acc[ai][bj][m][n], 0, 0, 0); __builtin_amdgcn_s_setprio(0); } while (0)
; #define PG8_WAIT_V(n) asm volatile("s_waitcnt vmcnt(" #n ")" ::: "memory")
; #define PG8_WAIT_L(n) asm volatile("s_waitcnt lgkmcnt(" #n ")" ::: "memory")
; #define PG8_BAR __builtin_amdgcn_s_barrier()
; #define PG8_SCHED __builtin_amdgcn_sched_barrier(0)
; template <class Epi, class Sched, bool ALIGN_EPI = false, bool SP2 = false>
; __device__ __forceinline__ void gemm_phase(PG8_LAS unsigned char* lds, const Gemm g, const Sched& S, const Epi& E) {
;     ...
;             PG8_WAIT_V(8); PG8_WAIT_L(0); PG8_BAR; PG8_MMA(0, 0, At, B0); PG8_MMA(0, 1, At, B1); PG8_BAR; PG8_SCHED;
;             PG8_LDA(At, 0, 1); PG8_STAGE(PG8_SB(0, 0), b2, voffB); PG8_STAGE(PG8_SB(0, 1), b2 + hstep, voffB); PG8_STAGE(PG8_SA(0, 0), a2, voffA);
;             PG8_WAIT_V(8); PG8_WAIT_L(0); PG8_BAR; PG8_MMA(1, 0, At, B0); PG8_MMA(1, 1, At, B1); PG8_BAR; PG8_SCHED;
	s_setprio 1
	s_waitcnt lgkmcnt(0)
	v_mfma_f32_16x16x32_bf16 v[124:127], v[144:147], v[184:187], v[124:127]
	v_mfma_f32_16x16x32_bf16 v[120:123], v[160:163], v[184:187], v[120:123]
	v_mfma_f32_16x16x32_bf16 v[108:111], v[144:147], v[192:195], v[108:111]
	v_mfma_f32_16x16x32_bf16 v[104:107], v[160:163], v[192:195], v[104:107]
	v_mfma_f32_16x16x32_bf16 v[92:95], v[144:147], v[202:205], v[92:95]
	v_mfma_f32_16x16x32_bf16 v[88:91], v[160:163], v[202:205], v[88:91]
	v_mfma_f32_16x16x32_bf16 v[76:79], v[144:147], v[210:213], v[76:79]
	v_mfma_f32_16x16x32_bf16 v[72:75], v[160:163], v[210:213], v[72:75]
	v_mfma_f32_16x16x32_bf16 v[124:127], v[156:159], v[188:191], v[124:127]
	v_mfma_f32_16x16x32_bf16 v[120:123], v[164:167], v[188:191], v[120:123]
	v_mfma_f32_16x16x32_bf16 v[108:111], v[156:159], v[196:199], v[108:111]
	v_mfma_f32_16x16x32_bf16 v[104:107], v[164:167], v[196:199], v[104:107]
	v_mfma_f32_16x16x32_bf16 v[92:95], v[156:159], v[206:209], v[92:95]
	v_mfma_f32_16x16x32_bf16 v[88:91], v[164:167], v[206:209], v[88:91]
	v_mfma_f32_16x16x32_bf16 v[76:79], v[156:159], v[214:217], v[76:79]
	v_mfma_f32_16x16x32_bf16 v[72:75], v[164:167], v[214:217], v[72:75]
	s_setprio 0
	s_setprio 1
	v_mfma_f32_16x16x32_bf16 v[116:119], v[168:171], v[184:187], v[116:119]
	v_mfma_f32_16x16x32_bf16 v[112:115], v[176:179], v[184:187], v[112:115]
	v_mfma_f32_16x16x32_bf16 v[100:103], v[168:171], v[192:195], v[100:103]
	v_mfma_f32_16x16x32_bf16 v[96:99], v[176:179], v[192:195], v[96:99]
	v_mfma_f32_16x16x32_bf16 v[84:87], v[168:171], v[202:205], v[84:87]
	v_mfma_f32_16x16x32_bf16 v[80:83], v[176:179], v[202:205], v[80:83]
	v_mfma_f32_16x16x32_bf16 v[68:71], v[168:171], v[210:213], v[68:71]
	v_mfma_f32_16x16x32_bf16 v[64:67], v[176:179], v[210:213], v[64:67]
	v_mfma_f32_16x16x32_bf16 v[116:119], v[172:175], v[188:191], v[116:119]
	v_mfma_f32_16x16x32_bf16 v[112:115], v[180:183], v[188:191], v[112:115]
	v_mfma_f32_16x16x32_bf16 v[100:103], v[172:175], v[196:199], v[100:103]
	v_mfma_f32_16x16x32_bf16 v[96:99], v[180:183], v[196:199], v[96:99]
	v_mfma_f32_16x16x32_bf16 v[84:87], v[172:175], v[206:209], v[84:87]
	v_mfma_f32_16x16x32_bf16 v[80:83], v[180:183], v[206:209], v[80:83]
	v_mfma_f32_16x16x32_bf16 v[68:71], v[172:175], v[214:217], v[68:71]
	v_mfma_f32_16x16x32_bf16 v[64:67], v[180:183], v[214:217], v[64:67]
	s_setprio 0
	s_barrier
	s_add_i32 s16, s62, s49
	s_mov_b32 m0, s16
	ds_read_b128 v[184:187], v153 offset:16384
	ds_read_b128 v[188:191], v153 offset:17408
	ds_read_b128 v[192:195], v153 offset:18432
	ds_read_b128 v[196:199], v153 offset:19456
	ds_read_b128 v[202:205], v153 offset:20480
	ds_read_b128 v[206:209], v153 offset:21504
	ds_read_b128 v[210:213], v153 offset:22528
	ds_read_b128 v[214:217], v153 offset:23552
	global_load_lds_dwordx4 v130, s[72:73]
	s_add_i32 m0, s16, 0x2000
	s_add_i32 s16, s63, s49
	global_load_lds_dwordx4 v134, s[72:73]
	s_mov_b32 m0, s16
	s_nop 0
	global_load_lds_dwordx4 v218, s[72:73]
	s_add_i32 m0, s16, 0x2000
	s_nop 0
	global_load_lds_dwordx4 v219, s[72:73]
	s_mov_b32 m0, s50
	s_nop 0
	global_load_lds_dwordx4 v128, s[46:47]
	s_mov_b32 m0, s51
	s_nop 0
	global_load_lds_dwordx4 v132, s[46:47]
	s_waitcnt vmcnt(8)
	s_waitcnt lgkmcnt(0)
	s_barrier
	s_setprio 1
	s_waitcnt lgkmcnt(0)
	v_mfma_f32_16x16x32_bf16 v[60:63], v[144:147], v[184:187], v[60:63]
	v_mfma_f32_16x16x32_bf16 v[56:59], v[160:163], v[184:187], v[56:59]
	v_mfma_f32_16x16x32_bf16 v[44:47], v[144:147], v[192:195], v[44:47]
	v_mfma_f32_16x16x32_bf16 v[40:43], v[160:163], v[192:195], v[40:43]
	v_mfma_f32_16x16x32_bf16 v[28:31], v[144:147], v[202:205], v[28:31]
	v_mfma_f32_16x16x32_bf16 v[24:27], v[160:163], v[202:205], v[24:27]
	v_mfma_f32_16x16x32_bf16 v[12:15], v[144:147], v[210:213], v[12:15]
	v_mfma_f32_16x16x32_bf16 v[8:11], v[160:163], v[210:213], v[8:11]
	v_mfma_f32_16x16x32_bf16 v[60:63], v[156:159], v[188:191], v[60:63]
	v_mfma_f32_16x16x32_bf16 v[56:59], v[164:167], v[188:191], v[56:59]
	v_mfma_f32_16x16x32_bf16 v[44:47], v[156:159], v[196:199], v[44:47]
	v_mfma_f32_16x16x32_bf16 v[40:43], v[164:167], v[196:199], v[40:43]
	v_mfma_f32_16x16x32_bf16 v[28:31], v[156:159], v[206:209], v[28:31]
	v_mfma_f32_16x16x32_bf16 v[24:27], v[164:167], v[206:209], v[24:27]
	v_mfma_f32_16x16x32_bf16 v[12:15], v[156:159], v[214:217], v[12:15]
	v_mfma_f32_16x16x32_bf16 v[8:11], v[164:167], v[214:217], v[8:11]
	s_setprio 0
	s_setprio 1
	v_mfma_f32_16x16x32_bf16 v[52:55], v[168:171], v[184:187], v[52:55]
	v_mfma_f32_16x16x32_bf16 v[48:51], v[176:179], v[184:187], v[48:51]
	v_mfma_f32_16x16x32_bf16 v[36:39], v[168:171], v[192:195], v[36:39]
	v_mfma_f32_16x16x32_bf16 v[32:35], v[176:179], v[192:195], v[32:35]
	v_mfma_f32_16x16x32_bf16 v[20:23], v[168:171], v[202:205], v[20:23]
	v_mfma_f32_16x16x32_bf16 v[16:19], v[176:179], v[202:205], v[16:19]
	v_mfma_f32_16x16x32_bf16 v[4:7], v[168:171], v[210:213], v[4:7]
	v_mfma_f32_16x16x32_bf16 v[0:3], v[176:179], v[210:213], v[0:3]
	v_mfma_f32_16x16x32_bf16 v[52:55], v[172:175], v[188:191], v[52:55]
	v_mfma_f32_16x16x32_bf16 v[48:51], v[180:183], v[188:191], v[48:51]
	v_mfma_f32_16x16x32_bf16 v[36:39], v[172:175], v[196:199], v[36:39]
	v_mfma_f32_16x16x32_bf16 v[32:35], v[180:183], v[196:199], v[32:35]
	v_mfma_f32_16x16x32_bf16 v[20:23], v[172:175], v[206:209], v[20:23]
	v_mfma_f32_16x16x32_bf16 v[16:19], v[180:183], v[206:209], v[16:19]
	v_mfma_f32_16x16x32_bf16 v[4:7], v[172:175], v[214:217], v[4:7]
	v_mfma_f32_16x16x32_bf16 v[0:3], v[180:183], v[214:217], v[0:3]
	s_setprio 0
	s_barrier
; #define PG8_STAGE(bufoff, gbase, voff) do { _Pragma("unroll") for (int _i = 0; _i < 2; ++_i) \
;         __builtin_amdgcn_global_load_lds((const unsigned*)((const char*)(gbase) + (voff)[_i]), (PG8_LAS unsigned*)(lds + (bufoff) + ldsw + _i * 8192), 16, 0, 0); } while (0)
; #define PG8_LDA(dst, b, h) do { _Pragma("unroll") for (int m = 0; m < 4; ++m) _Pragma("unroll") for (int k = 0; k < 2; ++k) dst[m][k] = *(const PG8_LAS bf16x8*)(lds + PG8_SA(b, h) + aoff + m * 2048 + k * 1024); } while (0)
; #define PG8_LDB(dst, b, h) do { _Pragma("unroll") for (int n = 0; n < 2; ++n) _Pragma("unroll") for (int k = 0; k < 2; ++k) dst[n][k] = *(const PG8_LAS bf16x8*)(lds + PG8_SB(b, h) + boff + n * 2048 + k * 1024); } while (0)
; #define PG8_MMA(ai, bj, At, Bt) do { __builtin_amdgcn_s_setprio(1); _Pragma("unroll") for (int m = 0; m < 4; ++m) _Pragma("unroll") for (int n = 0; n < 2; ++n) _Pragma("unroll") for (int k = 0; k < 2; ++k) \
;         acc[ai][bj][m][n] = __builtin_amdgcn_mfma_f32_16x16x32_bf16(Bt[n][k], At[m][k], acc[ai][bj][m][n], 0, 0, 0); __builtin_amdgcn_s_setprio(0); } while (0)
; #define PG8_WAIT_V(n) asm volatile("s_waitcnt vmcnt(" #n ")" ::: "memory")
; #define PG8_WAIT_L(n) asm volatile("s_waitcnt lgkmcnt(" #n ")" ::: "memory")
; #define PG8_BAR __builtin_amdgcn_s_barrier()
; #define PG8_SCHED __builtin_amdgcn_sched_barrier(0)
; template <class Epi, class Sched, bool ALIGN_EPI = false, bool SP2 = false>
; __device__ __forceinline__ void gemm_phase(PG8_LAS unsigned char* lds, const Gemm g, const Sched& S, const Epi& E) {
;     ...
;             PG8_LDB(B0, 1, 0); PG8_LDB(B1, 1, 1); PG8_SCHED; PG8_LDA(At, 1, 0); PG8_STAGE(PG8_SA(0, 1), a2 + hstep, voffA);
;             PG8_WAIT_V(8); PG8_WAIT_L(0); PG8_BAR; PG8_MMA(0, 0, At, B0); PG8_MMA(0, 1, At, B1); PG8_BAR; PG8_SCHED;
;             PG8_LDA(At, 1, 1); PG8_STAGE(PG8_SB(1, 0), b3, voffB); PG8_STAGE(PG8_SB(1, 1), b3 + hstep, voffB); PG8_STAGE(PG8_SA(1, 0), a3, voffA);
;             PG8_WAIT_V(8); PG8_WAIT_L(0); PG8_BAR; PG8_MMA(1, 0, At, B0); PG8_MMA(1, 1, At, B1); PG8_BAR; PG8_SCHED;
	s_add_i32 s16, 0, 0x18000
	v_add_u32_e32 v155, s16, v149
	s_add_i32 s17, 0, 0x1c000
	ds_read_b128 v[144:147], v155
	ds_read_b128 v[156:159], v155 offset:1024
	ds_read_b128 v[160:163], v155 offset:2048
	ds_read_b128 v[164:167], v155 offset:3072
	v_add_u32_e32 v155, s17, v149
	ds_read_b128 v[168:171], v155
	ds_read_b128 v[172:175], v155 offset:1024
	ds_read_b128 v[176:179], v155 offset:2048
	ds_read_b128 v[180:183], v155 offset:3072
	s_mov_b32 m0, s52
	ds_read_b128 v[184:187], v153 offset:32768
	ds_read_b128 v[188:191], v153 offset:33792
	ds_read_b128 v[192:195], v153 offset:34816
	ds_read_b128 v[196:199], v153 offset:35840
	ds_read_b128 v[202:205], v153 offset:36864
	ds_read_b128 v[206:209], v153 offset:37888
	ds_read_b128 v[210:213], v153 offset:38912
	ds_read_b128 v[214:217], v153 offset:39936
	global_load_lds_dwordx4 v220, s[46:47]
	s_mov_b32 m0, s53
	s_nop 0
	global_load_lds_dwordx4 v221, s[46:47]
	s_waitcnt vmcnt(8)
	s_waitcnt lgkmcnt(0)
	s_barrier
	s_setprio 1
	s_waitcnt lgkmcnt(0)
	v_mfma_f32_16x16x32_bf16 v[124:127], v[144:147], v[184:187], v[124:127]
	v_mfma_f32_16x16x32_bf16 v[120:123], v[160:163], v[184:187], v[120:123]
	v_mfma_f32_16x16x32_bf16 v[108:111], v[144:147], v[192:195], v[108:111]
	v_mfma_f32_16x16x32_bf16 v[104:107], v[160:163], v[192:195], v[104:107]
	v_mfma_f32_16x16x32_bf16 v[92:95], v[144:147], v[202:205], v[92:95]
	v_mfma_f32_16x16x32_bf16 v[88:91], v[160:163], v[202:205], v[88:91]
	v_mfma_f32_16x16x32_bf16 v[76:79], v[144:147], v[210:213], v[76:79]
	v_mfma_f32_16x16x32_bf16 v[72:75], v[160:163], v[210:213], v[72:75]
	v_mfma_f32_16x16x32_bf16 v[124:127], v[156:159], v[188:191], v[124:127]
	v_mfma_f32_16x16x32_bf16 v[120:123], v[164:167], v[188:191], v[120:123]
	v_mfma_f32_16x16x32_bf16 v[108:111], v[156:159], v[196:199], v[108:111]
	v_mfma_f32_16x16x32_bf16 v[104:107], v[164:167], v[196:199], v[104:107]
	v_mfma_f32_16x16x32_bf16 v[92:95], v[156:159], v[206:209], v[92:95]
	v_mfma_f32_16x16x32_bf16 v[88:91], v[164:167], v[206:209], v[88:91]
	v_mfma_f32_16x16x32_bf16 v[76:79], v[156:159], v[214:217], v[76:79]
	v_mfma_f32_16x16x32_bf16 v[72:75], v[164:167], v[214:217], v[72:75]
	s_setprio 0
	s_setprio 1
	v_mfma_f32_16x16x32_bf16 v[116:119], v[168:171], v[184:187], v[116:119]
	v_mfma_f32_16x16x32_bf16 v[112:115], v[176:179], v[184:187], v[112:115]
	v_mfma_f32_16x16x32_bf16 v[100:103], v[168:171], v[192:195], v[100:103]
	v_mfma_f32_16x16x32_bf16 v[96:99], v[176:179], v[192:195], v[96:99]
	v_mfma_f32_16x16x32_bf16 v[84:87], v[168:171], v[202:205], v[84:87]
	v_mfma_f32_16x16x32_bf16 v[80:83], v[176:179], v[202:205], v[80:83]
	v_mfma_f32_16x16x32_bf16 v[68:71], v[168:171], v[210:213], v[68:71]
	v_mfma_f32_16x16x32_bf16 v[64:67], v[176:179], v[210:213], v[64:67]
	v_mfma_f32_16x16x32_bf16 v[116:119], v[172:175], v[188:191], v[116:119]
	v_mfma_f32_16x16x32_bf16 v[112:115], v[180:183], v[188:191], v[112:115]
	v_mfma_f32_16x16x32_bf16 v[100:103], v[172:175], v[196:199], v[100:103]
	v_mfma_f32_16x16x32_bf16 v[96:99], v[180:183], v[196:199], v[96:99]
	v_mfma_f32_16x16x32_bf16 v[84:87], v[172:175], v[206:209], v[84:87]
	v_mfma_f32_16x16x32_bf16 v[80:83], v[180:183], v[206:209], v[80:83]
	v_mfma_f32_16x16x32_bf16 v[68:71], v[172:175], v[214:217], v[68:71]
	v_mfma_f32_16x16x32_bf16 v[64:67], v[180:183], v[214:217], v[64:67]
	s_setprio 0
	s_barrier
	s_add_i32 s16, s16, s49
	s_mov_b32 m0, s16
	ds_read_b128 v[184:187], v153 offset:49152
	ds_read_b128 v[188:191], v153 offset:50176
	ds_read_b128 v[192:195], v153 offset:51200
	ds_read_b128 v[196:199], v153 offset:52224
	ds_read_b128 v[202:205], v153 offset:53248
	ds_read_b128 v[206:209], v153 offset:54272
	ds_read_b128 v[210:213], v153 offset:55296
	ds_read_b128 v[214:217], v153 offset:56320
	global_load_lds_dwordx4 v222, s[72:73]
	s_add_i32 m0, s16, 0x2000
	s_add_i32 s16, s17, s49
	global_load_lds_dwordx4 v223, s[72:73]
	s_mov_b32 m0, s16
	s_nop 0
	global_load_lds_dwordx4 v224, s[72:73]
	s_add_i32 m0, s16, 0x2000
	s_nop 0
	global_load_lds_dwordx4 v225, s[72:73]
	s_mov_b32 m0, s54
	s_nop 0
	global_load_lds_dwordx4 v226, s[46:47]
	s_mov_b32 m0, s55
	s_nop 0
	global_load_lds_dwordx4 v227, s[46:47]
	s_waitcnt vmcnt(8)
	s_waitcnt lgkmcnt(0)
	s_barrier
	s_setprio 1
	s_waitcnt lgkmcnt(0)
	v_mfma_f32_16x16x32_bf16 v[60:63], v[144:147], v[184:187], v[60:63]
	v_mfma_f32_16x16x32_bf16 v[56:59], v[160:163], v[184:187], v[56:59]
	v_mfma_f32_16x16x32_bf16 v[44:47], v[144:147], v[192:195], v[44:47]
	v_mfma_f32_16x16x32_bf16 v[40:43], v[160:163], v[192:195], v[40:43]
	v_mfma_f32_16x16x32_bf16 v[28:31], v[144:147], v[202:205], v[28:31]
	v_mfma_f32_16x16x32_bf16 v[24:27], v[160:163], v[202:205], v[24:27]
	v_mfma_f32_16x16x32_bf16 v[12:15], v[144:147], v[210:213], v[12:15]
	v_mfma_f32_16x16x32_bf16 v[8:11], v[160:163], v[210:213], v[8:11]
	v_mfma_f32_16x16x32_bf16 v[60:63], v[156:159], v[188:191], v[60:63]
	v_mfma_f32_16x16x32_bf16 v[56:59], v[164:167], v[188:191], v[56:59]
	v_mfma_f32_16x16x32_bf16 v[44:47], v[156:159], v[196:199], v[44:47]
	v_mfma_f32_16x16x32_bf16 v[40:43], v[164:167], v[196:199], v[40:43]
	v_mfma_f32_16x16x32_bf16 v[28:31], v[156:159], v[206:209], v[28:31]
	v_mfma_f32_16x16x32_bf16 v[24:27], v[164:167], v[206:209], v[24:27]
	v_mfma_f32_16x16x32_bf16 v[12:15], v[156:159], v[214:217], v[12:15]
	v_mfma_f32_16x16x32_bf16 v[8:11], v[164:167], v[214:217], v[8:11]
	s_setprio 0
	s_setprio 1
	v_mfma_f32_16x16x32_bf16 v[52:55], v[168:171], v[184:187], v[52:55]
	v_mfma_f32_16x16x32_bf16 v[48:51], v[176:179], v[184:187], v[48:51]
	v_mfma_f32_16x16x32_bf16 v[36:39], v[168:171], v[192:195], v[36:39]
	v_mfma_f32_16x16x32_bf16 v[32:35], v[176:179], v[192:195], v[32:35]
	v_mfma_f32_16x16x32_bf16 v[20:23], v[168:171], v[202:205], v[20:23]
	v_mfma_f32_16x16x32_bf16 v[16:19], v[176:179], v[202:205], v[16:19]
	v_mfma_f32_16x16x32_bf16 v[4:7], v[168:171], v[210:213], v[4:7]
	v_mfma_f32_16x16x32_bf16 v[0:3], v[176:179], v[210:213], v[0:3]
	v_mfma_f32_16x16x32_bf16 v[52:55], v[172:175], v[188:191], v[52:55]
	v_mfma_f32_16x16x32_bf16 v[48:51], v[180:183], v[188:191], v[48:51]
	v_mfma_f32_16x16x32_bf16 v[36:39], v[172:175], v[196:199], v[36:39]
	v_mfma_f32_16x16x32_bf16 v[32:35], v[180:183], v[196:199], v[32:35]
	v_mfma_f32_16x16x32_bf16 v[20:23], v[172:175], v[206:209], v[20:23]
	v_mfma_f32_16x16x32_bf16 v[16:19], v[180:183], v[206:209], v[16:19]
	v_mfma_f32_16x16x32_bf16 v[4:7], v[172:175], v[214:217], v[4:7]
	v_mfma_f32_16x16x32_bf16 v[0:3], v[180:183], v[214:217], v[0:3]
	s_setprio 0
	s_barrier
	s_add_u32 s44, s44, 0x10000
	s_addc_u32 s45, s45, 0
	s_add_u32 s68, s68, 0x100
	s_addc_u32 s69, s69, 0
	s_cmp_ge_i32 s70, s57
	s_mov_b32 s46, s70
	s_cbranch_scc0 .LBB0_1104
